# LDS-DMA operand staging in all four bf16 GEMM phases (PH2/PH6/PH8 unrolled with MFMA-interleaved DMA issue; PH9 rolled K=4096 loop); scan/prep/epilogue edits as before
# speedup vs baseline: 1.0500x; 1.0112x over previous
.LBB0_232:
	s_mul_hi_i32 s2, s8, 0x66666667
	s_lshr_b32 s3, s2, 31
	s_ashr_i32 s2, s2, 3
	s_add_i32 s34, s2, s3
	s_ashr_i32 s35, s34, 31
	v_readlane_b32 s36, v210, 50
	v_mov_b32_e32 v36, v133
	s_lshl_b64 s[2:3], s[34:35], 18
	v_readlane_b32 s38, v210, 52
	v_readlane_b32 s39, v210, 53
	v_ashrrev_i32_e32 v34, 3, v36
	s_add_u32 s2, s38, s2
	v_ashrrev_i32_e32 v35, 31, v34
	s_addc_u32 s3, s39, s3
	v_lshlrev_b64 v[2:3], 11, v[34:35]
	s_waitcnt vmcnt(0)
	v_lshlrev_b32_e32 v0, 4, v36
	v_lshl_add_u64 v[2:3], s[2:3], 0, v[2:3]
	v_and_b32_e32 v0, 0x70, v0
	s_mul_i32 s2, s34, 0xa00
	v_lshl_add_u64 v[66:67], v[2:3], 0, v[0:1]
	v_subrev_u32_e32 v2, s2, v34
	v_add_u32_e32 v2, s7, v2
	v_ashrrev_i32_e32 v3, 31, v2
	v_lshlrev_b64 v[2:3], 11, v[2:3]
	v_lshl_add_u64 v[2:3], s[0:1], 0, v[2:3]
	v_add_co_u32_e32 v70, vcc, s56, v66
	v_lshl_add_u64 v[68:69], v[2:3], 0, v[0:1]
	s_nop 0
	v_addc_co_u32_e32 v71, vcc, 0, v67, vcc
	v_add_co_u32_e32 v72, vcc, s56, v68
	v_addc_co_u32_e32 v73, vcc, 0, v69, vcc
	v_add_co_u32_e32 v74, vcc, s57, v66
	s_nop 0
	v_addc_co_u32_e32 v75, vcc, 0, v67, vcc
	v_add_co_u32_e32 v76, vcc, s57, v68
	s_nop 0
	v_addc_co_u32_e32 v77, vcc, 0, v69, vcc
	v_add_co_u32_e32 v78, vcc, s58, v66
	s_nop 0
	v_addc_co_u32_e32 v79, vcc, 0, v67, vcc
	v_add_co_u32_e32 v80, vcc, s58, v68
	v_lshlrev_b32_e32 v0, 7, v34
	s_nop 0
	v_addc_co_u32_e32 v81, vcc, 0, v69, vcc
	v_lshrrev_b32_e32 v216, 4, v133
	v_xor_b32_e32 v216, v216, v133
	v_and_b32_e32 v216, 7, v216
	v_lshlrev_b32_e32 v216, 4, v216
	v_mov_b32_e32 v217, 0x70
	v_lshrrev_b32_e32 v218, 6, v133
	v_lshlrev_b32_e32 v218, 10, v218
	s_nop 0
	v_readfirstlane_b32 s32, v218
	v_bfi_b32 v66, v217, v216, v66
	v_bfi_b32 v70, v217, v216, v70
	v_bfi_b32 v74, v217, v216, v74
	v_bfi_b32 v78, v217, v216, v78
	v_bfi_b32 v68, v217, v216, v68
	v_bfi_b32 v72, v217, v216, v72
	v_bfi_b32 v76, v217, v216, v76
	v_bfi_b32 v80, v217, v216, v80
	s_mov_b64 s[98:99], 0x80
	s_add_u32 m0, s32, 0x0
	s_nop 0
	global_load_lds_dwordx4 v[66:67], off
	s_add_u32 m0, s32, 0x1000
	s_nop 0
	global_load_lds_dwordx4 v[70:71], off
	s_add_u32 m0, s32, 0x2000
	s_nop 0
	global_load_lds_dwordx4 v[74:75], off
	s_add_u32 m0, s32, 0x3000
	s_nop 0
	global_load_lds_dwordx4 v[78:79], off
	s_add_u32 m0, s32, 0x8000
	s_nop 0
	global_load_lds_dwordx4 v[68:69], off
	s_add_u32 m0, s32, 0x9000
	s_nop 0
	global_load_lds_dwordx4 v[72:73], off
	s_add_u32 m0, s32, 0xa000
	s_nop 0
	global_load_lds_dwordx4 v[76:77], off
	s_add_u32 m0, s32, 0xb000
	s_nop 0
	global_load_lds_dwordx4 v[80:81], off
	v_lshl_add_u64 v[66:67], v[66:67], 0, s[98:99]
	v_lshl_add_u64 v[70:71], v[70:71], 0, s[98:99]
	v_lshl_add_u64 v[74:75], v[74:75], 0, s[98:99]
	v_lshl_add_u64 v[78:79], v[78:79], 0, s[98:99]
	v_lshl_add_u64 v[68:69], v[68:69], 0, s[98:99]
	v_lshl_add_u64 v[72:73], v[72:73], 0, s[98:99]
	v_lshl_add_u64 v[76:77], v[76:77], 0, s[98:99]
	v_lshl_add_u64 v[80:81], v[80:81], 0, s[98:99]
	v_lshrrev_b32_e32 v34, 1, v34
	v_xor_b32_e32 v34, v34, v36
	v_lshlrev_b32_e32 v34, 4, v34
	v_and_or_b32 v0, v34, s59, v0
	v_and_b32_e32 v84, 31, v36
	v_bfe_u32 v82, v36, 5, 1
	v_ashrrev_i32_e32 v83, 7, v36
	v_bfe_u32 v85, v36, 6, 1
	v_readlane_b32 s40, v210, 54
	v_readlane_b32 s41, v210, 55
	v_readlane_b32 s37, v210, 51
	v_readlane_b32 s42, v210, 56
	v_readlane_b32 s43, v210, 57
	v_readlane_b32 s44, v210, 58
	v_readlane_b32 s45, v210, 59
	v_readlane_b32 s46, v210, 60
	v_readlane_b32 s47, v210, 61
	v_readlane_b32 s48, v210, 62
	v_readlane_b32 s49, v210, 63
	v_readlane_b32 s50, v209, 0
	v_readlane_b32 s51, v209, 1
	s_waitcnt vmcnt(0)
	s_waitcnt lgkmcnt(0)
	s_barrier
	s_add_u32 m0, s32, 0x4000
	s_nop 0
	global_load_lds_dwordx4 v[66:67], off
	s_add_u32 m0, s32, 0x5000
	s_nop 0
	global_load_lds_dwordx4 v[70:71], off
	s_add_u32 m0, s32, 0x6000
	s_nop 0
	global_load_lds_dwordx4 v[74:75], off
	s_add_u32 m0, s32, 0x7000
	s_nop 0
	global_load_lds_dwordx4 v[78:79], off
	s_add_u32 m0, s32, 0xc000
	s_nop 0
	global_load_lds_dwordx4 v[68:69], off
	s_add_u32 m0, s32, 0xd000
	s_nop 0
	global_load_lds_dwordx4 v[72:73], off
	s_add_u32 m0, s32, 0xe000
	s_nop 0
	global_load_lds_dwordx4 v[76:77], off
	s_add_u32 m0, s32, 0xf000
	s_nop 0
	global_load_lds_dwordx4 v[80:81], off
	v_lshrrev_b32_e32 v4, 1, v36
	v_lshlrev_b32_e32 v2, 7, v84
	v_bitop3_b32 v4, v4, v82, 7 bitop3:0x6c
	v_lshl_or_b32 v3, v83, 13, v2
	v_bfe_u32 v5, v36, 1, 3
	v_lshlrev_b32_e32 v4, 4, v4
	v_lshl_or_b32 v2, v85, 13, v2
	v_or_b32_e32 v91, v3, v4
	v_or_b32_e32 v92, v2, v4
	v_bitop3_b32 v4, v82, v5, 2 bitop3:0x36
	v_lshlrev_b32_e32 v4, 4, v4
	v_or_b32_e32 v93, v3, v4
	v_or_b32_e32 v90, v2, v4
	v_bitop3_b32 v4, v82, v5, 4 bitop3:0x36
	v_lshlrev_b32_e32 v4, 4, v4
	v_or_b32_e32 v89, v3, v4
	v_or_b32_e32 v88, v2, v4
	v_bitop3_b32 v4, v82, v5, 6 bitop3:0x36
	v_lshlrev_b32_e32 v4, 4, v4
	v_or_b32_e32 v87, v3, v4
	v_or_b32_e32 v86, v2, v4
	ds_read_b128 v[2:5], v91
	ds_read_b128 v[6:9], v92 offset:32768
	ds_read_b128 v[10:13], v91 offset:4096
	ds_read_b128 v[14:17], v92 offset:36864
	ds_read_b128 v[162:165], v93
	ds_read_b128 v[166:169], v90 offset:32768
	ds_read_b128 v[182:185], v93 offset:4096
	ds_read_b128 v[186:189], v90 offset:36864
	s_waitcnt lgkmcnt(6)
	v_mfma_f32_32x32x16_bf16 v[50:65], v[2:5], v[6:9], 0
	s_waitcnt lgkmcnt(4)
	v_mfma_f32_32x32x16_bf16 v[34:49], v[2:5], v[14:17], 0
	v_mfma_f32_32x32x16_bf16 v[18:33], v[10:13], v[6:9], 0
	v_mfma_f32_32x32x16_bf16 v[2:17], v[10:13], v[14:17], 0
	ds_read_b128 v[190:193], v89
	ds_read_b128 v[194:197], v89 offset:4096
	ds_read_b128 v[198:201], v88 offset:32768
	ds_read_b128 v[202:205], v88 offset:36864
	s_waitcnt lgkmcnt(6)
	v_mfma_f32_32x32x16_bf16 v[50:65], v[162:165], v[166:169], v[50:65]
	s_waitcnt lgkmcnt(4)
	v_mfma_f32_32x32x16_bf16 v[34:49], v[162:165], v[186:189], v[34:49]
	v_mfma_f32_32x32x16_bf16 v[18:33], v[182:185], v[166:169], v[18:33]
	v_mfma_f32_32x32x16_bf16 v[2:17], v[182:185], v[186:189], v[2:17]
	ds_read_b128 v[162:165], v87
	ds_read_b128 v[166:169], v87 offset:4096
	ds_read_b128 v[182:185], v86 offset:32768
	ds_read_b128 v[186:189], v86 offset:36864
	v_lshl_add_u64 v[66:67], v[66:67], 0, s[98:99]
	v_lshl_add_u64 v[70:71], v[70:71], 0, s[98:99]
	v_lshl_add_u64 v[74:75], v[74:75], 0, s[98:99]
	v_lshl_add_u64 v[78:79], v[78:79], 0, s[98:99]
	v_lshl_add_u64 v[68:69], v[68:69], 0, s[98:99]
	v_lshl_add_u64 v[72:73], v[72:73], 0, s[98:99]
	v_lshl_add_u64 v[76:77], v[76:77], 0, s[98:99]
	v_lshl_add_u64 v[80:81], v[80:81], 0, s[98:99]
	s_waitcnt vmcnt(0)
	s_waitcnt lgkmcnt(0)
	s_barrier
	s_add_u32 m0, s32, 0x0
	v_mfma_f32_32x32x16_bf16 v[50:65], v[190:193], v[198:201], v[50:65]
	global_load_lds_dwordx4 v[66:67], off
	s_add_u32 m0, s32, 0x1000
	v_mfma_f32_32x32x16_bf16 v[34:49], v[190:193], v[202:205], v[34:49]
	global_load_lds_dwordx4 v[70:71], off
	s_add_u32 m0, s32, 0x2000
	v_mfma_f32_32x32x16_bf16 v[18:33], v[194:197], v[198:201], v[18:33]
	global_load_lds_dwordx4 v[74:75], off
	s_add_u32 m0, s32, 0x3000
	v_mfma_f32_32x32x16_bf16 v[2:17], v[194:197], v[202:205], v[2:17]
	global_load_lds_dwordx4 v[78:79], off
	s_add_u32 m0, s32, 0x8000
	v_mfma_f32_32x32x16_bf16 v[50:65], v[162:165], v[182:185], v[50:65]
	global_load_lds_dwordx4 v[68:69], off
	s_add_u32 m0, s32, 0x9000
	v_mfma_f32_32x32x16_bf16 v[34:49], v[162:165], v[186:189], v[34:49]
	global_load_lds_dwordx4 v[72:73], off
	s_add_u32 m0, s32, 0xa000
	v_mfma_f32_32x32x16_bf16 v[18:33], v[166:169], v[182:185], v[18:33]
	global_load_lds_dwordx4 v[76:77], off
	s_add_u32 m0, s32, 0xb000
	v_mfma_f32_32x32x16_bf16 v[2:17], v[166:169], v[186:189], v[2:17]
	global_load_lds_dwordx4 v[80:81], off
	ds_read_b128 v[162:165], v91 offset:16384
	ds_read_b128 v[166:169], v92 offset:49152
	ds_read_b128 v[182:185], v91 offset:20480
	ds_read_b128 v[186:189], v92 offset:53248
	ds_read_b128 v[190:193], v93 offset:16384
	ds_read_b128 v[194:197], v90 offset:49152
	ds_read_b128 v[198:201], v93 offset:20480
	ds_read_b128 v[202:205], v90 offset:53248
	s_waitcnt lgkmcnt(6)
	v_mfma_f32_32x32x16_bf16 v[50:65], v[162:165], v[166:169], v[50:65]
	s_waitcnt lgkmcnt(4)
	v_mfma_f32_32x32x16_bf16 v[34:49], v[162:165], v[186:189], v[34:49]
	v_mfma_f32_32x32x16_bf16 v[18:33], v[182:185], v[166:169], v[18:33]
	v_mfma_f32_32x32x16_bf16 v[2:17], v[182:185], v[186:189], v[2:17]
	ds_read_b128 v[162:165], v89 offset:16384
	ds_read_b128 v[166:169], v89 offset:20480
	ds_read_b128 v[182:185], v88 offset:49152
	ds_read_b128 v[186:189], v88 offset:53248
	s_waitcnt lgkmcnt(6)
	v_mfma_f32_32x32x16_bf16 v[50:65], v[190:193], v[194:197], v[50:65]
	s_waitcnt lgkmcnt(4)
	v_mfma_f32_32x32x16_bf16 v[34:49], v[190:193], v[202:205], v[34:49]
	v_mfma_f32_32x32x16_bf16 v[18:33], v[198:201], v[194:197], v[18:33]
	v_mfma_f32_32x32x16_bf16 v[2:17], v[198:201], v[202:205], v[2:17]
	ds_read_b128 v[190:193], v87 offset:16384
	ds_read_b128 v[194:197], v87 offset:20480
	ds_read_b128 v[198:201], v86 offset:49152
	ds_read_b128 v[202:205], v86 offset:53248
	v_lshl_add_u64 v[66:67], v[66:67], 0, s[98:99]
	v_lshl_add_u64 v[70:71], v[70:71], 0, s[98:99]
	v_lshl_add_u64 v[74:75], v[74:75], 0, s[98:99]
	v_lshl_add_u64 v[78:79], v[78:79], 0, s[98:99]
	v_lshl_add_u64 v[68:69], v[68:69], 0, s[98:99]
	v_lshl_add_u64 v[72:73], v[72:73], 0, s[98:99]
	v_lshl_add_u64 v[76:77], v[76:77], 0, s[98:99]
	v_lshl_add_u64 v[80:81], v[80:81], 0, s[98:99]
	s_waitcnt vmcnt(0)
	s_waitcnt lgkmcnt(0)
	s_barrier
	s_add_u32 m0, s32, 0x4000
	v_mfma_f32_32x32x16_bf16 v[50:65], v[162:165], v[182:185], v[50:65]
	global_load_lds_dwordx4 v[66:67], off
	s_add_u32 m0, s32, 0x5000
	v_mfma_f32_32x32x16_bf16 v[34:49], v[162:165], v[186:189], v[34:49]
	global_load_lds_dwordx4 v[70:71], off
	s_add_u32 m0, s32, 0x6000
	v_mfma_f32_32x32x16_bf16 v[18:33], v[166:169], v[182:185], v[18:33]
	global_load_lds_dwordx4 v[74:75], off
	s_add_u32 m0, s32, 0x7000
	v_mfma_f32_32x32x16_bf16 v[2:17], v[166:169], v[186:189], v[2:17]
	global_load_lds_dwordx4 v[78:79], off
	s_add_u32 m0, s32, 0xc000
	v_mfma_f32_32x32x16_bf16 v[50:65], v[190:193], v[198:201], v[50:65]
	global_load_lds_dwordx4 v[68:69], off
	s_add_u32 m0, s32, 0xd000
	v_mfma_f32_32x32x16_bf16 v[34:49], v[190:193], v[202:205], v[34:49]
	global_load_lds_dwordx4 v[72:73], off
	s_add_u32 m0, s32, 0xe000
	v_mfma_f32_32x32x16_bf16 v[18:33], v[194:197], v[198:201], v[18:33]
	global_load_lds_dwordx4 v[76:77], off
	s_add_u32 m0, s32, 0xf000
	v_mfma_f32_32x32x16_bf16 v[2:17], v[194:197], v[202:205], v[2:17]
	global_load_lds_dwordx4 v[80:81], off
	ds_read_b128 v[162:165], v91
	ds_read_b128 v[166:169], v92 offset:32768
	ds_read_b128 v[182:185], v91 offset:4096
	ds_read_b128 v[186:189], v92 offset:36864
	ds_read_b128 v[190:193], v93
	ds_read_b128 v[194:197], v90 offset:32768
	ds_read_b128 v[198:201], v93 offset:4096
	ds_read_b128 v[202:205], v90 offset:36864
	s_waitcnt lgkmcnt(6)
	v_mfma_f32_32x32x16_bf16 v[50:65], v[162:165], v[166:169], v[50:65]
	s_waitcnt lgkmcnt(4)
	v_mfma_f32_32x32x16_bf16 v[34:49], v[162:165], v[186:189], v[34:49]
	v_mfma_f32_32x32x16_bf16 v[18:33], v[182:185], v[166:169], v[18:33]
	v_mfma_f32_32x32x16_bf16 v[2:17], v[182:185], v[186:189], v[2:17]
	ds_read_b128 v[162:165], v89
	ds_read_b128 v[166:169], v89 offset:4096
	ds_read_b128 v[182:185], v88 offset:32768
	ds_read_b128 v[186:189], v88 offset:36864
	s_waitcnt lgkmcnt(6)
	v_mfma_f32_32x32x16_bf16 v[50:65], v[190:193], v[194:197], v[50:65]
	s_waitcnt lgkmcnt(4)
	v_mfma_f32_32x32x16_bf16 v[34:49], v[190:193], v[202:205], v[34:49]
	v_mfma_f32_32x32x16_bf16 v[18:33], v[198:201], v[194:197], v[18:33]
	v_mfma_f32_32x32x16_bf16 v[2:17], v[198:201], v[202:205], v[2:17]
	ds_read_b128 v[190:193], v87
	ds_read_b128 v[194:197], v87 offset:4096
	ds_read_b128 v[198:201], v86 offset:32768
	ds_read_b128 v[202:205], v86 offset:36864
	v_lshl_add_u64 v[66:67], v[66:67], 0, s[98:99]
	v_lshl_add_u64 v[70:71], v[70:71], 0, s[98:99]
	v_lshl_add_u64 v[74:75], v[74:75], 0, s[98:99]
	v_lshl_add_u64 v[78:79], v[78:79], 0, s[98:99]
	v_lshl_add_u64 v[68:69], v[68:69], 0, s[98:99]
	v_lshl_add_u64 v[72:73], v[72:73], 0, s[98:99]
	v_lshl_add_u64 v[76:77], v[76:77], 0, s[98:99]
	v_lshl_add_u64 v[80:81], v[80:81], 0, s[98:99]
	s_waitcnt vmcnt(0)
	s_waitcnt lgkmcnt(0)
	s_barrier
	s_add_u32 m0, s32, 0x0
	v_mfma_f32_32x32x16_bf16 v[50:65], v[162:165], v[182:185], v[50:65]
	global_load_lds_dwordx4 v[66:67], off
	s_add_u32 m0, s32, 0x1000
	v_mfma_f32_32x32x16_bf16 v[34:49], v[162:165], v[186:189], v[34:49]
	global_load_lds_dwordx4 v[70:71], off
	s_add_u32 m0, s32, 0x2000
	v_mfma_f32_32x32x16_bf16 v[18:33], v[166:169], v[182:185], v[18:33]
	global_load_lds_dwordx4 v[74:75], off
	s_add_u32 m0, s32, 0x3000
	v_mfma_f32_32x32x16_bf16 v[2:17], v[166:169], v[186:189], v[2:17]
	global_load_lds_dwordx4 v[78:79], off
	s_add_u32 m0, s32, 0x8000
	v_mfma_f32_32x32x16_bf16 v[50:65], v[190:193], v[198:201], v[50:65]
	global_load_lds_dwordx4 v[68:69], off
	s_add_u32 m0, s32, 0x9000
	v_mfma_f32_32x32x16_bf16 v[34:49], v[190:193], v[202:205], v[34:49]
	global_load_lds_dwordx4 v[72:73], off
	s_add_u32 m0, s32, 0xa000
	v_mfma_f32_32x32x16_bf16 v[18:33], v[194:197], v[198:201], v[18:33]
	global_load_lds_dwordx4 v[76:77], off
	s_add_u32 m0, s32, 0xb000
	v_mfma_f32_32x32x16_bf16 v[2:17], v[194:197], v[202:205], v[2:17]
	global_load_lds_dwordx4 v[80:81], off
	ds_read_b128 v[162:165], v91 offset:16384
	ds_read_b128 v[166:169], v92 offset:49152
	ds_read_b128 v[182:185], v91 offset:20480
	ds_read_b128 v[186:189], v92 offset:53248
	ds_read_b128 v[190:193], v93 offset:16384
	ds_read_b128 v[194:197], v90 offset:49152
	ds_read_b128 v[198:201], v93 offset:20480
	ds_read_b128 v[202:205], v90 offset:53248
	s_waitcnt lgkmcnt(6)
	v_mfma_f32_32x32x16_bf16 v[50:65], v[162:165], v[166:169], v[50:65]
	s_waitcnt lgkmcnt(4)
	v_mfma_f32_32x32x16_bf16 v[34:49], v[162:165], v[186:189], v[34:49]
	v_mfma_f32_32x32x16_bf16 v[18:33], v[182:185], v[166:169], v[18:33]
	v_mfma_f32_32x32x16_bf16 v[2:17], v[182:185], v[186:189], v[2:17]
	ds_read_b128 v[162:165], v89 offset:16384
	ds_read_b128 v[166:169], v89 offset:20480
	ds_read_b128 v[182:185], v88 offset:49152
	ds_read_b128 v[186:189], v88 offset:53248
	s_waitcnt lgkmcnt(6)
	v_mfma_f32_32x32x16_bf16 v[50:65], v[190:193], v[194:197], v[50:65]
	s_waitcnt lgkmcnt(4)
	v_mfma_f32_32x32x16_bf16 v[34:49], v[190:193], v[202:205], v[34:49]
	v_mfma_f32_32x32x16_bf16 v[18:33], v[198:201], v[194:197], v[18:33]
	v_mfma_f32_32x32x16_bf16 v[2:17], v[198:201], v[202:205], v[2:17]
	ds_read_b128 v[190:193], v87 offset:16384
	ds_read_b128 v[194:197], v87 offset:20480
	ds_read_b128 v[198:201], v86 offset:49152
	ds_read_b128 v[202:205], v86 offset:53248
	v_lshl_add_u64 v[66:67], v[66:67], 0, s[98:99]
	v_lshl_add_u64 v[70:71], v[70:71], 0, s[98:99]
	v_lshl_add_u64 v[74:75], v[74:75], 0, s[98:99]
	v_lshl_add_u64 v[78:79], v[78:79], 0, s[98:99]
	v_lshl_add_u64 v[68:69], v[68:69], 0, s[98:99]
	v_lshl_add_u64 v[72:73], v[72:73], 0, s[98:99]
	v_lshl_add_u64 v[76:77], v[76:77], 0, s[98:99]
	v_lshl_add_u64 v[80:81], v[80:81], 0, s[98:99]
	s_waitcnt vmcnt(0)
	s_waitcnt lgkmcnt(0)
	s_barrier
	s_add_u32 m0, s32, 0x4000
	v_mfma_f32_32x32x16_bf16 v[50:65], v[162:165], v[182:185], v[50:65]
	global_load_lds_dwordx4 v[66:67], off
	s_add_u32 m0, s32, 0x5000
	v_mfma_f32_32x32x16_bf16 v[34:49], v[162:165], v[186:189], v[34:49]
	global_load_lds_dwordx4 v[70:71], off
	s_add_u32 m0, s32, 0x6000
	v_mfma_f32_32x32x16_bf16 v[18:33], v[166:169], v[182:185], v[18:33]
	global_load_lds_dwordx4 v[74:75], off
	s_add_u32 m0, s32, 0x7000
	v_mfma_f32_32x32x16_bf16 v[2:17], v[166:169], v[186:189], v[2:17]
	global_load_lds_dwordx4 v[78:79], off
	s_add_u32 m0, s32, 0xc000
	v_mfma_f32_32x32x16_bf16 v[50:65], v[190:193], v[198:201], v[50:65]
	global_load_lds_dwordx4 v[68:69], off
	s_add_u32 m0, s32, 0xd000
	v_mfma_f32_32x32x16_bf16 v[34:49], v[190:193], v[202:205], v[34:49]
	global_load_lds_dwordx4 v[72:73], off
	s_add_u32 m0, s32, 0xe000
	v_mfma_f32_32x32x16_bf16 v[18:33], v[194:197], v[198:201], v[18:33]
	global_load_lds_dwordx4 v[76:77], off
	s_add_u32 m0, s32, 0xf000
	v_mfma_f32_32x32x16_bf16 v[2:17], v[194:197], v[202:205], v[2:17]
	global_load_lds_dwordx4 v[80:81], off
	ds_read_b128 v[162:165], v91
	ds_read_b128 v[166:169], v92 offset:32768
	ds_read_b128 v[182:185], v91 offset:4096
	ds_read_b128 v[186:189], v92 offset:36864
	ds_read_b128 v[190:193], v93
	ds_read_b128 v[194:197], v90 offset:32768
	ds_read_b128 v[198:201], v93 offset:4096
	ds_read_b128 v[202:205], v90 offset:36864
	s_waitcnt lgkmcnt(6)
	v_mfma_f32_32x32x16_bf16 v[50:65], v[162:165], v[166:169], v[50:65]
	s_waitcnt lgkmcnt(4)
	v_mfma_f32_32x32x16_bf16 v[34:49], v[162:165], v[186:189], v[34:49]
	v_mfma_f32_32x32x16_bf16 v[18:33], v[182:185], v[166:169], v[18:33]
	v_mfma_f32_32x32x16_bf16 v[2:17], v[182:185], v[186:189], v[2:17]
	ds_read_b128 v[162:165], v89
	ds_read_b128 v[166:169], v89 offset:4096
	ds_read_b128 v[182:185], v88 offset:32768
	ds_read_b128 v[186:189], v88 offset:36864
	s_waitcnt lgkmcnt(6)
	v_mfma_f32_32x32x16_bf16 v[50:65], v[190:193], v[194:197], v[50:65]
	s_waitcnt lgkmcnt(4)
	v_mfma_f32_32x32x16_bf16 v[34:49], v[190:193], v[202:205], v[34:49]
	v_mfma_f32_32x32x16_bf16 v[18:33], v[198:201], v[194:197], v[18:33]
	v_mfma_f32_32x32x16_bf16 v[2:17], v[198:201], v[202:205], v[2:17]
	ds_read_b128 v[190:193], v87
	ds_read_b128 v[194:197], v87 offset:4096
	ds_read_b128 v[198:201], v86 offset:32768
	ds_read_b128 v[202:205], v86 offset:36864
	v_lshl_add_u64 v[66:67], v[66:67], 0, s[98:99]
	v_lshl_add_u64 v[70:71], v[70:71], 0, s[98:99]
	v_lshl_add_u64 v[74:75], v[74:75], 0, s[98:99]
	v_lshl_add_u64 v[78:79], v[78:79], 0, s[98:99]
	v_lshl_add_u64 v[68:69], v[68:69], 0, s[98:99]
	v_lshl_add_u64 v[72:73], v[72:73], 0, s[98:99]
	v_lshl_add_u64 v[76:77], v[76:77], 0, s[98:99]
	v_lshl_add_u64 v[80:81], v[80:81], 0, s[98:99]
	s_waitcnt vmcnt(0)
	s_waitcnt lgkmcnt(0)
	s_barrier
	s_add_u32 m0, s32, 0x0
	v_mfma_f32_32x32x16_bf16 v[50:65], v[162:165], v[182:185], v[50:65]
	global_load_lds_dwordx4 v[66:67], off
	s_add_u32 m0, s32, 0x1000
	v_mfma_f32_32x32x16_bf16 v[34:49], v[162:165], v[186:189], v[34:49]
	global_load_lds_dwordx4 v[70:71], off
	s_add_u32 m0, s32, 0x2000
	v_mfma_f32_32x32x16_bf16 v[18:33], v[166:169], v[182:185], v[18:33]
	global_load_lds_dwordx4 v[74:75], off
	s_add_u32 m0, s32, 0x3000
	v_mfma_f32_32x32x16_bf16 v[2:17], v[166:169], v[186:189], v[2:17]
	global_load_lds_dwordx4 v[78:79], off
	s_add_u32 m0, s32, 0x8000
	v_mfma_f32_32x32x16_bf16 v[50:65], v[190:193], v[198:201], v[50:65]
	global_load_lds_dwordx4 v[68:69], off
	s_add_u32 m0, s32, 0x9000
	v_mfma_f32_32x32x16_bf16 v[34:49], v[190:193], v[202:205], v[34:49]
	global_load_lds_dwordx4 v[72:73], off
	s_add_u32 m0, s32, 0xa000
	v_mfma_f32_32x32x16_bf16 v[18:33], v[194:197], v[198:201], v[18:33]
	global_load_lds_dwordx4 v[76:77], off
	s_add_u32 m0, s32, 0xb000
	v_mfma_f32_32x32x16_bf16 v[2:17], v[194:197], v[202:205], v[2:17]
	global_load_lds_dwordx4 v[80:81], off
	ds_read_b128 v[162:165], v91 offset:16384
	ds_read_b128 v[166:169], v92 offset:49152
	ds_read_b128 v[182:185], v91 offset:20480
	ds_read_b128 v[186:189], v92 offset:53248
	ds_read_b128 v[190:193], v93 offset:16384
	ds_read_b128 v[194:197], v90 offset:49152
	ds_read_b128 v[198:201], v93 offset:20480
	ds_read_b128 v[202:205], v90 offset:53248
	s_waitcnt lgkmcnt(6)
	v_mfma_f32_32x32x16_bf16 v[50:65], v[162:165], v[166:169], v[50:65]
	s_waitcnt lgkmcnt(4)
	v_mfma_f32_32x32x16_bf16 v[34:49], v[162:165], v[186:189], v[34:49]
	v_mfma_f32_32x32x16_bf16 v[18:33], v[182:185], v[166:169], v[18:33]
	v_mfma_f32_32x32x16_bf16 v[2:17], v[182:185], v[186:189], v[2:17]
	ds_read_b128 v[162:165], v89 offset:16384
	ds_read_b128 v[166:169], v89 offset:20480
	ds_read_b128 v[182:185], v88 offset:49152
	ds_read_b128 v[186:189], v88 offset:53248
	s_waitcnt lgkmcnt(6)
	v_mfma_f32_32x32x16_bf16 v[50:65], v[190:193], v[194:197], v[50:65]
	s_waitcnt lgkmcnt(4)
	v_mfma_f32_32x32x16_bf16 v[34:49], v[190:193], v[202:205], v[34:49]
	v_mfma_f32_32x32x16_bf16 v[18:33], v[198:201], v[194:197], v[18:33]
	v_mfma_f32_32x32x16_bf16 v[2:17], v[198:201], v[202:205], v[2:17]
	ds_read_b128 v[190:193], v87 offset:16384
	ds_read_b128 v[194:197], v87 offset:20480
	ds_read_b128 v[198:201], v86 offset:49152
	ds_read_b128 v[202:205], v86 offset:53248
	v_lshl_add_u64 v[66:67], v[66:67], 0, s[98:99]
	v_lshl_add_u64 v[70:71], v[70:71], 0, s[98:99]
	v_lshl_add_u64 v[74:75], v[74:75], 0, s[98:99]
	v_lshl_add_u64 v[78:79], v[78:79], 0, s[98:99]
	v_lshl_add_u64 v[68:69], v[68:69], 0, s[98:99]
	v_lshl_add_u64 v[72:73], v[72:73], 0, s[98:99]
	v_lshl_add_u64 v[76:77], v[76:77], 0, s[98:99]
	v_lshl_add_u64 v[80:81], v[80:81], 0, s[98:99]
	s_waitcnt vmcnt(0)
	s_waitcnt lgkmcnt(0)
	s_barrier
	s_add_u32 m0, s32, 0x4000
	v_mfma_f32_32x32x16_bf16 v[50:65], v[162:165], v[182:185], v[50:65]
	global_load_lds_dwordx4 v[66:67], off
	s_add_u32 m0, s32, 0x5000
	v_mfma_f32_32x32x16_bf16 v[34:49], v[162:165], v[186:189], v[34:49]
	global_load_lds_dwordx4 v[70:71], off
	s_add_u32 m0, s32, 0x6000
	v_mfma_f32_32x32x16_bf16 v[18:33], v[166:169], v[182:185], v[18:33]
	global_load_lds_dwordx4 v[74:75], off
	s_add_u32 m0, s32, 0x7000
	v_mfma_f32_32x32x16_bf16 v[2:17], v[166:169], v[186:189], v[2:17]
	global_load_lds_dwordx4 v[78:79], off
	s_add_u32 m0, s32, 0xc000
	v_mfma_f32_32x32x16_bf16 v[50:65], v[190:193], v[198:201], v[50:65]
	global_load_lds_dwordx4 v[68:69], off
	s_add_u32 m0, s32, 0xd000
	v_mfma_f32_32x32x16_bf16 v[34:49], v[190:193], v[202:205], v[34:49]
	global_load_lds_dwordx4 v[72:73], off
	s_add_u32 m0, s32, 0xe000
	v_mfma_f32_32x32x16_bf16 v[18:33], v[194:197], v[198:201], v[18:33]
	global_load_lds_dwordx4 v[76:77], off
	s_add_u32 m0, s32, 0xf000
	v_mfma_f32_32x32x16_bf16 v[2:17], v[194:197], v[202:205], v[2:17]
	global_load_lds_dwordx4 v[80:81], off
	ds_read_b128 v[162:165], v91
	ds_read_b128 v[166:169], v92 offset:32768
	ds_read_b128 v[182:185], v91 offset:4096
	ds_read_b128 v[186:189], v92 offset:36864
	ds_read_b128 v[190:193], v93
	ds_read_b128 v[194:197], v90 offset:32768
	ds_read_b128 v[198:201], v93 offset:4096
	ds_read_b128 v[202:205], v90 offset:36864
	s_waitcnt lgkmcnt(6)
	v_mfma_f32_32x32x16_bf16 v[50:65], v[162:165], v[166:169], v[50:65]
	s_waitcnt lgkmcnt(4)
	v_mfma_f32_32x32x16_bf16 v[34:49], v[162:165], v[186:189], v[34:49]
	v_mfma_f32_32x32x16_bf16 v[18:33], v[182:185], v[166:169], v[18:33]
	v_mfma_f32_32x32x16_bf16 v[2:17], v[182:185], v[186:189], v[2:17]
	ds_read_b128 v[162:165], v89
	ds_read_b128 v[166:169], v89 offset:4096
	ds_read_b128 v[182:185], v88 offset:32768
	ds_read_b128 v[186:189], v88 offset:36864
	s_waitcnt lgkmcnt(6)
	v_mfma_f32_32x32x16_bf16 v[50:65], v[190:193], v[194:197], v[50:65]
	s_waitcnt lgkmcnt(4)
	v_mfma_f32_32x32x16_bf16 v[34:49], v[190:193], v[202:205], v[34:49]
	v_mfma_f32_32x32x16_bf16 v[18:33], v[198:201], v[194:197], v[18:33]
	v_mfma_f32_32x32x16_bf16 v[2:17], v[198:201], v[202:205], v[2:17]
	ds_read_b128 v[190:193], v87
	ds_read_b128 v[194:197], v87 offset:4096
	ds_read_b128 v[198:201], v86 offset:32768
	ds_read_b128 v[202:205], v86 offset:36864
	v_lshl_add_u64 v[66:67], v[66:67], 0, s[98:99]
	v_lshl_add_u64 v[70:71], v[70:71], 0, s[98:99]
	v_lshl_add_u64 v[74:75], v[74:75], 0, s[98:99]
	v_lshl_add_u64 v[78:79], v[78:79], 0, s[98:99]
	v_lshl_add_u64 v[68:69], v[68:69], 0, s[98:99]
	v_lshl_add_u64 v[72:73], v[72:73], 0, s[98:99]
	v_lshl_add_u64 v[76:77], v[76:77], 0, s[98:99]
	v_lshl_add_u64 v[80:81], v[80:81], 0, s[98:99]
	s_waitcnt vmcnt(0)
	s_waitcnt lgkmcnt(0)
	s_barrier
	s_add_u32 m0, s32, 0x0
	v_mfma_f32_32x32x16_bf16 v[50:65], v[162:165], v[182:185], v[50:65]
	global_load_lds_dwordx4 v[66:67], off
	s_add_u32 m0, s32, 0x1000
	v_mfma_f32_32x32x16_bf16 v[34:49], v[162:165], v[186:189], v[34:49]
	global_load_lds_dwordx4 v[70:71], off
	s_add_u32 m0, s32, 0x2000
	v_mfma_f32_32x32x16_bf16 v[18:33], v[166:169], v[182:185], v[18:33]
	global_load_lds_dwordx4 v[74:75], off
	s_add_u32 m0, s32, 0x3000
	v_mfma_f32_32x32x16_bf16 v[2:17], v[166:169], v[186:189], v[2:17]
	global_load_lds_dwordx4 v[78:79], off
	s_add_u32 m0, s32, 0x8000
	v_mfma_f32_32x32x16_bf16 v[50:65], v[190:193], v[198:201], v[50:65]
	global_load_lds_dwordx4 v[68:69], off
	s_add_u32 m0, s32, 0x9000
	v_mfma_f32_32x32x16_bf16 v[34:49], v[190:193], v[202:205], v[34:49]
	global_load_lds_dwordx4 v[72:73], off
	s_add_u32 m0, s32, 0xa000
	v_mfma_f32_32x32x16_bf16 v[18:33], v[194:197], v[198:201], v[18:33]
	global_load_lds_dwordx4 v[76:77], off
	s_add_u32 m0, s32, 0xb000
	v_mfma_f32_32x32x16_bf16 v[2:17], v[194:197], v[202:205], v[2:17]
	global_load_lds_dwordx4 v[80:81], off
	ds_read_b128 v[162:165], v91 offset:16384
	ds_read_b128 v[166:169], v92 offset:49152
	ds_read_b128 v[182:185], v91 offset:20480
	ds_read_b128 v[186:189], v92 offset:53248
	ds_read_b128 v[190:193], v93 offset:16384
	ds_read_b128 v[194:197], v90 offset:49152
	ds_read_b128 v[198:201], v93 offset:20480
	ds_read_b128 v[202:205], v90 offset:53248
	s_waitcnt lgkmcnt(6)
	v_mfma_f32_32x32x16_bf16 v[50:65], v[162:165], v[166:169], v[50:65]
	s_waitcnt lgkmcnt(4)
	v_mfma_f32_32x32x16_bf16 v[34:49], v[162:165], v[186:189], v[34:49]
	v_mfma_f32_32x32x16_bf16 v[18:33], v[182:185], v[166:169], v[18:33]
	v_mfma_f32_32x32x16_bf16 v[2:17], v[182:185], v[186:189], v[2:17]
	ds_read_b128 v[162:165], v89 offset:16384
	ds_read_b128 v[166:169], v89 offset:20480
	ds_read_b128 v[182:185], v88 offset:49152
	ds_read_b128 v[186:189], v88 offset:53248
	s_waitcnt lgkmcnt(6)
	v_mfma_f32_32x32x16_bf16 v[50:65], v[190:193], v[194:197], v[50:65]
	s_waitcnt lgkmcnt(4)
	v_mfma_f32_32x32x16_bf16 v[34:49], v[190:193], v[202:205], v[34:49]
	v_mfma_f32_32x32x16_bf16 v[18:33], v[198:201], v[194:197], v[18:33]
	v_mfma_f32_32x32x16_bf16 v[2:17], v[198:201], v[202:205], v[2:17]
	ds_read_b128 v[190:193], v87 offset:16384
	ds_read_b128 v[194:197], v87 offset:20480
	ds_read_b128 v[198:201], v86 offset:49152
	ds_read_b128 v[202:205], v86 offset:53248
	v_lshl_add_u64 v[66:67], v[66:67], 0, s[98:99]
	v_lshl_add_u64 v[70:71], v[70:71], 0, s[98:99]
	v_lshl_add_u64 v[74:75], v[74:75], 0, s[98:99]
	v_lshl_add_u64 v[78:79], v[78:79], 0, s[98:99]
	v_lshl_add_u64 v[68:69], v[68:69], 0, s[98:99]
	v_lshl_add_u64 v[72:73], v[72:73], 0, s[98:99]
	v_lshl_add_u64 v[76:77], v[76:77], 0, s[98:99]
	v_lshl_add_u64 v[80:81], v[80:81], 0, s[98:99]
	s_waitcnt vmcnt(0)
	s_waitcnt lgkmcnt(0)
	s_barrier
	s_add_u32 m0, s32, 0x4000
	v_mfma_f32_32x32x16_bf16 v[50:65], v[162:165], v[182:185], v[50:65]
	global_load_lds_dwordx4 v[66:67], off
	s_add_u32 m0, s32, 0x5000
	v_mfma_f32_32x32x16_bf16 v[34:49], v[162:165], v[186:189], v[34:49]
	global_load_lds_dwordx4 v[70:71], off
	s_add_u32 m0, s32, 0x6000
	v_mfma_f32_32x32x16_bf16 v[18:33], v[166:169], v[182:185], v[18:33]
	global_load_lds_dwordx4 v[74:75], off
	s_add_u32 m0, s32, 0x7000
	v_mfma_f32_32x32x16_bf16 v[2:17], v[166:169], v[186:189], v[2:17]
	global_load_lds_dwordx4 v[78:79], off
	s_add_u32 m0, s32, 0xc000
	v_mfma_f32_32x32x16_bf16 v[50:65], v[190:193], v[198:201], v[50:65]
	global_load_lds_dwordx4 v[68:69], off
	s_add_u32 m0, s32, 0xd000
	v_mfma_f32_32x32x16_bf16 v[34:49], v[190:193], v[202:205], v[34:49]
	global_load_lds_dwordx4 v[72:73], off
	s_add_u32 m0, s32, 0xe000
	v_mfma_f32_32x32x16_bf16 v[18:33], v[194:197], v[198:201], v[18:33]
	global_load_lds_dwordx4 v[76:77], off
	s_add_u32 m0, s32, 0xf000
	v_mfma_f32_32x32x16_bf16 v[2:17], v[194:197], v[202:205], v[2:17]
	global_load_lds_dwordx4 v[80:81], off
	ds_read_b128 v[162:165], v91
	ds_read_b128 v[166:169], v92 offset:32768
	ds_read_b128 v[182:185], v91 offset:4096
	ds_read_b128 v[186:189], v92 offset:36864
	ds_read_b128 v[190:193], v93
	ds_read_b128 v[194:197], v90 offset:32768
	ds_read_b128 v[198:201], v93 offset:4096
	ds_read_b128 v[202:205], v90 offset:36864
	s_waitcnt lgkmcnt(6)
	v_mfma_f32_32x32x16_bf16 v[50:65], v[162:165], v[166:169], v[50:65]
	s_waitcnt lgkmcnt(4)
	v_mfma_f32_32x32x16_bf16 v[34:49], v[162:165], v[186:189], v[34:49]
	v_mfma_f32_32x32x16_bf16 v[18:33], v[182:185], v[166:169], v[18:33]
	v_mfma_f32_32x32x16_bf16 v[2:17], v[182:185], v[186:189], v[2:17]
	ds_read_b128 v[162:165], v89
	ds_read_b128 v[166:169], v89 offset:4096
	ds_read_b128 v[182:185], v88 offset:32768
	ds_read_b128 v[186:189], v88 offset:36864
	s_waitcnt lgkmcnt(6)
	v_mfma_f32_32x32x16_bf16 v[50:65], v[190:193], v[194:197], v[50:65]
	s_waitcnt lgkmcnt(4)
	v_mfma_f32_32x32x16_bf16 v[34:49], v[190:193], v[202:205], v[34:49]
	v_mfma_f32_32x32x16_bf16 v[18:33], v[198:201], v[194:197], v[18:33]
	v_mfma_f32_32x32x16_bf16 v[2:17], v[198:201], v[202:205], v[2:17]
	ds_read_b128 v[190:193], v87
	ds_read_b128 v[194:197], v87 offset:4096
	ds_read_b128 v[198:201], v86 offset:32768
	ds_read_b128 v[202:205], v86 offset:36864
	v_lshl_add_u64 v[66:67], v[66:67], 0, s[98:99]
	v_lshl_add_u64 v[70:71], v[70:71], 0, s[98:99]
	v_lshl_add_u64 v[74:75], v[74:75], 0, s[98:99]
	v_lshl_add_u64 v[78:79], v[78:79], 0, s[98:99]
	v_lshl_add_u64 v[68:69], v[68:69], 0, s[98:99]
	v_lshl_add_u64 v[72:73], v[72:73], 0, s[98:99]
	v_lshl_add_u64 v[76:77], v[76:77], 0, s[98:99]
	v_lshl_add_u64 v[80:81], v[80:81], 0, s[98:99]
	s_waitcnt vmcnt(0)
	s_waitcnt lgkmcnt(0)
	s_barrier
	s_add_u32 m0, s32, 0x0
	v_mfma_f32_32x32x16_bf16 v[50:65], v[162:165], v[182:185], v[50:65]
	global_load_lds_dwordx4 v[66:67], off
	s_add_u32 m0, s32, 0x1000
	v_mfma_f32_32x32x16_bf16 v[34:49], v[162:165], v[186:189], v[34:49]
	global_load_lds_dwordx4 v[70:71], off
	s_add_u32 m0, s32, 0x2000
	v_mfma_f32_32x32x16_bf16 v[18:33], v[166:169], v[182:185], v[18:33]
	global_load_lds_dwordx4 v[74:75], off
	s_add_u32 m0, s32, 0x3000
	v_mfma_f32_32x32x16_bf16 v[2:17], v[166:169], v[186:189], v[2:17]
	global_load_lds_dwordx4 v[78:79], off
	s_add_u32 m0, s32, 0x8000
	v_mfma_f32_32x32x16_bf16 v[50:65], v[190:193], v[198:201], v[50:65]
	global_load_lds_dwordx4 v[68:69], off
	s_add_u32 m0, s32, 0x9000
	v_mfma_f32_32x32x16_bf16 v[34:49], v[190:193], v[202:205], v[34:49]
	global_load_lds_dwordx4 v[72:73], off
	s_add_u32 m0, s32, 0xa000
	v_mfma_f32_32x32x16_bf16 v[18:33], v[194:197], v[198:201], v[18:33]
	global_load_lds_dwordx4 v[76:77], off
	s_add_u32 m0, s32, 0xb000
	v_mfma_f32_32x32x16_bf16 v[2:17], v[194:197], v[202:205], v[2:17]
	global_load_lds_dwordx4 v[80:81], off
	ds_read_b128 v[162:165], v91 offset:16384
	ds_read_b128 v[166:169], v92 offset:49152
	ds_read_b128 v[182:185], v91 offset:20480
	ds_read_b128 v[186:189], v92 offset:53248
	ds_read_b128 v[190:193], v93 offset:16384
	ds_read_b128 v[194:197], v90 offset:49152
	ds_read_b128 v[198:201], v93 offset:20480
	ds_read_b128 v[202:205], v90 offset:53248
	s_waitcnt lgkmcnt(6)
	v_mfma_f32_32x32x16_bf16 v[50:65], v[162:165], v[166:169], v[50:65]
	s_waitcnt lgkmcnt(4)
	v_mfma_f32_32x32x16_bf16 v[34:49], v[162:165], v[186:189], v[34:49]
	v_mfma_f32_32x32x16_bf16 v[18:33], v[182:185], v[166:169], v[18:33]
	v_mfma_f32_32x32x16_bf16 v[2:17], v[182:185], v[186:189], v[2:17]
	ds_read_b128 v[162:165], v89 offset:16384
	ds_read_b128 v[166:169], v89 offset:20480
	ds_read_b128 v[182:185], v88 offset:49152
	ds_read_b128 v[186:189], v88 offset:53248
	s_waitcnt lgkmcnt(6)
	v_mfma_f32_32x32x16_bf16 v[50:65], v[190:193], v[194:197], v[50:65]
	s_waitcnt lgkmcnt(4)
	v_mfma_f32_32x32x16_bf16 v[34:49], v[190:193], v[202:205], v[34:49]
	v_mfma_f32_32x32x16_bf16 v[18:33], v[198:201], v[194:197], v[18:33]
	v_mfma_f32_32x32x16_bf16 v[2:17], v[198:201], v[202:205], v[2:17]
	ds_read_b128 v[190:193], v87 offset:16384
	ds_read_b128 v[194:197], v87 offset:20480
	ds_read_b128 v[198:201], v86 offset:49152
	ds_read_b128 v[202:205], v86 offset:53248
	v_lshl_add_u64 v[66:67], v[66:67], 0, s[98:99]
	v_lshl_add_u64 v[70:71], v[70:71], 0, s[98:99]
	v_lshl_add_u64 v[74:75], v[74:75], 0, s[98:99]
	v_lshl_add_u64 v[78:79], v[78:79], 0, s[98:99]
	v_lshl_add_u64 v[68:69], v[68:69], 0, s[98:99]
	v_lshl_add_u64 v[72:73], v[72:73], 0, s[98:99]
	v_lshl_add_u64 v[76:77], v[76:77], 0, s[98:99]
	v_lshl_add_u64 v[80:81], v[80:81], 0, s[98:99]
	s_waitcnt vmcnt(0)
	s_waitcnt lgkmcnt(0)
	s_barrier
	s_add_u32 m0, s32, 0x4000
	v_mfma_f32_32x32x16_bf16 v[50:65], v[162:165], v[182:185], v[50:65]
	global_load_lds_dwordx4 v[66:67], off
	s_add_u32 m0, s32, 0x5000
	v_mfma_f32_32x32x16_bf16 v[34:49], v[162:165], v[186:189], v[34:49]
	global_load_lds_dwordx4 v[70:71], off
	s_add_u32 m0, s32, 0x6000
	v_mfma_f32_32x32x16_bf16 v[18:33], v[166:169], v[182:185], v[18:33]
	global_load_lds_dwordx4 v[74:75], off
	s_add_u32 m0, s32, 0x7000
	v_mfma_f32_32x32x16_bf16 v[2:17], v[166:169], v[186:189], v[2:17]
	global_load_lds_dwordx4 v[78:79], off
	s_add_u32 m0, s32, 0xc000
	v_mfma_f32_32x32x16_bf16 v[50:65], v[190:193], v[198:201], v[50:65]
	global_load_lds_dwordx4 v[68:69], off
	s_add_u32 m0, s32, 0xd000
	v_mfma_f32_32x32x16_bf16 v[34:49], v[190:193], v[202:205], v[34:49]
	global_load_lds_dwordx4 v[72:73], off
	s_add_u32 m0, s32, 0xe000
	v_mfma_f32_32x32x16_bf16 v[18:33], v[194:197], v[198:201], v[18:33]
	global_load_lds_dwordx4 v[76:77], off
	s_add_u32 m0, s32, 0xf000
	v_mfma_f32_32x32x16_bf16 v[2:17], v[194:197], v[202:205], v[2:17]
	global_load_lds_dwordx4 v[80:81], off
	ds_read_b128 v[162:165], v91
	ds_read_b128 v[166:169], v92 offset:32768
	ds_read_b128 v[182:185], v91 offset:4096
	ds_read_b128 v[186:189], v92 offset:36864
	ds_read_b128 v[190:193], v93
	ds_read_b128 v[194:197], v90 offset:32768
	ds_read_b128 v[198:201], v93 offset:4096
	ds_read_b128 v[202:205], v90 offset:36864
	s_waitcnt lgkmcnt(6)
	v_mfma_f32_32x32x16_bf16 v[50:65], v[162:165], v[166:169], v[50:65]
	s_waitcnt lgkmcnt(4)
	v_mfma_f32_32x32x16_bf16 v[34:49], v[162:165], v[186:189], v[34:49]
	v_mfma_f32_32x32x16_bf16 v[18:33], v[182:185], v[166:169], v[18:33]
	v_mfma_f32_32x32x16_bf16 v[2:17], v[182:185], v[186:189], v[2:17]
	ds_read_b128 v[162:165], v89
	ds_read_b128 v[166:169], v89 offset:4096
	ds_read_b128 v[182:185], v88 offset:32768
	ds_read_b128 v[186:189], v88 offset:36864
	s_waitcnt lgkmcnt(6)
	v_mfma_f32_32x32x16_bf16 v[50:65], v[190:193], v[194:197], v[50:65]
	s_waitcnt lgkmcnt(4)
	v_mfma_f32_32x32x16_bf16 v[34:49], v[190:193], v[202:205], v[34:49]
	v_mfma_f32_32x32x16_bf16 v[18:33], v[198:201], v[194:197], v[18:33]
	v_mfma_f32_32x32x16_bf16 v[2:17], v[198:201], v[202:205], v[2:17]
	ds_read_b128 v[190:193], v87
	ds_read_b128 v[194:197], v87 offset:4096
	ds_read_b128 v[198:201], v86 offset:32768
	ds_read_b128 v[202:205], v86 offset:36864
	v_lshl_add_u64 v[66:67], v[66:67], 0, s[98:99]
	v_lshl_add_u64 v[70:71], v[70:71], 0, s[98:99]
	v_lshl_add_u64 v[74:75], v[74:75], 0, s[98:99]
	v_lshl_add_u64 v[78:79], v[78:79], 0, s[98:99]
	v_lshl_add_u64 v[68:69], v[68:69], 0, s[98:99]
	v_lshl_add_u64 v[72:73], v[72:73], 0, s[98:99]
	v_lshl_add_u64 v[76:77], v[76:77], 0, s[98:99]
	v_lshl_add_u64 v[80:81], v[80:81], 0, s[98:99]
	s_waitcnt vmcnt(0)
	s_waitcnt lgkmcnt(0)
	s_barrier
	s_add_u32 m0, s32, 0x0
	v_mfma_f32_32x32x16_bf16 v[50:65], v[162:165], v[182:185], v[50:65]
	global_load_lds_dwordx4 v[66:67], off
	s_add_u32 m0, s32, 0x1000
	v_mfma_f32_32x32x16_bf16 v[34:49], v[162:165], v[186:189], v[34:49]
	global_load_lds_dwordx4 v[70:71], off
	s_add_u32 m0, s32, 0x2000
	v_mfma_f32_32x32x16_bf16 v[18:33], v[166:169], v[182:185], v[18:33]
	global_load_lds_dwordx4 v[74:75], off
	s_add_u32 m0, s32, 0x3000
	v_mfma_f32_32x32x16_bf16 v[2:17], v[166:169], v[186:189], v[2:17]
	global_load_lds_dwordx4 v[78:79], off
	s_add_u32 m0, s32, 0x8000
	v_mfma_f32_32x32x16_bf16 v[50:65], v[190:193], v[198:201], v[50:65]
	global_load_lds_dwordx4 v[68:69], off
	s_add_u32 m0, s32, 0x9000
	v_mfma_f32_32x32x16_bf16 v[34:49], v[190:193], v[202:205], v[34:49]
	global_load_lds_dwordx4 v[72:73], off
	s_add_u32 m0, s32, 0xa000
	v_mfma_f32_32x32x16_bf16 v[18:33], v[194:197], v[198:201], v[18:33]
	global_load_lds_dwordx4 v[76:77], off
	s_add_u32 m0, s32, 0xb000
	v_mfma_f32_32x32x16_bf16 v[2:17], v[194:197], v[202:205], v[2:17]
	global_load_lds_dwordx4 v[80:81], off
	ds_read_b128 v[162:165], v91 offset:16384
	ds_read_b128 v[166:169], v92 offset:49152
	ds_read_b128 v[182:185], v91 offset:20480
	ds_read_b128 v[186:189], v92 offset:53248
	ds_read_b128 v[190:193], v93 offset:16384
	ds_read_b128 v[194:197], v90 offset:49152
	ds_read_b128 v[198:201], v93 offset:20480
	ds_read_b128 v[202:205], v90 offset:53248
	s_waitcnt lgkmcnt(6)
	v_mfma_f32_32x32x16_bf16 v[50:65], v[162:165], v[166:169], v[50:65]
	s_waitcnt lgkmcnt(4)
	v_mfma_f32_32x32x16_bf16 v[34:49], v[162:165], v[186:189], v[34:49]
	v_mfma_f32_32x32x16_bf16 v[18:33], v[182:185], v[166:169], v[18:33]
	v_mfma_f32_32x32x16_bf16 v[2:17], v[182:185], v[186:189], v[2:17]
	ds_read_b128 v[162:165], v89 offset:16384
	ds_read_b128 v[166:169], v89 offset:20480
	ds_read_b128 v[182:185], v88 offset:49152
	ds_read_b128 v[186:189], v88 offset:53248
	s_waitcnt lgkmcnt(6)
	v_mfma_f32_32x32x16_bf16 v[50:65], v[190:193], v[194:197], v[50:65]
	s_waitcnt lgkmcnt(4)
	v_mfma_f32_32x32x16_bf16 v[34:49], v[190:193], v[202:205], v[34:49]
	v_mfma_f32_32x32x16_bf16 v[18:33], v[198:201], v[194:197], v[18:33]
	v_mfma_f32_32x32x16_bf16 v[2:17], v[198:201], v[202:205], v[2:17]
	ds_read_b128 v[190:193], v87 offset:16384
	ds_read_b128 v[194:197], v87 offset:20480
	ds_read_b128 v[198:201], v86 offset:49152
	ds_read_b128 v[202:205], v86 offset:53248
	v_lshl_add_u64 v[66:67], v[66:67], 0, s[98:99]
	v_lshl_add_u64 v[70:71], v[70:71], 0, s[98:99]
	v_lshl_add_u64 v[74:75], v[74:75], 0, s[98:99]
	v_lshl_add_u64 v[78:79], v[78:79], 0, s[98:99]
	v_lshl_add_u64 v[68:69], v[68:69], 0, s[98:99]
	v_lshl_add_u64 v[72:73], v[72:73], 0, s[98:99]
	v_lshl_add_u64 v[76:77], v[76:77], 0, s[98:99]
	v_lshl_add_u64 v[80:81], v[80:81], 0, s[98:99]
	s_waitcnt vmcnt(0)
	s_waitcnt lgkmcnt(0)
	s_barrier
	s_add_u32 m0, s32, 0x4000
	v_mfma_f32_32x32x16_bf16 v[50:65], v[162:165], v[182:185], v[50:65]
	global_load_lds_dwordx4 v[66:67], off
	s_add_u32 m0, s32, 0x5000
	v_mfma_f32_32x32x16_bf16 v[34:49], v[162:165], v[186:189], v[34:49]
	global_load_lds_dwordx4 v[70:71], off
	s_add_u32 m0, s32, 0x6000
	v_mfma_f32_32x32x16_bf16 v[18:33], v[166:169], v[182:185], v[18:33]
	global_load_lds_dwordx4 v[74:75], off
	s_add_u32 m0, s32, 0x7000
	v_mfma_f32_32x32x16_bf16 v[2:17], v[166:169], v[186:189], v[2:17]
	global_load_lds_dwordx4 v[78:79], off
	s_add_u32 m0, s32, 0xc000
	v_mfma_f32_32x32x16_bf16 v[50:65], v[190:193], v[198:201], v[50:65]
	global_load_lds_dwordx4 v[68:69], off
	s_add_u32 m0, s32, 0xd000
	v_mfma_f32_32x32x16_bf16 v[34:49], v[190:193], v[202:205], v[34:49]
	global_load_lds_dwordx4 v[72:73], off
	s_add_u32 m0, s32, 0xe000
	v_mfma_f32_32x32x16_bf16 v[18:33], v[194:197], v[198:201], v[18:33]
	global_load_lds_dwordx4 v[76:77], off
	s_add_u32 m0, s32, 0xf000
	v_mfma_f32_32x32x16_bf16 v[2:17], v[194:197], v[202:205], v[2:17]
	global_load_lds_dwordx4 v[80:81], off
	ds_read_b128 v[162:165], v91
	ds_read_b128 v[166:169], v92 offset:32768
	ds_read_b128 v[182:185], v91 offset:4096
	ds_read_b128 v[186:189], v92 offset:36864
	ds_read_b128 v[190:193], v93
	ds_read_b128 v[194:197], v90 offset:32768
	ds_read_b128 v[198:201], v93 offset:4096
	ds_read_b128 v[202:205], v90 offset:36864
	s_waitcnt lgkmcnt(6)
	v_mfma_f32_32x32x16_bf16 v[50:65], v[162:165], v[166:169], v[50:65]
	s_waitcnt lgkmcnt(4)
	v_mfma_f32_32x32x16_bf16 v[34:49], v[162:165], v[186:189], v[34:49]
	v_mfma_f32_32x32x16_bf16 v[18:33], v[182:185], v[166:169], v[18:33]
	v_mfma_f32_32x32x16_bf16 v[2:17], v[182:185], v[186:189], v[2:17]
	ds_read_b128 v[162:165], v89
	ds_read_b128 v[166:169], v89 offset:4096
	ds_read_b128 v[182:185], v88 offset:32768
	ds_read_b128 v[186:189], v88 offset:36864
	s_waitcnt lgkmcnt(6)
	v_mfma_f32_32x32x16_bf16 v[50:65], v[190:193], v[194:197], v[50:65]
	s_waitcnt lgkmcnt(4)
	v_mfma_f32_32x32x16_bf16 v[34:49], v[190:193], v[202:205], v[34:49]
	v_mfma_f32_32x32x16_bf16 v[18:33], v[198:201], v[194:197], v[18:33]
	v_mfma_f32_32x32x16_bf16 v[2:17], v[198:201], v[202:205], v[2:17]
	ds_read_b128 v[190:193], v87
	ds_read_b128 v[194:197], v87 offset:4096
	ds_read_b128 v[198:201], v86 offset:32768
	ds_read_b128 v[202:205], v86 offset:36864
	v_lshl_add_u64 v[66:67], v[66:67], 0, s[98:99]
	v_lshl_add_u64 v[70:71], v[70:71], 0, s[98:99]
	v_lshl_add_u64 v[74:75], v[74:75], 0, s[98:99]
	v_lshl_add_u64 v[78:79], v[78:79], 0, s[98:99]
	v_lshl_add_u64 v[68:69], v[68:69], 0, s[98:99]
	v_lshl_add_u64 v[72:73], v[72:73], 0, s[98:99]
	v_lshl_add_u64 v[76:77], v[76:77], 0, s[98:99]
	v_lshl_add_u64 v[80:81], v[80:81], 0, s[98:99]
	s_waitcnt vmcnt(0)
	s_waitcnt lgkmcnt(0)
	s_barrier
	s_add_u32 m0, s32, 0x0
	s_nop 0
	global_load_lds_dwordx4 v[66:67], off
	s_add_u32 m0, s32, 0x1000
	s_nop 0
	global_load_lds_dwordx4 v[70:71], off
	s_add_u32 m0, s32, 0x2000
	s_nop 0
	global_load_lds_dwordx4 v[74:75], off
	s_add_u32 m0, s32, 0x3000
	s_nop 0
	global_load_lds_dwordx4 v[78:79], off
	s_add_u32 m0, s32, 0x8000
	s_nop 0
	global_load_lds_dwordx4 v[68:69], off
	s_add_u32 m0, s32, 0x9000
	s_nop 0
	global_load_lds_dwordx4 v[72:73], off
	s_add_u32 m0, s32, 0xa000
	s_nop 0
	global_load_lds_dwordx4 v[76:77], off
	s_add_u32 m0, s32, 0xb000
	s_nop 0
	global_load_lds_dwordx4 v[80:81], off
	s_nop 0
	s_nop 0
	s_nop 0
	s_nop 0
	s_nop 0
	s_nop 0
	s_nop 0
	v_mfma_f32_32x32x16_bf16 v[50:65], v[162:165], v[182:185], v[50:65]
	v_mfma_f32_32x32x16_bf16 v[34:49], v[162:165], v[186:189], v[34:49]
	v_mfma_f32_32x32x16_bf16 v[18:33], v[166:169], v[182:185], v[18:33]
	v_mfma_f32_32x32x16_bf16 v[2:17], v[166:169], v[186:189], v[2:17]
	ds_read_b128 v[110:113], v91 offset:16384
	ds_read_b128 v[114:117], v91 offset:20480
	ds_read_b128 v[118:121], v92 offset:49152
	ds_read_b128 v[122:125], v92 offset:53248
	ds_read_b128 v[162:165], v93 offset:16384
	ds_read_b128 v[166:169], v93 offset:20480
	ds_read_b128 v[182:185], v90 offset:49152
	ds_read_b128 v[186:189], v90 offset:53248
	v_mfma_f32_32x32x16_bf16 v[50:65], v[190:193], v[198:201], v[50:65]
	v_mfma_f32_32x32x16_bf16 v[34:49], v[190:193], v[202:205], v[34:49]
	v_mfma_f32_32x32x16_bf16 v[18:33], v[194:197], v[198:201], v[18:33]
	v_mfma_f32_32x32x16_bf16 v[2:17], v[194:197], v[202:205], v[2:17]
	s_waitcnt lgkmcnt(5)
	v_mfma_f32_32x32x16_bf16 v[50:65], v[110:113], v[118:121], v[50:65]
	s_waitcnt lgkmcnt(4)
	v_mfma_f32_32x32x16_bf16 v[34:49], v[110:113], v[122:125], v[34:49]
	v_mfma_f32_32x32x16_bf16 v[18:33], v[114:117], v[118:121], v[18:33]
	v_mfma_f32_32x32x16_bf16 v[2:17], v[114:117], v[122:125], v[2:17]
	ds_read_b128 v[110:113], v89 offset:16384
	ds_read_b128 v[114:117], v89 offset:20480
	ds_read_b128 v[118:121], v88 offset:49152
	ds_read_b128 v[122:125], v88 offset:53248
	s_waitcnt lgkmcnt(5)
	v_mfma_f32_32x32x16_bf16 v[50:65], v[162:165], v[182:185], v[50:65]
	s_waitcnt lgkmcnt(4)
	v_mfma_f32_32x32x16_bf16 v[34:49], v[162:165], v[186:189], v[34:49]
	v_mfma_f32_32x32x16_bf16 v[18:33], v[166:169], v[182:185], v[18:33]
	v_mfma_f32_32x32x16_bf16 v[2:17], v[166:169], v[186:189], v[2:17]
	ds_read_b128 v[162:165], v87 offset:16384
	ds_read_b128 v[166:169], v87 offset:20480
	ds_read_b128 v[182:185], v86 offset:49152
	ds_read_b128 v[186:189], v86 offset:53248
	s_waitcnt lgkmcnt(5)
	v_mfma_f32_32x32x16_bf16 v[50:65], v[110:113], v[118:121], v[50:65]
	v_lshl_add_u64 v[66:67], v[66:67], 0, s[98:99]
	v_lshl_add_u64 v[70:71], v[70:71], 0, s[98:99]
	v_lshl_add_u64 v[74:75], v[74:75], 0, s[98:99]
	v_lshl_add_u64 v[78:79], v[78:79], 0, s[98:99]
	v_lshl_add_u64 v[68:69], v[68:69], 0, s[98:99]
	v_lshl_add_u64 v[72:73], v[72:73], 0, s[98:99]
	v_lshl_add_u64 v[76:77], v[76:77], 0, s[98:99]
	v_lshl_add_u64 v[80:81], v[80:81], 0, s[98:99]
	s_waitcnt vmcnt(0)
	s_waitcnt lgkmcnt(0)
	s_barrier
	s_add_u32 m0, s32, 0x4000
	s_nop 0
	global_load_lds_dwordx4 v[66:67], off
	s_add_u32 m0, s32, 0x5000
	s_nop 0
	global_load_lds_dwordx4 v[70:71], off
	s_add_u32 m0, s32, 0x6000
	s_nop 0
	global_load_lds_dwordx4 v[74:75], off
	s_add_u32 m0, s32, 0x7000
	s_nop 0
	global_load_lds_dwordx4 v[78:79], off
	s_add_u32 m0, s32, 0xc000
	s_nop 0
	global_load_lds_dwordx4 v[68:69], off
	s_add_u32 m0, s32, 0xd000
	s_nop 0
	global_load_lds_dwordx4 v[72:73], off
	s_add_u32 m0, s32, 0xe000
	s_nop 0
	global_load_lds_dwordx4 v[76:77], off
	s_add_u32 m0, s32, 0xf000
	s_nop 0
	global_load_lds_dwordx4 v[80:81], off
	v_mfma_f32_32x32x16_bf16 v[34:49], v[110:113], v[122:125], v[34:49]
	v_mfma_f32_32x32x16_bf16 v[18:33], v[114:117], v[118:121], v[18:33]
	v_mfma_f32_32x32x16_bf16 v[2:17], v[114:117], v[122:125], v[2:17]
	ds_read_b128 v[110:113], v91
	ds_read_b128 v[114:117], v91 offset:4096
	ds_read_b128 v[118:121], v92 offset:32768
	ds_read_b128 v[122:125], v92 offset:36864
	ds_read_b128 v[126:129], v93
	ds_read_b128 v[134:137], v93 offset:4096
	ds_read_b128 v[138:141], v90 offset:32768
	ds_read_b128 v[142:145], v90 offset:36864
	v_mfma_f32_32x32x16_bf16 v[50:65], v[162:165], v[182:185], v[50:65]
	v_mfma_f32_32x32x16_bf16 v[34:49], v[162:165], v[186:189], v[34:49]
	v_mfma_f32_32x32x16_bf16 v[18:33], v[166:169], v[182:185], v[18:33]
	v_mfma_f32_32x32x16_bf16 v[2:17], v[166:169], v[186:189], v[2:17]
	s_waitcnt lgkmcnt(5)
	v_mfma_f32_32x32x16_bf16 v[50:65], v[110:113], v[118:121], v[50:65]
	s_waitcnt lgkmcnt(4)
	v_mfma_f32_32x32x16_bf16 v[34:49], v[110:113], v[122:125], v[34:49]
	v_mfma_f32_32x32x16_bf16 v[18:33], v[114:117], v[118:121], v[18:33]
	v_mfma_f32_32x32x16_bf16 v[2:17], v[114:117], v[122:125], v[2:17]
	ds_read_b128 v[110:113], v89
	ds_read_b128 v[114:117], v89 offset:4096
	ds_read_b128 v[118:121], v88 offset:32768
	ds_read_b128 v[122:125], v88 offset:36864
	s_waitcnt lgkmcnt(5)
	v_mfma_f32_32x32x16_bf16 v[50:65], v[126:129], v[138:141], v[50:65]
	s_waitcnt lgkmcnt(4)
	v_mfma_f32_32x32x16_bf16 v[34:49], v[126:129], v[142:145], v[34:49]
	v_mfma_f32_32x32x16_bf16 v[18:33], v[134:137], v[138:141], v[18:33]
	v_mfma_f32_32x32x16_bf16 v[2:17], v[134:137], v[142:145], v[2:17]
	ds_read_b128 v[126:129], v87
	ds_read_b128 v[134:137], v87 offset:4096
	ds_read_b128 v[138:141], v86 offset:32768
	ds_read_b128 v[142:145], v86 offset:36864
	s_waitcnt lgkmcnt(5)
	v_mfma_f32_32x32x16_bf16 v[50:65], v[110:113], v[118:121], v[50:65]
	s_waitcnt vmcnt(0)
	s_waitcnt lgkmcnt(0)
	s_barrier
	ds_read_b128 v[66:69], v91 offset:16384
	ds_read_b128 v[70:73], v91 offset:20480
	ds_read_b128 v[74:77], v92 offset:49152
	ds_read_b128 v[78:81], v92 offset:53248
	ds_read_b128 v[94:97], v93 offset:16384
	ds_read_b128 v[98:101], v93 offset:20480
	ds_read_b128 v[102:105], v90 offset:49152
	ds_read_b128 v[90:93], v90 offset:53248
	v_mfma_f32_32x32x16_bf16 v[34:49], v[110:113], v[122:125], v[34:49]
	v_mfma_f32_32x32x16_bf16 v[18:33], v[114:117], v[118:121], v[18:33]
	v_mfma_f32_32x32x16_bf16 v[2:17], v[114:117], v[122:125], v[2:17]
	v_mfma_f32_32x32x16_bf16 v[50:65], v[126:129], v[138:141], v[50:65]
	v_mfma_f32_32x32x16_bf16 v[34:49], v[126:129], v[142:145], v[34:49]
	v_mfma_f32_32x32x16_bf16 v[18:33], v[134:137], v[138:141], v[18:33]
	v_mfma_f32_32x32x16_bf16 v[2:17], v[134:137], v[142:145], v[2:17]
	s_waitcnt lgkmcnt(5)
	v_mfma_f32_32x32x16_bf16 v[50:65], v[66:69], v[74:77], v[50:65]
	s_waitcnt lgkmcnt(4)
	v_mfma_f32_32x32x16_bf16 v[34:49], v[66:69], v[78:81], v[34:49]
	v_mfma_f32_32x32x16_bf16 v[18:33], v[70:73], v[74:77], v[18:33]
	v_mfma_f32_32x32x16_bf16 v[2:17], v[70:73], v[78:81], v[2:17]
	ds_read_b128 v[66:69], v89 offset:16384
	ds_read_b128 v[70:73], v89 offset:20480
	ds_read_b128 v[74:77], v88 offset:49152
	ds_read_b128 v[78:81], v88 offset:53248
	s_waitcnt lgkmcnt(5)
	v_mfma_f32_32x32x16_bf16 v[50:65], v[94:97], v[102:105], v[50:65]
	s_waitcnt lgkmcnt(4)
	v_mfma_f32_32x32x16_bf16 v[34:49], v[94:97], v[90:93], v[34:49]
	v_mfma_f32_32x32x16_bf16 v[18:33], v[98:101], v[102:105], v[18:33]
	v_mfma_f32_32x32x16_bf16 v[2:17], v[98:101], v[90:93], v[2:17]
	ds_read_b128 v[88:91], v87 offset:16384
	ds_read_b128 v[92:95], v87 offset:20480
	ds_read_b128 v[96:99], v86 offset:49152
	ds_read_b128 v[100:103], v86 offset:53248
	s_waitcnt lgkmcnt(5)
	v_mfma_f32_32x32x16_bf16 v[50:65], v[66:69], v[74:77], v[50:65]
	v_lshlrev_b32_e32 v0, 6, v85
	v_subrev_u32_e32 v0, s2, v0
	s_lshl_b32 s3, s34, 7
	s_movk_i32 s2, 0x9c0
	s_waitcnt lgkmcnt(0)
	s_barrier
	v_mfma_f32_32x32x16_bf16 v[34:49], v[66:69], v[78:81], v[34:49]
	v_add_u32_e32 v66, s7, v0
	v_lshl_add_u32 v68, v83, 6, s3
	v_add_u32_e32 v0, v66, v84
	v_cmp_lt_i32_e64 s[40:41], s63, v0
	v_cmp_gt_u32_e32 vcc, s2, v66
	v_lshl_add_u64 v[66:67], v[0:1], 1, s[48:49]
	v_mfma_f32_32x32x16_bf16 v[18:33], v[70:73], v[74:77], v[18:33]
	v_mfma_f32_32x32x16_bf16 v[2:17], v[70:73], v[78:81], v[2:17]
	v_lshl_or_b32 v70, v82, 2, v68
	v_mfma_f32_32x32x16_bf16 v[50:65], v[88:91], v[96:99], v[50:65]
	v_mfma_f32_32x32x16_bf16 v[34:49], v[88:91], v[100:103], v[34:49]
	v_mfma_f32_32x32x16_bf16 v[18:33], v[92:95], v[96:99], v[18:33]
	v_mfma_f32_32x32x16_bf16 v[2:17], v[92:95], v[100:103], v[2:17]
	s_and_saveexec_b64 s[2:3], s[40:41]
	s_xor_b64 s[2:3], exec, s[2:3]
	s_cbranch_execz .LBB0_236
	s_and_saveexec_b64 s[4:5], vcc
	s_cbranch_execz .LBB0_235
	s_nop 3
	v_cvt_pk_bf16_f32 v71, v50, s0
	v_mad_i64_i32 v[68:69], s[34:35], v70, s68, v[66:67]
	global_store_short v[68:69], v71, off offset:-1920

.LBB0_1186:
	s_ashr_i32 s5, s4, 31
	s_lshr_b32 s5, s5, 29
	s_add_i32 s5, s4, s5
	s_ashr_i32 s34, s5, 3
	s_ashr_i32 s35, s34, 31
	v_readlane_b32 s36, v210, 50
	v_mov_b32_e32 v36, v133
	s_lshl_b64 s[6:7], s[34:35], 18
	v_readlane_b32 s38, v210, 52
	v_readlane_b32 s39, v210, 53
	v_ashrrev_i32_e32 v34, 3, v36
	s_add_u32 s6, s38, s6
	v_ashrrev_i32_e32 v35, 31, v34
	s_addc_u32 s7, s39, s7
	v_lshlrev_b64 v[2:3], 11, v[34:35]
	v_lshlrev_b32_e32 v0, 4, v36
	v_lshl_add_u64 v[2:3], s[6:7], 0, v[2:3]
	v_and_b32_e32 v0, 0x70, v0
	s_lshl_b32 s5, s34, 10
	v_lshl_add_u64 v[66:67], v[2:3], 0, v[0:1]
	v_subrev_u32_e32 v2, s5, v34
	v_add_u32_e32 v2, s3, v2
	v_ashrrev_i32_e32 v3, 31, v2
	v_lshlrev_b64 v[2:3], 11, v[2:3]
	v_lshl_add_u64 v[2:3], s[0:1], 0, v[2:3]
	v_add_co_u32_e32 v70, vcc, s10, v66
	v_lshl_add_u64 v[68:69], v[2:3], 0, v[0:1]
	s_nop 0
	v_addc_co_u32_e32 v71, vcc, 0, v67, vcc
	v_add_co_u32_e32 v72, vcc, s10, v68
	v_addc_co_u32_e32 v73, vcc, 0, v69, vcc
	v_add_co_u32_e32 v74, vcc, s63, v66
	s_nop 0
	v_addc_co_u32_e32 v75, vcc, 0, v67, vcc
	v_add_co_u32_e32 v76, vcc, s63, v68
	s_nop 0
	v_addc_co_u32_e32 v77, vcc, 0, v69, vcc
	v_add_co_u32_e32 v78, vcc, s61, v66
	s_nop 0
	v_addc_co_u32_e32 v79, vcc, 0, v67, vcc
	v_add_co_u32_e32 v80, vcc, s61, v68
	v_lshlrev_b32_e32 v0, 7, v34
	s_nop 0
	v_addc_co_u32_e32 v81, vcc, 0, v69, vcc
	v_lshrrev_b32_e32 v216, 4, v133
	v_xor_b32_e32 v216, v216, v133
	v_and_b32_e32 v216, 7, v216
	v_lshlrev_b32_e32 v216, 4, v216
	v_mov_b32_e32 v217, 0x70
	v_lshrrev_b32_e32 v218, 6, v133
	v_lshlrev_b32_e32 v218, 10, v218
	s_nop 0
	v_readfirstlane_b32 s32, v218
	v_bfi_b32 v66, v217, v216, v66
	v_bfi_b32 v70, v217, v216, v70
	v_bfi_b32 v74, v217, v216, v74
	v_bfi_b32 v78, v217, v216, v78
	v_bfi_b32 v68, v217, v216, v68
	v_bfi_b32 v72, v217, v216, v72
	v_bfi_b32 v76, v217, v216, v76
	v_bfi_b32 v80, v217, v216, v80
	s_mov_b64 s[98:99], 0x80
	s_add_u32 m0, s32, 0x0
	s_nop 0
	global_load_lds_dwordx4 v[66:67], off
	s_add_u32 m0, s32, 0x1000
	s_nop 0
	global_load_lds_dwordx4 v[70:71], off
	s_add_u32 m0, s32, 0x2000
	s_nop 0
	global_load_lds_dwordx4 v[74:75], off
	s_add_u32 m0, s32, 0x3000
	s_nop 0
	global_load_lds_dwordx4 v[78:79], off
	s_add_u32 m0, s32, 0x8000
	s_nop 0
	global_load_lds_dwordx4 v[68:69], off
	s_add_u32 m0, s32, 0x9000
	s_nop 0
	global_load_lds_dwordx4 v[72:73], off
	s_add_u32 m0, s32, 0xa000
	s_nop 0
	global_load_lds_dwordx4 v[76:77], off
	s_add_u32 m0, s32, 0xb000
	s_nop 0
	global_load_lds_dwordx4 v[80:81], off
	v_lshl_add_u64 v[66:67], v[66:67], 0, s[98:99]
	v_lshl_add_u64 v[70:71], v[70:71], 0, s[98:99]
	v_lshl_add_u64 v[74:75], v[74:75], 0, s[98:99]
	v_lshl_add_u64 v[78:79], v[78:79], 0, s[98:99]
	v_lshl_add_u64 v[68:69], v[68:69], 0, s[98:99]
	v_lshl_add_u64 v[72:73], v[72:73], 0, s[98:99]
	v_lshl_add_u64 v[76:77], v[76:77], 0, s[98:99]
	v_lshl_add_u64 v[80:81], v[80:81], 0, s[98:99]
	v_lshrrev_b32_e32 v34, 1, v34
	v_xor_b32_e32 v34, v34, v36
	v_lshlrev_b32_e32 v34, 4, v34
	s_movk_i32 s6, 0x70
	v_and_or_b32 v0, v34, s6, v0
	s_waitcnt vmcnt(26)
	v_and_b32_e32 v82, 31, v36
	v_bfe_u32 v85, v36, 5, 1
	v_ashrrev_i32_e32 v84, 7, v36
	v_bfe_u32 v83, v36, 6, 1
	v_readlane_b32 s37, v210, 51
	v_readlane_b32 s40, v210, 54
	v_readlane_b32 s41, v210, 55
	v_readlane_b32 s42, v210, 56
	v_readlane_b32 s43, v210, 57
	v_readlane_b32 s44, v210, 58
	v_readlane_b32 s45, v210, 59
	v_readlane_b32 s46, v210, 60
	v_readlane_b32 s47, v210, 61
	v_readlane_b32 s48, v210, 62
	v_readlane_b32 s49, v210, 63
	v_readlane_b32 s50, v209, 0
	v_readlane_b32 s51, v209, 1
	s_waitcnt vmcnt(0)
	s_waitcnt lgkmcnt(0)
	s_barrier
	s_add_u32 m0, s32, 0x4000
	s_nop 0
	global_load_lds_dwordx4 v[66:67], off
	s_add_u32 m0, s32, 0x5000
	s_nop 0
	global_load_lds_dwordx4 v[70:71], off
	s_add_u32 m0, s32, 0x6000
	s_nop 0
	global_load_lds_dwordx4 v[74:75], off
	s_add_u32 m0, s32, 0x7000
	s_nop 0
	global_load_lds_dwordx4 v[78:79], off
	s_add_u32 m0, s32, 0xc000
	s_nop 0
	global_load_lds_dwordx4 v[68:69], off
	s_add_u32 m0, s32, 0xd000
	s_nop 0
	global_load_lds_dwordx4 v[72:73], off
	s_add_u32 m0, s32, 0xe000
	s_nop 0
	global_load_lds_dwordx4 v[76:77], off
	s_add_u32 m0, s32, 0xf000
	s_nop 0
	global_load_lds_dwordx4 v[80:81], off
	v_lshrrev_b32_e32 v4, 1, v36
	v_lshlrev_b32_e32 v2, 7, v82
	v_bitop3_b32 v4, v4, v85, 7 bitop3:0x6c
	v_lshl_or_b32 v3, v84, 13, v2
	v_bfe_u32 v5, v36, 1, 3
	v_lshlrev_b32_e32 v4, 4, v4
	v_lshl_or_b32 v2, v83, 13, v2
	v_or_b32_e32 v91, v3, v4
	v_or_b32_e32 v92, v2, v4
	v_bitop3_b32 v4, v85, v5, 2 bitop3:0x36
	v_lshlrev_b32_e32 v4, 4, v4
	v_or_b32_e32 v93, v3, v4
	v_or_b32_e32 v90, v2, v4
	v_bitop3_b32 v4, v85, v5, 4 bitop3:0x36
	v_lshlrev_b32_e32 v4, 4, v4
	v_or_b32_e32 v89, v3, v4
	v_or_b32_e32 v88, v2, v4
	v_bitop3_b32 v4, v85, v5, 6 bitop3:0x36
	v_lshlrev_b32_e32 v4, 4, v4
	v_or_b32_e32 v87, v3, v4
	v_or_b32_e32 v86, v2, v4
	ds_read_b128 v[2:5], v91
	ds_read_b128 v[6:9], v92 offset:32768
	ds_read_b128 v[10:13], v91 offset:4096
	ds_read_b128 v[14:17], v92 offset:36864
	ds_read_b128 v[162:165], v93
	ds_read_b128 v[166:169], v90 offset:32768
	ds_read_b128 v[182:185], v93 offset:4096
	ds_read_b128 v[186:189], v90 offset:36864
	s_waitcnt lgkmcnt(6)
	v_mfma_f32_32x32x16_bf16 v[50:65], v[2:5], v[6:9], 0
	s_waitcnt lgkmcnt(4)
	v_mfma_f32_32x32x16_bf16 v[18:33], v[2:5], v[14:17], 0
	v_mfma_f32_32x32x16_bf16 v[34:49], v[10:13], v[6:9], 0
	v_mfma_f32_32x32x16_bf16 v[2:17], v[10:13], v[14:17], 0
	ds_read_b128 v[190:193], v89
	ds_read_b128 v[194:197], v89 offset:4096
	ds_read_b128 v[198:201], v88 offset:32768
	ds_read_b128 v[202:205], v88 offset:36864
	s_waitcnt lgkmcnt(6)
	v_mfma_f32_32x32x16_bf16 v[50:65], v[162:165], v[166:169], v[50:65]
	s_waitcnt lgkmcnt(4)
	v_mfma_f32_32x32x16_bf16 v[18:33], v[162:165], v[186:189], v[18:33]
	v_mfma_f32_32x32x16_bf16 v[34:49], v[182:185], v[166:169], v[34:49]
	v_mfma_f32_32x32x16_bf16 v[2:17], v[182:185], v[186:189], v[2:17]
	ds_read_b128 v[162:165], v87
	ds_read_b128 v[166:169], v87 offset:4096
	ds_read_b128 v[182:185], v86 offset:32768
	ds_read_b128 v[186:189], v86 offset:36864
	v_lshl_add_u64 v[66:67], v[66:67], 0, s[98:99]
	v_lshl_add_u64 v[70:71], v[70:71], 0, s[98:99]
	v_lshl_add_u64 v[74:75], v[74:75], 0, s[98:99]
	v_lshl_add_u64 v[78:79], v[78:79], 0, s[98:99]
	v_lshl_add_u64 v[68:69], v[68:69], 0, s[98:99]
	v_lshl_add_u64 v[72:73], v[72:73], 0, s[98:99]
	v_lshl_add_u64 v[76:77], v[76:77], 0, s[98:99]
	v_lshl_add_u64 v[80:81], v[80:81], 0, s[98:99]
	s_waitcnt vmcnt(0)
	s_waitcnt lgkmcnt(0)
	s_barrier
	s_add_u32 m0, s32, 0x0
	v_mfma_f32_32x32x16_bf16 v[50:65], v[190:193], v[198:201], v[50:65]
	global_load_lds_dwordx4 v[66:67], off
	s_add_u32 m0, s32, 0x1000
	v_mfma_f32_32x32x16_bf16 v[18:33], v[190:193], v[202:205], v[18:33]
	global_load_lds_dwordx4 v[70:71], off
	s_add_u32 m0, s32, 0x2000
	v_mfma_f32_32x32x16_bf16 v[34:49], v[194:197], v[198:201], v[34:49]
	global_load_lds_dwordx4 v[74:75], off
	s_add_u32 m0, s32, 0x3000
	v_mfma_f32_32x32x16_bf16 v[2:17], v[194:197], v[202:205], v[2:17]
	global_load_lds_dwordx4 v[78:79], off
	s_add_u32 m0, s32, 0x8000
	v_mfma_f32_32x32x16_bf16 v[50:65], v[162:165], v[182:185], v[50:65]
	global_load_lds_dwordx4 v[68:69], off
	s_add_u32 m0, s32, 0x9000
	v_mfma_f32_32x32x16_bf16 v[18:33], v[162:165], v[186:189], v[18:33]
	global_load_lds_dwordx4 v[72:73], off
	s_add_u32 m0, s32, 0xa000
	v_mfma_f32_32x32x16_bf16 v[34:49], v[166:169], v[182:185], v[34:49]
	global_load_lds_dwordx4 v[76:77], off
	s_add_u32 m0, s32, 0xb000
	v_mfma_f32_32x32x16_bf16 v[2:17], v[166:169], v[186:189], v[2:17]
	global_load_lds_dwordx4 v[80:81], off
	ds_read_b128 v[162:165], v91 offset:16384
	ds_read_b128 v[166:169], v92 offset:49152
	ds_read_b128 v[182:185], v91 offset:20480
	ds_read_b128 v[186:189], v92 offset:53248
	ds_read_b128 v[190:193], v93 offset:16384
	ds_read_b128 v[194:197], v90 offset:49152
	ds_read_b128 v[198:201], v93 offset:20480
	ds_read_b128 v[202:205], v90 offset:53248
	s_waitcnt lgkmcnt(6)
	v_mfma_f32_32x32x16_bf16 v[50:65], v[162:165], v[166:169], v[50:65]
	s_waitcnt lgkmcnt(4)
	v_mfma_f32_32x32x16_bf16 v[18:33], v[162:165], v[186:189], v[18:33]
	v_mfma_f32_32x32x16_bf16 v[34:49], v[182:185], v[166:169], v[34:49]
	v_mfma_f32_32x32x16_bf16 v[2:17], v[182:185], v[186:189], v[2:17]
	ds_read_b128 v[162:165], v89 offset:16384
	ds_read_b128 v[166:169], v89 offset:20480
	ds_read_b128 v[182:185], v88 offset:49152
	ds_read_b128 v[186:189], v88 offset:53248
	s_waitcnt lgkmcnt(6)
	v_mfma_f32_32x32x16_bf16 v[50:65], v[190:193], v[194:197], v[50:65]
	s_waitcnt lgkmcnt(4)
	v_mfma_f32_32x32x16_bf16 v[18:33], v[190:193], v[202:205], v[18:33]
	v_mfma_f32_32x32x16_bf16 v[34:49], v[198:201], v[194:197], v[34:49]
	v_mfma_f32_32x32x16_bf16 v[2:17], v[198:201], v[202:205], v[2:17]
	ds_read_b128 v[190:193], v87 offset:16384
	ds_read_b128 v[194:197], v87 offset:20480
	ds_read_b128 v[198:201], v86 offset:49152
	ds_read_b128 v[202:205], v86 offset:53248
	v_lshl_add_u64 v[66:67], v[66:67], 0, s[98:99]
	v_lshl_add_u64 v[70:71], v[70:71], 0, s[98:99]
	v_lshl_add_u64 v[74:75], v[74:75], 0, s[98:99]
	v_lshl_add_u64 v[78:79], v[78:79], 0, s[98:99]
	v_lshl_add_u64 v[68:69], v[68:69], 0, s[98:99]
	v_lshl_add_u64 v[72:73], v[72:73], 0, s[98:99]
	v_lshl_add_u64 v[76:77], v[76:77], 0, s[98:99]
	v_lshl_add_u64 v[80:81], v[80:81], 0, s[98:99]
	s_waitcnt vmcnt(0)
	s_waitcnt lgkmcnt(0)
	s_barrier
	s_add_u32 m0, s32, 0x4000
	v_mfma_f32_32x32x16_bf16 v[50:65], v[162:165], v[182:185], v[50:65]
	global_load_lds_dwordx4 v[66:67], off
	s_add_u32 m0, s32, 0x5000
	v_mfma_f32_32x32x16_bf16 v[18:33], v[162:165], v[186:189], v[18:33]
	global_load_lds_dwordx4 v[70:71], off
	s_add_u32 m0, s32, 0x6000
	v_mfma_f32_32x32x16_bf16 v[34:49], v[166:169], v[182:185], v[34:49]
	global_load_lds_dwordx4 v[74:75], off
	s_add_u32 m0, s32, 0x7000
	v_mfma_f32_32x32x16_bf16 v[2:17], v[166:169], v[186:189], v[2:17]
	global_load_lds_dwordx4 v[78:79], off
	s_add_u32 m0, s32, 0xc000
	v_mfma_f32_32x32x16_bf16 v[50:65], v[190:193], v[198:201], v[50:65]
	global_load_lds_dwordx4 v[68:69], off
	s_add_u32 m0, s32, 0xd000
	v_mfma_f32_32x32x16_bf16 v[18:33], v[190:193], v[202:205], v[18:33]
	global_load_lds_dwordx4 v[72:73], off
	s_add_u32 m0, s32, 0xe000
	v_mfma_f32_32x32x16_bf16 v[34:49], v[194:197], v[198:201], v[34:49]
	global_load_lds_dwordx4 v[76:77], off
	s_add_u32 m0, s32, 0xf000
	v_mfma_f32_32x32x16_bf16 v[2:17], v[194:197], v[202:205], v[2:17]
	global_load_lds_dwordx4 v[80:81], off
	ds_read_b128 v[162:165], v91
	ds_read_b128 v[166:169], v92 offset:32768
	ds_read_b128 v[182:185], v91 offset:4096
	ds_read_b128 v[186:189], v92 offset:36864
	ds_read_b128 v[190:193], v93
	ds_read_b128 v[194:197], v90 offset:32768
	ds_read_b128 v[198:201], v93 offset:4096
	ds_read_b128 v[202:205], v90 offset:36864
	s_waitcnt lgkmcnt(6)
	v_mfma_f32_32x32x16_bf16 v[50:65], v[162:165], v[166:169], v[50:65]
	s_waitcnt lgkmcnt(4)
	v_mfma_f32_32x32x16_bf16 v[18:33], v[162:165], v[186:189], v[18:33]
	v_mfma_f32_32x32x16_bf16 v[34:49], v[182:185], v[166:169], v[34:49]
	v_mfma_f32_32x32x16_bf16 v[2:17], v[182:185], v[186:189], v[2:17]
	ds_read_b128 v[162:165], v89
	ds_read_b128 v[166:169], v89 offset:4096
	ds_read_b128 v[182:185], v88 offset:32768
	ds_read_b128 v[186:189], v88 offset:36864
	s_waitcnt lgkmcnt(6)
	v_mfma_f32_32x32x16_bf16 v[50:65], v[190:193], v[194:197], v[50:65]
	s_waitcnt lgkmcnt(4)
	v_mfma_f32_32x32x16_bf16 v[18:33], v[190:193], v[202:205], v[18:33]
	v_mfma_f32_32x32x16_bf16 v[34:49], v[198:201], v[194:197], v[34:49]
	v_mfma_f32_32x32x16_bf16 v[2:17], v[198:201], v[202:205], v[2:17]
	ds_read_b128 v[190:193], v87
	ds_read_b128 v[194:197], v87 offset:4096
	ds_read_b128 v[198:201], v86 offset:32768
	ds_read_b128 v[202:205], v86 offset:36864
	v_lshl_add_u64 v[66:67], v[66:67], 0, s[98:99]
	v_lshl_add_u64 v[70:71], v[70:71], 0, s[98:99]
	v_lshl_add_u64 v[74:75], v[74:75], 0, s[98:99]
	v_lshl_add_u64 v[78:79], v[78:79], 0, s[98:99]
	v_lshl_add_u64 v[68:69], v[68:69], 0, s[98:99]
	v_lshl_add_u64 v[72:73], v[72:73], 0, s[98:99]
	v_lshl_add_u64 v[76:77], v[76:77], 0, s[98:99]
	v_lshl_add_u64 v[80:81], v[80:81], 0, s[98:99]
	s_waitcnt vmcnt(0)
	s_waitcnt lgkmcnt(0)
	s_barrier
	s_add_u32 m0, s32, 0x0
	v_mfma_f32_32x32x16_bf16 v[50:65], v[162:165], v[182:185], v[50:65]
	global_load_lds_dwordx4 v[66:67], off
	s_add_u32 m0, s32, 0x1000
	v_mfma_f32_32x32x16_bf16 v[18:33], v[162:165], v[186:189], v[18:33]
	global_load_lds_dwordx4 v[70:71], off
	s_add_u32 m0, s32, 0x2000
	v_mfma_f32_32x32x16_bf16 v[34:49], v[166:169], v[182:185], v[34:49]
	global_load_lds_dwordx4 v[74:75], off
	s_add_u32 m0, s32, 0x3000
	v_mfma_f32_32x32x16_bf16 v[2:17], v[166:169], v[186:189], v[2:17]
	global_load_lds_dwordx4 v[78:79], off
	s_add_u32 m0, s32, 0x8000
	v_mfma_f32_32x32x16_bf16 v[50:65], v[190:193], v[198:201], v[50:65]
	global_load_lds_dwordx4 v[68:69], off
	s_add_u32 m0, s32, 0x9000
	v_mfma_f32_32x32x16_bf16 v[18:33], v[190:193], v[202:205], v[18:33]
	global_load_lds_dwordx4 v[72:73], off
	s_add_u32 m0, s32, 0xa000
	v_mfma_f32_32x32x16_bf16 v[34:49], v[194:197], v[198:201], v[34:49]
	global_load_lds_dwordx4 v[76:77], off
	s_add_u32 m0, s32, 0xb000
	v_mfma_f32_32x32x16_bf16 v[2:17], v[194:197], v[202:205], v[2:17]
	global_load_lds_dwordx4 v[80:81], off
	ds_read_b128 v[162:165], v91 offset:16384
	ds_read_b128 v[166:169], v92 offset:49152
	ds_read_b128 v[182:185], v91 offset:20480
	ds_read_b128 v[186:189], v92 offset:53248
	ds_read_b128 v[190:193], v93 offset:16384
	ds_read_b128 v[194:197], v90 offset:49152
	ds_read_b128 v[198:201], v93 offset:20480
	ds_read_b128 v[202:205], v90 offset:53248
	s_waitcnt lgkmcnt(6)
	v_mfma_f32_32x32x16_bf16 v[50:65], v[162:165], v[166:169], v[50:65]
	s_waitcnt lgkmcnt(4)
	v_mfma_f32_32x32x16_bf16 v[18:33], v[162:165], v[186:189], v[18:33]
	v_mfma_f32_32x32x16_bf16 v[34:49], v[182:185], v[166:169], v[34:49]
	v_mfma_f32_32x32x16_bf16 v[2:17], v[182:185], v[186:189], v[2:17]
	ds_read_b128 v[162:165], v89 offset:16384
	ds_read_b128 v[166:169], v89 offset:20480
	ds_read_b128 v[182:185], v88 offset:49152
	ds_read_b128 v[186:189], v88 offset:53248
	s_waitcnt lgkmcnt(6)
	v_mfma_f32_32x32x16_bf16 v[50:65], v[190:193], v[194:197], v[50:65]
	s_waitcnt lgkmcnt(4)
	v_mfma_f32_32x32x16_bf16 v[18:33], v[190:193], v[202:205], v[18:33]
	v_mfma_f32_32x32x16_bf16 v[34:49], v[198:201], v[194:197], v[34:49]
	v_mfma_f32_32x32x16_bf16 v[2:17], v[198:201], v[202:205], v[2:17]
	ds_read_b128 v[190:193], v87 offset:16384
	ds_read_b128 v[194:197], v87 offset:20480
	ds_read_b128 v[198:201], v86 offset:49152
	ds_read_b128 v[202:205], v86 offset:53248
	v_lshl_add_u64 v[66:67], v[66:67], 0, s[98:99]
	v_lshl_add_u64 v[70:71], v[70:71], 0, s[98:99]
	v_lshl_add_u64 v[74:75], v[74:75], 0, s[98:99]
	v_lshl_add_u64 v[78:79], v[78:79], 0, s[98:99]
	v_lshl_add_u64 v[68:69], v[68:69], 0, s[98:99]
	v_lshl_add_u64 v[72:73], v[72:73], 0, s[98:99]
	v_lshl_add_u64 v[76:77], v[76:77], 0, s[98:99]
	v_lshl_add_u64 v[80:81], v[80:81], 0, s[98:99]
	s_waitcnt vmcnt(0)
	s_waitcnt lgkmcnt(0)
	s_barrier
	s_add_u32 m0, s32, 0x4000
	v_mfma_f32_32x32x16_bf16 v[50:65], v[162:165], v[182:185], v[50:65]
	global_load_lds_dwordx4 v[66:67], off
	s_add_u32 m0, s32, 0x5000
	v_mfma_f32_32x32x16_bf16 v[18:33], v[162:165], v[186:189], v[18:33]
	global_load_lds_dwordx4 v[70:71], off
	s_add_u32 m0, s32, 0x6000
	v_mfma_f32_32x32x16_bf16 v[34:49], v[166:169], v[182:185], v[34:49]
	global_load_lds_dwordx4 v[74:75], off
	s_add_u32 m0, s32, 0x7000
	v_mfma_f32_32x32x16_bf16 v[2:17], v[166:169], v[186:189], v[2:17]
	global_load_lds_dwordx4 v[78:79], off
	s_add_u32 m0, s32, 0xc000
	v_mfma_f32_32x32x16_bf16 v[50:65], v[190:193], v[198:201], v[50:65]
	global_load_lds_dwordx4 v[68:69], off
	s_add_u32 m0, s32, 0xd000
	v_mfma_f32_32x32x16_bf16 v[18:33], v[190:193], v[202:205], v[18:33]
	global_load_lds_dwordx4 v[72:73], off
	s_add_u32 m0, s32, 0xe000
	v_mfma_f32_32x32x16_bf16 v[34:49], v[194:197], v[198:201], v[34:49]
	global_load_lds_dwordx4 v[76:77], off
	s_add_u32 m0, s32, 0xf000
	v_mfma_f32_32x32x16_bf16 v[2:17], v[194:197], v[202:205], v[2:17]
	global_load_lds_dwordx4 v[80:81], off
	ds_read_b128 v[162:165], v91
	ds_read_b128 v[166:169], v92 offset:32768
	ds_read_b128 v[182:185], v91 offset:4096
	ds_read_b128 v[186:189], v92 offset:36864
	ds_read_b128 v[190:193], v93
	ds_read_b128 v[194:197], v90 offset:32768
	ds_read_b128 v[198:201], v93 offset:4096
	ds_read_b128 v[202:205], v90 offset:36864
	s_waitcnt lgkmcnt(6)
	v_mfma_f32_32x32x16_bf16 v[50:65], v[162:165], v[166:169], v[50:65]
	s_waitcnt lgkmcnt(4)
	v_mfma_f32_32x32x16_bf16 v[18:33], v[162:165], v[186:189], v[18:33]
	v_mfma_f32_32x32x16_bf16 v[34:49], v[182:185], v[166:169], v[34:49]
	v_mfma_f32_32x32x16_bf16 v[2:17], v[182:185], v[186:189], v[2:17]
	ds_read_b128 v[162:165], v89
	ds_read_b128 v[166:169], v89 offset:4096
	ds_read_b128 v[182:185], v88 offset:32768
	ds_read_b128 v[186:189], v88 offset:36864
	s_waitcnt lgkmcnt(6)
	v_mfma_f32_32x32x16_bf16 v[50:65], v[190:193], v[194:197], v[50:65]
	s_waitcnt lgkmcnt(4)
	v_mfma_f32_32x32x16_bf16 v[18:33], v[190:193], v[202:205], v[18:33]
	v_mfma_f32_32x32x16_bf16 v[34:49], v[198:201], v[194:197], v[34:49]
	v_mfma_f32_32x32x16_bf16 v[2:17], v[198:201], v[202:205], v[2:17]
	ds_read_b128 v[190:193], v87
	ds_read_b128 v[194:197], v87 offset:4096
	ds_read_b128 v[198:201], v86 offset:32768
	ds_read_b128 v[202:205], v86 offset:36864
	v_lshl_add_u64 v[66:67], v[66:67], 0, s[98:99]
	v_lshl_add_u64 v[70:71], v[70:71], 0, s[98:99]
	v_lshl_add_u64 v[74:75], v[74:75], 0, s[98:99]
	v_lshl_add_u64 v[78:79], v[78:79], 0, s[98:99]
	v_lshl_add_u64 v[68:69], v[68:69], 0, s[98:99]
	v_lshl_add_u64 v[72:73], v[72:73], 0, s[98:99]
	v_lshl_add_u64 v[76:77], v[76:77], 0, s[98:99]
	v_lshl_add_u64 v[80:81], v[80:81], 0, s[98:99]
	s_waitcnt vmcnt(0)
	s_waitcnt lgkmcnt(0)
	s_barrier
	s_add_u32 m0, s32, 0x0
	v_mfma_f32_32x32x16_bf16 v[50:65], v[162:165], v[182:185], v[50:65]
	global_load_lds_dwordx4 v[66:67], off
	s_add_u32 m0, s32, 0x1000
	v_mfma_f32_32x32x16_bf16 v[18:33], v[162:165], v[186:189], v[18:33]
	global_load_lds_dwordx4 v[70:71], off
	s_add_u32 m0, s32, 0x2000
	v_mfma_f32_32x32x16_bf16 v[34:49], v[166:169], v[182:185], v[34:49]
	global_load_lds_dwordx4 v[74:75], off
	s_add_u32 m0, s32, 0x3000
	v_mfma_f32_32x32x16_bf16 v[2:17], v[166:169], v[186:189], v[2:17]
	global_load_lds_dwordx4 v[78:79], off
	s_add_u32 m0, s32, 0x8000
	v_mfma_f32_32x32x16_bf16 v[50:65], v[190:193], v[198:201], v[50:65]
	global_load_lds_dwordx4 v[68:69], off
	s_add_u32 m0, s32, 0x9000
	v_mfma_f32_32x32x16_bf16 v[18:33], v[190:193], v[202:205], v[18:33]
	global_load_lds_dwordx4 v[72:73], off
	s_add_u32 m0, s32, 0xa000
	v_mfma_f32_32x32x16_bf16 v[34:49], v[194:197], v[198:201], v[34:49]
	global_load_lds_dwordx4 v[76:77], off
	s_add_u32 m0, s32, 0xb000
	v_mfma_f32_32x32x16_bf16 v[2:17], v[194:197], v[202:205], v[2:17]
	global_load_lds_dwordx4 v[80:81], off
	ds_read_b128 v[162:165], v91 offset:16384
	ds_read_b128 v[166:169], v92 offset:49152
	ds_read_b128 v[182:185], v91 offset:20480
	ds_read_b128 v[186:189], v92 offset:53248
	ds_read_b128 v[190:193], v93 offset:16384
	ds_read_b128 v[194:197], v90 offset:49152
	ds_read_b128 v[198:201], v93 offset:20480
	ds_read_b128 v[202:205], v90 offset:53248
	s_waitcnt lgkmcnt(6)
	v_mfma_f32_32x32x16_bf16 v[50:65], v[162:165], v[166:169], v[50:65]
	s_waitcnt lgkmcnt(4)
	v_mfma_f32_32x32x16_bf16 v[18:33], v[162:165], v[186:189], v[18:33]
	v_mfma_f32_32x32x16_bf16 v[34:49], v[182:185], v[166:169], v[34:49]
	v_mfma_f32_32x32x16_bf16 v[2:17], v[182:185], v[186:189], v[2:17]
	ds_read_b128 v[162:165], v89 offset:16384
	ds_read_b128 v[166:169], v89 offset:20480
	ds_read_b128 v[182:185], v88 offset:49152
	ds_read_b128 v[186:189], v88 offset:53248
	s_waitcnt lgkmcnt(6)
	v_mfma_f32_32x32x16_bf16 v[50:65], v[190:193], v[194:197], v[50:65]
	s_waitcnt lgkmcnt(4)
	v_mfma_f32_32x32x16_bf16 v[18:33], v[190:193], v[202:205], v[18:33]
	v_mfma_f32_32x32x16_bf16 v[34:49], v[198:201], v[194:197], v[34:49]
	v_mfma_f32_32x32x16_bf16 v[2:17], v[198:201], v[202:205], v[2:17]
	ds_read_b128 v[190:193], v87 offset:16384
	ds_read_b128 v[194:197], v87 offset:20480
	ds_read_b128 v[198:201], v86 offset:49152
	ds_read_b128 v[202:205], v86 offset:53248
	v_lshl_add_u64 v[66:67], v[66:67], 0, s[98:99]
	v_lshl_add_u64 v[70:71], v[70:71], 0, s[98:99]
	v_lshl_add_u64 v[74:75], v[74:75], 0, s[98:99]
	v_lshl_add_u64 v[78:79], v[78:79], 0, s[98:99]
	v_lshl_add_u64 v[68:69], v[68:69], 0, s[98:99]
	v_lshl_add_u64 v[72:73], v[72:73], 0, s[98:99]
	v_lshl_add_u64 v[76:77], v[76:77], 0, s[98:99]
	v_lshl_add_u64 v[80:81], v[80:81], 0, s[98:99]
	s_waitcnt vmcnt(0)
	s_waitcnt lgkmcnt(0)
	s_barrier
	s_add_u32 m0, s32, 0x4000
	v_mfma_f32_32x32x16_bf16 v[50:65], v[162:165], v[182:185], v[50:65]
	global_load_lds_dwordx4 v[66:67], off
	s_add_u32 m0, s32, 0x5000
	v_mfma_f32_32x32x16_bf16 v[18:33], v[162:165], v[186:189], v[18:33]
	global_load_lds_dwordx4 v[70:71], off
	s_add_u32 m0, s32, 0x6000
	v_mfma_f32_32x32x16_bf16 v[34:49], v[166:169], v[182:185], v[34:49]
	global_load_lds_dwordx4 v[74:75], off
	s_add_u32 m0, s32, 0x7000
	v_mfma_f32_32x32x16_bf16 v[2:17], v[166:169], v[186:189], v[2:17]
	global_load_lds_dwordx4 v[78:79], off
	s_add_u32 m0, s32, 0xc000
	v_mfma_f32_32x32x16_bf16 v[50:65], v[190:193], v[198:201], v[50:65]
	global_load_lds_dwordx4 v[68:69], off
	s_add_u32 m0, s32, 0xd000
	v_mfma_f32_32x32x16_bf16 v[18:33], v[190:193], v[202:205], v[18:33]
	global_load_lds_dwordx4 v[72:73], off
	s_add_u32 m0, s32, 0xe000
	v_mfma_f32_32x32x16_bf16 v[34:49], v[194:197], v[198:201], v[34:49]
	global_load_lds_dwordx4 v[76:77], off
	s_add_u32 m0, s32, 0xf000
	v_mfma_f32_32x32x16_bf16 v[2:17], v[194:197], v[202:205], v[2:17]
	global_load_lds_dwordx4 v[80:81], off
	ds_read_b128 v[162:165], v91
	ds_read_b128 v[166:169], v92 offset:32768
	ds_read_b128 v[182:185], v91 offset:4096
	ds_read_b128 v[186:189], v92 offset:36864
	ds_read_b128 v[190:193], v93
	ds_read_b128 v[194:197], v90 offset:32768
	ds_read_b128 v[198:201], v93 offset:4096
	ds_read_b128 v[202:205], v90 offset:36864
	s_waitcnt lgkmcnt(6)
	v_mfma_f32_32x32x16_bf16 v[50:65], v[162:165], v[166:169], v[50:65]
	s_waitcnt lgkmcnt(4)
	v_mfma_f32_32x32x16_bf16 v[18:33], v[162:165], v[186:189], v[18:33]
	v_mfma_f32_32x32x16_bf16 v[34:49], v[182:185], v[166:169], v[34:49]
	v_mfma_f32_32x32x16_bf16 v[2:17], v[182:185], v[186:189], v[2:17]
	ds_read_b128 v[162:165], v89
	ds_read_b128 v[166:169], v89 offset:4096
	ds_read_b128 v[182:185], v88 offset:32768
	ds_read_b128 v[186:189], v88 offset:36864
	s_waitcnt lgkmcnt(6)
	v_mfma_f32_32x32x16_bf16 v[50:65], v[190:193], v[194:197], v[50:65]
	s_waitcnt lgkmcnt(4)
	v_mfma_f32_32x32x16_bf16 v[18:33], v[190:193], v[202:205], v[18:33]
	v_mfma_f32_32x32x16_bf16 v[34:49], v[198:201], v[194:197], v[34:49]
	v_mfma_f32_32x32x16_bf16 v[2:17], v[198:201], v[202:205], v[2:17]
	ds_read_b128 v[190:193], v87
	ds_read_b128 v[194:197], v87 offset:4096
	ds_read_b128 v[198:201], v86 offset:32768
	ds_read_b128 v[202:205], v86 offset:36864
	v_lshl_add_u64 v[66:67], v[66:67], 0, s[98:99]
	v_lshl_add_u64 v[70:71], v[70:71], 0, s[98:99]
	v_lshl_add_u64 v[74:75], v[74:75], 0, s[98:99]
	v_lshl_add_u64 v[78:79], v[78:79], 0, s[98:99]
	v_lshl_add_u64 v[68:69], v[68:69], 0, s[98:99]
	v_lshl_add_u64 v[72:73], v[72:73], 0, s[98:99]
	v_lshl_add_u64 v[76:77], v[76:77], 0, s[98:99]
	v_lshl_add_u64 v[80:81], v[80:81], 0, s[98:99]
	s_waitcnt vmcnt(0)
	s_waitcnt lgkmcnt(0)
	s_barrier
	s_add_u32 m0, s32, 0x0
	v_mfma_f32_32x32x16_bf16 v[50:65], v[162:165], v[182:185], v[50:65]
	global_load_lds_dwordx4 v[66:67], off
	s_add_u32 m0, s32, 0x1000
	v_mfma_f32_32x32x16_bf16 v[18:33], v[162:165], v[186:189], v[18:33]
	global_load_lds_dwordx4 v[70:71], off
	s_add_u32 m0, s32, 0x2000
	v_mfma_f32_32x32x16_bf16 v[34:49], v[166:169], v[182:185], v[34:49]
	global_load_lds_dwordx4 v[74:75], off
	s_add_u32 m0, s32, 0x3000
	v_mfma_f32_32x32x16_bf16 v[2:17], v[166:169], v[186:189], v[2:17]
	global_load_lds_dwordx4 v[78:79], off
	s_add_u32 m0, s32, 0x8000
	v_mfma_f32_32x32x16_bf16 v[50:65], v[190:193], v[198:201], v[50:65]
	global_load_lds_dwordx4 v[68:69], off
	s_add_u32 m0, s32, 0x9000
	v_mfma_f32_32x32x16_bf16 v[18:33], v[190:193], v[202:205], v[18:33]
	global_load_lds_dwordx4 v[72:73], off
	s_add_u32 m0, s32, 0xa000
	v_mfma_f32_32x32x16_bf16 v[34:49], v[194:197], v[198:201], v[34:49]
	global_load_lds_dwordx4 v[76:77], off
	s_add_u32 m0, s32, 0xb000
	v_mfma_f32_32x32x16_bf16 v[2:17], v[194:197], v[202:205], v[2:17]
	global_load_lds_dwordx4 v[80:81], off
	ds_read_b128 v[162:165], v91 offset:16384
	ds_read_b128 v[166:169], v92 offset:49152
	ds_read_b128 v[182:185], v91 offset:20480
	ds_read_b128 v[186:189], v92 offset:53248
	ds_read_b128 v[190:193], v93 offset:16384
	ds_read_b128 v[194:197], v90 offset:49152
	ds_read_b128 v[198:201], v93 offset:20480
	ds_read_b128 v[202:205], v90 offset:53248
	s_waitcnt lgkmcnt(6)
	v_mfma_f32_32x32x16_bf16 v[50:65], v[162:165], v[166:169], v[50:65]
	s_waitcnt lgkmcnt(4)
	v_mfma_f32_32x32x16_bf16 v[18:33], v[162:165], v[186:189], v[18:33]
	v_mfma_f32_32x32x16_bf16 v[34:49], v[182:185], v[166:169], v[34:49]
	v_mfma_f32_32x32x16_bf16 v[2:17], v[182:185], v[186:189], v[2:17]
	ds_read_b128 v[162:165], v89 offset:16384
	ds_read_b128 v[166:169], v89 offset:20480
	ds_read_b128 v[182:185], v88 offset:49152
	ds_read_b128 v[186:189], v88 offset:53248
	s_waitcnt lgkmcnt(6)
	v_mfma_f32_32x32x16_bf16 v[50:65], v[190:193], v[194:197], v[50:65]
	s_waitcnt lgkmcnt(4)
	v_mfma_f32_32x32x16_bf16 v[18:33], v[190:193], v[202:205], v[18:33]
	v_mfma_f32_32x32x16_bf16 v[34:49], v[198:201], v[194:197], v[34:49]
	v_mfma_f32_32x32x16_bf16 v[2:17], v[198:201], v[202:205], v[2:17]
	ds_read_b128 v[190:193], v87 offset:16384
	ds_read_b128 v[194:197], v87 offset:20480
	ds_read_b128 v[198:201], v86 offset:49152
	ds_read_b128 v[202:205], v86 offset:53248
	v_lshl_add_u64 v[66:67], v[66:67], 0, s[98:99]
	v_lshl_add_u64 v[70:71], v[70:71], 0, s[98:99]
	v_lshl_add_u64 v[74:75], v[74:75], 0, s[98:99]
	v_lshl_add_u64 v[78:79], v[78:79], 0, s[98:99]
	v_lshl_add_u64 v[68:69], v[68:69], 0, s[98:99]
	v_lshl_add_u64 v[72:73], v[72:73], 0, s[98:99]
	v_lshl_add_u64 v[76:77], v[76:77], 0, s[98:99]
	v_lshl_add_u64 v[80:81], v[80:81], 0, s[98:99]
	s_waitcnt vmcnt(0)
	s_waitcnt lgkmcnt(0)
	s_barrier
	s_add_u32 m0, s32, 0x4000
	v_mfma_f32_32x32x16_bf16 v[50:65], v[162:165], v[182:185], v[50:65]
	global_load_lds_dwordx4 v[66:67], off
	s_add_u32 m0, s32, 0x5000
	v_mfma_f32_32x32x16_bf16 v[18:33], v[162:165], v[186:189], v[18:33]
	global_load_lds_dwordx4 v[70:71], off
	s_add_u32 m0, s32, 0x6000
	v_mfma_f32_32x32x16_bf16 v[34:49], v[166:169], v[182:185], v[34:49]
	global_load_lds_dwordx4 v[74:75], off
	s_add_u32 m0, s32, 0x7000
	v_mfma_f32_32x32x16_bf16 v[2:17], v[166:169], v[186:189], v[2:17]
	global_load_lds_dwordx4 v[78:79], off
	s_add_u32 m0, s32, 0xc000
	v_mfma_f32_32x32x16_bf16 v[50:65], v[190:193], v[198:201], v[50:65]
	global_load_lds_dwordx4 v[68:69], off
	s_add_u32 m0, s32, 0xd000
	v_mfma_f32_32x32x16_bf16 v[18:33], v[190:193], v[202:205], v[18:33]
	global_load_lds_dwordx4 v[72:73], off
	s_add_u32 m0, s32, 0xe000
	v_mfma_f32_32x32x16_bf16 v[34:49], v[194:197], v[198:201], v[34:49]
	global_load_lds_dwordx4 v[76:77], off
	s_add_u32 m0, s32, 0xf000
	v_mfma_f32_32x32x16_bf16 v[2:17], v[194:197], v[202:205], v[2:17]
	global_load_lds_dwordx4 v[80:81], off
	ds_read_b128 v[162:165], v91
	ds_read_b128 v[166:169], v92 offset:32768
	ds_read_b128 v[182:185], v91 offset:4096
	ds_read_b128 v[186:189], v92 offset:36864
	ds_read_b128 v[190:193], v93
	ds_read_b128 v[194:197], v90 offset:32768
	ds_read_b128 v[198:201], v93 offset:4096
	ds_read_b128 v[202:205], v90 offset:36864
	s_waitcnt lgkmcnt(6)
	v_mfma_f32_32x32x16_bf16 v[50:65], v[162:165], v[166:169], v[50:65]
	s_waitcnt lgkmcnt(4)
	v_mfma_f32_32x32x16_bf16 v[18:33], v[162:165], v[186:189], v[18:33]
	v_mfma_f32_32x32x16_bf16 v[34:49], v[182:185], v[166:169], v[34:49]
	v_mfma_f32_32x32x16_bf16 v[2:17], v[182:185], v[186:189], v[2:17]
	ds_read_b128 v[162:165], v89
	ds_read_b128 v[166:169], v89 offset:4096
	ds_read_b128 v[182:185], v88 offset:32768
	ds_read_b128 v[186:189], v88 offset:36864
	s_waitcnt lgkmcnt(6)
	v_mfma_f32_32x32x16_bf16 v[50:65], v[190:193], v[194:197], v[50:65]
	s_waitcnt lgkmcnt(4)
	v_mfma_f32_32x32x16_bf16 v[18:33], v[190:193], v[202:205], v[18:33]
	v_mfma_f32_32x32x16_bf16 v[34:49], v[198:201], v[194:197], v[34:49]
	v_mfma_f32_32x32x16_bf16 v[2:17], v[198:201], v[202:205], v[2:17]
	ds_read_b128 v[190:193], v87
	ds_read_b128 v[194:197], v87 offset:4096
	ds_read_b128 v[198:201], v86 offset:32768
	ds_read_b128 v[202:205], v86 offset:36864
	v_lshl_add_u64 v[66:67], v[66:67], 0, s[98:99]
	v_lshl_add_u64 v[70:71], v[70:71], 0, s[98:99]
	v_lshl_add_u64 v[74:75], v[74:75], 0, s[98:99]
	v_lshl_add_u64 v[78:79], v[78:79], 0, s[98:99]
	v_lshl_add_u64 v[68:69], v[68:69], 0, s[98:99]
	v_lshl_add_u64 v[72:73], v[72:73], 0, s[98:99]
	v_lshl_add_u64 v[76:77], v[76:77], 0, s[98:99]
	v_lshl_add_u64 v[80:81], v[80:81], 0, s[98:99]
	s_waitcnt vmcnt(0)
	s_waitcnt lgkmcnt(0)
	s_barrier
	s_add_u32 m0, s32, 0x0
	v_mfma_f32_32x32x16_bf16 v[50:65], v[162:165], v[182:185], v[50:65]
	global_load_lds_dwordx4 v[66:67], off
	s_add_u32 m0, s32, 0x1000
	v_mfma_f32_32x32x16_bf16 v[18:33], v[162:165], v[186:189], v[18:33]
	global_load_lds_dwordx4 v[70:71], off
	s_add_u32 m0, s32, 0x2000
	v_mfma_f32_32x32x16_bf16 v[34:49], v[166:169], v[182:185], v[34:49]
	global_load_lds_dwordx4 v[74:75], off
	s_add_u32 m0, s32, 0x3000
	v_mfma_f32_32x32x16_bf16 v[2:17], v[166:169], v[186:189], v[2:17]
	global_load_lds_dwordx4 v[78:79], off
	s_add_u32 m0, s32, 0x8000
	v_mfma_f32_32x32x16_bf16 v[50:65], v[190:193], v[198:201], v[50:65]
	global_load_lds_dwordx4 v[68:69], off
	s_add_u32 m0, s32, 0x9000
	v_mfma_f32_32x32x16_bf16 v[18:33], v[190:193], v[202:205], v[18:33]
	global_load_lds_dwordx4 v[72:73], off
	s_add_u32 m0, s32, 0xa000
	v_mfma_f32_32x32x16_bf16 v[34:49], v[194:197], v[198:201], v[34:49]
	global_load_lds_dwordx4 v[76:77], off
	s_add_u32 m0, s32, 0xb000
	v_mfma_f32_32x32x16_bf16 v[2:17], v[194:197], v[202:205], v[2:17]
	global_load_lds_dwordx4 v[80:81], off
	ds_read_b128 v[162:165], v91 offset:16384
	ds_read_b128 v[166:169], v92 offset:49152
	ds_read_b128 v[182:185], v91 offset:20480
	ds_read_b128 v[186:189], v92 offset:53248
	ds_read_b128 v[190:193], v93 offset:16384
	ds_read_b128 v[194:197], v90 offset:49152
	ds_read_b128 v[198:201], v93 offset:20480
	ds_read_b128 v[202:205], v90 offset:53248
	s_waitcnt lgkmcnt(6)
	v_mfma_f32_32x32x16_bf16 v[50:65], v[162:165], v[166:169], v[50:65]
	s_waitcnt lgkmcnt(4)
	v_mfma_f32_32x32x16_bf16 v[18:33], v[162:165], v[186:189], v[18:33]
	v_mfma_f32_32x32x16_bf16 v[34:49], v[182:185], v[166:169], v[34:49]
	v_mfma_f32_32x32x16_bf16 v[2:17], v[182:185], v[186:189], v[2:17]
	ds_read_b128 v[162:165], v89 offset:16384
	ds_read_b128 v[166:169], v89 offset:20480
	ds_read_b128 v[182:185], v88 offset:49152
	ds_read_b128 v[186:189], v88 offset:53248
	s_waitcnt lgkmcnt(6)
	v_mfma_f32_32x32x16_bf16 v[50:65], v[190:193], v[194:197], v[50:65]
	s_waitcnt lgkmcnt(4)
	v_mfma_f32_32x32x16_bf16 v[18:33], v[190:193], v[202:205], v[18:33]
	v_mfma_f32_32x32x16_bf16 v[34:49], v[198:201], v[194:197], v[34:49]
	v_mfma_f32_32x32x16_bf16 v[2:17], v[198:201], v[202:205], v[2:17]
	ds_read_b128 v[190:193], v87 offset:16384
	ds_read_b128 v[194:197], v87 offset:20480
	ds_read_b128 v[198:201], v86 offset:49152
	ds_read_b128 v[202:205], v86 offset:53248
	v_lshl_add_u64 v[66:67], v[66:67], 0, s[98:99]
	v_lshl_add_u64 v[70:71], v[70:71], 0, s[98:99]
	v_lshl_add_u64 v[74:75], v[74:75], 0, s[98:99]
	v_lshl_add_u64 v[78:79], v[78:79], 0, s[98:99]
	v_lshl_add_u64 v[68:69], v[68:69], 0, s[98:99]
	v_lshl_add_u64 v[72:73], v[72:73], 0, s[98:99]
	v_lshl_add_u64 v[76:77], v[76:77], 0, s[98:99]
	v_lshl_add_u64 v[80:81], v[80:81], 0, s[98:99]
	s_waitcnt vmcnt(0)
	s_waitcnt lgkmcnt(0)
	s_barrier
	s_add_u32 m0, s32, 0x4000
	v_mfma_f32_32x32x16_bf16 v[50:65], v[162:165], v[182:185], v[50:65]
	global_load_lds_dwordx4 v[66:67], off
	s_add_u32 m0, s32, 0x5000
	v_mfma_f32_32x32x16_bf16 v[18:33], v[162:165], v[186:189], v[18:33]
	global_load_lds_dwordx4 v[70:71], off
	s_add_u32 m0, s32, 0x6000
	v_mfma_f32_32x32x16_bf16 v[34:49], v[166:169], v[182:185], v[34:49]
	global_load_lds_dwordx4 v[74:75], off
	s_add_u32 m0, s32, 0x7000
	v_mfma_f32_32x32x16_bf16 v[2:17], v[166:169], v[186:189], v[2:17]
	global_load_lds_dwordx4 v[78:79], off
	s_add_u32 m0, s32, 0xc000
	v_mfma_f32_32x32x16_bf16 v[50:65], v[190:193], v[198:201], v[50:65]
	global_load_lds_dwordx4 v[68:69], off
	s_add_u32 m0, s32, 0xd000
	v_mfma_f32_32x32x16_bf16 v[18:33], v[190:193], v[202:205], v[18:33]
	global_load_lds_dwordx4 v[72:73], off
	s_add_u32 m0, s32, 0xe000
	v_mfma_f32_32x32x16_bf16 v[34:49], v[194:197], v[198:201], v[34:49]
	global_load_lds_dwordx4 v[76:77], off
	s_add_u32 m0, s32, 0xf000
	v_mfma_f32_32x32x16_bf16 v[2:17], v[194:197], v[202:205], v[2:17]
	global_load_lds_dwordx4 v[80:81], off
	ds_read_b128 v[162:165], v91
	ds_read_b128 v[166:169], v92 offset:32768
	ds_read_b128 v[182:185], v91 offset:4096
	ds_read_b128 v[186:189], v92 offset:36864
	ds_read_b128 v[190:193], v93
	ds_read_b128 v[194:197], v90 offset:32768
	ds_read_b128 v[198:201], v93 offset:4096
	ds_read_b128 v[202:205], v90 offset:36864
	s_waitcnt lgkmcnt(6)
	v_mfma_f32_32x32x16_bf16 v[50:65], v[162:165], v[166:169], v[50:65]
	s_waitcnt lgkmcnt(4)
	v_mfma_f32_32x32x16_bf16 v[18:33], v[162:165], v[186:189], v[18:33]
	v_mfma_f32_32x32x16_bf16 v[34:49], v[182:185], v[166:169], v[34:49]
	v_mfma_f32_32x32x16_bf16 v[2:17], v[182:185], v[186:189], v[2:17]
	ds_read_b128 v[162:165], v89
	ds_read_b128 v[166:169], v89 offset:4096
	ds_read_b128 v[182:185], v88 offset:32768
	ds_read_b128 v[186:189], v88 offset:36864
	s_waitcnt lgkmcnt(6)
	v_mfma_f32_32x32x16_bf16 v[50:65], v[190:193], v[194:197], v[50:65]
	s_waitcnt lgkmcnt(4)
	v_mfma_f32_32x32x16_bf16 v[18:33], v[190:193], v[202:205], v[18:33]
	v_mfma_f32_32x32x16_bf16 v[34:49], v[198:201], v[194:197], v[34:49]
	v_mfma_f32_32x32x16_bf16 v[2:17], v[198:201], v[202:205], v[2:17]
	ds_read_b128 v[190:193], v87
	ds_read_b128 v[194:197], v87 offset:4096
	ds_read_b128 v[198:201], v86 offset:32768
	ds_read_b128 v[202:205], v86 offset:36864
	v_lshl_add_u64 v[66:67], v[66:67], 0, s[98:99]
	v_lshl_add_u64 v[70:71], v[70:71], 0, s[98:99]
	v_lshl_add_u64 v[74:75], v[74:75], 0, s[98:99]
	v_lshl_add_u64 v[78:79], v[78:79], 0, s[98:99]
	v_lshl_add_u64 v[68:69], v[68:69], 0, s[98:99]
	v_lshl_add_u64 v[72:73], v[72:73], 0, s[98:99]
	v_lshl_add_u64 v[76:77], v[76:77], 0, s[98:99]
	v_lshl_add_u64 v[80:81], v[80:81], 0, s[98:99]
	s_waitcnt vmcnt(0)
	s_waitcnt lgkmcnt(0)
	s_barrier
	s_add_u32 m0, s32, 0x0
	v_mfma_f32_32x32x16_bf16 v[50:65], v[162:165], v[182:185], v[50:65]
	global_load_lds_dwordx4 v[66:67], off
	s_add_u32 m0, s32, 0x1000
	v_mfma_f32_32x32x16_bf16 v[18:33], v[162:165], v[186:189], v[18:33]
	global_load_lds_dwordx4 v[70:71], off
	s_add_u32 m0, s32, 0x2000
	v_mfma_f32_32x32x16_bf16 v[34:49], v[166:169], v[182:185], v[34:49]
	global_load_lds_dwordx4 v[74:75], off
	s_add_u32 m0, s32, 0x3000
	v_mfma_f32_32x32x16_bf16 v[2:17], v[166:169], v[186:189], v[2:17]
	global_load_lds_dwordx4 v[78:79], off
	s_add_u32 m0, s32, 0x8000
	v_mfma_f32_32x32x16_bf16 v[50:65], v[190:193], v[198:201], v[50:65]
	global_load_lds_dwordx4 v[68:69], off
	s_add_u32 m0, s32, 0x9000
	v_mfma_f32_32x32x16_bf16 v[18:33], v[190:193], v[202:205], v[18:33]
	global_load_lds_dwordx4 v[72:73], off
	s_add_u32 m0, s32, 0xa000
	v_mfma_f32_32x32x16_bf16 v[34:49], v[194:197], v[198:201], v[34:49]
	global_load_lds_dwordx4 v[76:77], off
	s_add_u32 m0, s32, 0xb000
	v_mfma_f32_32x32x16_bf16 v[2:17], v[194:197], v[202:205], v[2:17]
	global_load_lds_dwordx4 v[80:81], off
	ds_read_b128 v[162:165], v91 offset:16384
	ds_read_b128 v[166:169], v92 offset:49152
	ds_read_b128 v[182:185], v91 offset:20480
	ds_read_b128 v[186:189], v92 offset:53248
	ds_read_b128 v[190:193], v93 offset:16384
	ds_read_b128 v[194:197], v90 offset:49152
	ds_read_b128 v[198:201], v93 offset:20480
	ds_read_b128 v[202:205], v90 offset:53248
	s_waitcnt lgkmcnt(6)
	v_mfma_f32_32x32x16_bf16 v[50:65], v[162:165], v[166:169], v[50:65]
	s_waitcnt lgkmcnt(4)
	v_mfma_f32_32x32x16_bf16 v[18:33], v[162:165], v[186:189], v[18:33]
	v_mfma_f32_32x32x16_bf16 v[34:49], v[182:185], v[166:169], v[34:49]
	v_mfma_f32_32x32x16_bf16 v[2:17], v[182:185], v[186:189], v[2:17]
	ds_read_b128 v[162:165], v89 offset:16384
	ds_read_b128 v[166:169], v89 offset:20480
	ds_read_b128 v[182:185], v88 offset:49152
	ds_read_b128 v[186:189], v88 offset:53248
	s_waitcnt lgkmcnt(6)
	v_mfma_f32_32x32x16_bf16 v[50:65], v[190:193], v[194:197], v[50:65]
	s_waitcnt lgkmcnt(4)
	v_mfma_f32_32x32x16_bf16 v[18:33], v[190:193], v[202:205], v[18:33]
	v_mfma_f32_32x32x16_bf16 v[34:49], v[198:201], v[194:197], v[34:49]
	v_mfma_f32_32x32x16_bf16 v[2:17], v[198:201], v[202:205], v[2:17]
	ds_read_b128 v[190:193], v87 offset:16384
	ds_read_b128 v[194:197], v87 offset:20480
	ds_read_b128 v[198:201], v86 offset:49152
	ds_read_b128 v[202:205], v86 offset:53248
	v_lshl_add_u64 v[66:67], v[66:67], 0, s[98:99]
	v_lshl_add_u64 v[70:71], v[70:71], 0, s[98:99]
	v_lshl_add_u64 v[74:75], v[74:75], 0, s[98:99]
	v_lshl_add_u64 v[78:79], v[78:79], 0, s[98:99]
	v_lshl_add_u64 v[68:69], v[68:69], 0, s[98:99]
	v_lshl_add_u64 v[72:73], v[72:73], 0, s[98:99]
	v_lshl_add_u64 v[76:77], v[76:77], 0, s[98:99]
	v_lshl_add_u64 v[80:81], v[80:81], 0, s[98:99]
	s_waitcnt vmcnt(0)
	s_waitcnt lgkmcnt(0)
	s_barrier
	s_add_u32 m0, s32, 0x4000
	v_mfma_f32_32x32x16_bf16 v[50:65], v[162:165], v[182:185], v[50:65]
	global_load_lds_dwordx4 v[66:67], off
	s_add_u32 m0, s32, 0x5000
	v_mfma_f32_32x32x16_bf16 v[18:33], v[162:165], v[186:189], v[18:33]
	global_load_lds_dwordx4 v[70:71], off
	s_add_u32 m0, s32, 0x6000
	v_mfma_f32_32x32x16_bf16 v[34:49], v[166:169], v[182:185], v[34:49]
	global_load_lds_dwordx4 v[74:75], off
	s_add_u32 m0, s32, 0x7000
	v_mfma_f32_32x32x16_bf16 v[2:17], v[166:169], v[186:189], v[2:17]
	global_load_lds_dwordx4 v[78:79], off
	s_add_u32 m0, s32, 0xc000
	v_mfma_f32_32x32x16_bf16 v[50:65], v[190:193], v[198:201], v[50:65]
	global_load_lds_dwordx4 v[68:69], off
	s_add_u32 m0, s32, 0xd000
	v_mfma_f32_32x32x16_bf16 v[18:33], v[190:193], v[202:205], v[18:33]
	global_load_lds_dwordx4 v[72:73], off
	s_add_u32 m0, s32, 0xe000
	v_mfma_f32_32x32x16_bf16 v[34:49], v[194:197], v[198:201], v[34:49]
	global_load_lds_dwordx4 v[76:77], off
	s_add_u32 m0, s32, 0xf000
	v_mfma_f32_32x32x16_bf16 v[2:17], v[194:197], v[202:205], v[2:17]
	global_load_lds_dwordx4 v[80:81], off
	ds_read_b128 v[162:165], v91
	ds_read_b128 v[166:169], v92 offset:32768
	ds_read_b128 v[182:185], v91 offset:4096
	ds_read_b128 v[186:189], v92 offset:36864
	ds_read_b128 v[190:193], v93
	ds_read_b128 v[194:197], v90 offset:32768
	ds_read_b128 v[198:201], v93 offset:4096
	ds_read_b128 v[202:205], v90 offset:36864
	s_waitcnt lgkmcnt(6)
	v_mfma_f32_32x32x16_bf16 v[50:65], v[162:165], v[166:169], v[50:65]
	s_waitcnt lgkmcnt(4)
	v_mfma_f32_32x32x16_bf16 v[18:33], v[162:165], v[186:189], v[18:33]
	v_mfma_f32_32x32x16_bf16 v[34:49], v[182:185], v[166:169], v[34:49]
	v_mfma_f32_32x32x16_bf16 v[2:17], v[182:185], v[186:189], v[2:17]
	ds_read_b128 v[162:165], v89
	ds_read_b128 v[166:169], v89 offset:4096
	ds_read_b128 v[182:185], v88 offset:32768
	ds_read_b128 v[186:189], v88 offset:36864
	s_waitcnt lgkmcnt(6)
	v_mfma_f32_32x32x16_bf16 v[50:65], v[190:193], v[194:197], v[50:65]
	s_waitcnt lgkmcnt(4)
	v_mfma_f32_32x32x16_bf16 v[18:33], v[190:193], v[202:205], v[18:33]
	v_mfma_f32_32x32x16_bf16 v[34:49], v[198:201], v[194:197], v[34:49]
	v_mfma_f32_32x32x16_bf16 v[2:17], v[198:201], v[202:205], v[2:17]
	ds_read_b128 v[190:193], v87
	ds_read_b128 v[194:197], v87 offset:4096
	ds_read_b128 v[198:201], v86 offset:32768
	ds_read_b128 v[202:205], v86 offset:36864
	v_lshl_add_u64 v[66:67], v[66:67], 0, s[98:99]
	v_lshl_add_u64 v[70:71], v[70:71], 0, s[98:99]
	v_lshl_add_u64 v[74:75], v[74:75], 0, s[98:99]
	v_lshl_add_u64 v[78:79], v[78:79], 0, s[98:99]
	v_lshl_add_u64 v[68:69], v[68:69], 0, s[98:99]
	v_lshl_add_u64 v[72:73], v[72:73], 0, s[98:99]
	v_lshl_add_u64 v[76:77], v[76:77], 0, s[98:99]
	v_lshl_add_u64 v[80:81], v[80:81], 0, s[98:99]
	s_waitcnt vmcnt(0)
	s_waitcnt lgkmcnt(0)
	s_barrier
	s_add_u32 m0, s32, 0x0
	s_nop 0
	global_load_lds_dwordx4 v[66:67], off
	s_add_u32 m0, s32, 0x1000
	s_nop 0
	global_load_lds_dwordx4 v[70:71], off
	s_add_u32 m0, s32, 0x2000
	s_nop 0
	global_load_lds_dwordx4 v[74:75], off
	s_add_u32 m0, s32, 0x3000
	s_nop 0
	global_load_lds_dwordx4 v[78:79], off
	s_add_u32 m0, s32, 0x8000
	s_nop 0
	global_load_lds_dwordx4 v[68:69], off
	s_add_u32 m0, s32, 0x9000
	s_nop 0
	global_load_lds_dwordx4 v[72:73], off
	s_add_u32 m0, s32, 0xa000
	s_nop 0
	global_load_lds_dwordx4 v[76:77], off
	s_add_u32 m0, s32, 0xb000
	s_nop 0
	global_load_lds_dwordx4 v[80:81], off
	s_nop 0
	s_nop 0
	s_nop 0
	s_nop 0
	s_nop 0
	s_nop 0
	s_nop 0
	v_mfma_f32_32x32x16_bf16 v[50:65], v[162:165], v[182:185], v[50:65]
	v_mfma_f32_32x32x16_bf16 v[18:33], v[162:165], v[186:189], v[18:33]
	v_mfma_f32_32x32x16_bf16 v[34:49], v[166:169], v[182:185], v[34:49]
	v_mfma_f32_32x32x16_bf16 v[2:17], v[166:169], v[186:189], v[2:17]
	ds_read_b128 v[110:113], v91 offset:16384
	ds_read_b128 v[114:117], v91 offset:20480
	ds_read_b128 v[118:121], v92 offset:49152
	ds_read_b128 v[122:125], v92 offset:53248
	ds_read_b128 v[162:165], v93 offset:16384
	ds_read_b128 v[166:169], v93 offset:20480
	ds_read_b128 v[182:185], v90 offset:49152
	ds_read_b128 v[186:189], v90 offset:53248
	v_mfma_f32_32x32x16_bf16 v[50:65], v[190:193], v[198:201], v[50:65]
	v_mfma_f32_32x32x16_bf16 v[18:33], v[190:193], v[202:205], v[18:33]
	v_mfma_f32_32x32x16_bf16 v[34:49], v[194:197], v[198:201], v[34:49]
	v_mfma_f32_32x32x16_bf16 v[2:17], v[194:197], v[202:205], v[2:17]
	s_waitcnt lgkmcnt(5)
	v_mfma_f32_32x32x16_bf16 v[50:65], v[110:113], v[118:121], v[50:65]
	s_waitcnt lgkmcnt(4)
	v_mfma_f32_32x32x16_bf16 v[18:33], v[110:113], v[122:125], v[18:33]
	v_mfma_f32_32x32x16_bf16 v[34:49], v[114:117], v[118:121], v[34:49]
	v_mfma_f32_32x32x16_bf16 v[2:17], v[114:117], v[122:125], v[2:17]
	ds_read_b128 v[110:113], v89 offset:16384
	ds_read_b128 v[114:117], v89 offset:20480
	ds_read_b128 v[118:121], v88 offset:49152
	ds_read_b128 v[122:125], v88 offset:53248
	s_waitcnt lgkmcnt(5)
	v_mfma_f32_32x32x16_bf16 v[50:65], v[162:165], v[182:185], v[50:65]
	s_waitcnt lgkmcnt(4)
	v_mfma_f32_32x32x16_bf16 v[18:33], v[162:165], v[186:189], v[18:33]
	v_mfma_f32_32x32x16_bf16 v[34:49], v[166:169], v[182:185], v[34:49]
	v_mfma_f32_32x32x16_bf16 v[2:17], v[166:169], v[186:189], v[2:17]
	ds_read_b128 v[162:165], v87 offset:16384
	ds_read_b128 v[166:169], v87 offset:20480
	ds_read_b128 v[182:185], v86 offset:49152
	ds_read_b128 v[186:189], v86 offset:53248
	s_waitcnt lgkmcnt(5)
	v_mfma_f32_32x32x16_bf16 v[50:65], v[110:113], v[118:121], v[50:65]
	v_lshl_add_u64 v[66:67], v[66:67], 0, s[98:99]
	v_lshl_add_u64 v[70:71], v[70:71], 0, s[98:99]
	v_lshl_add_u64 v[74:75], v[74:75], 0, s[98:99]
	v_lshl_add_u64 v[78:79], v[78:79], 0, s[98:99]
	v_lshl_add_u64 v[68:69], v[68:69], 0, s[98:99]
	v_lshl_add_u64 v[72:73], v[72:73], 0, s[98:99]
	v_lshl_add_u64 v[76:77], v[76:77], 0, s[98:99]
	v_lshl_add_u64 v[80:81], v[80:81], 0, s[98:99]
	s_waitcnt vmcnt(0)
	s_waitcnt lgkmcnt(0)
	s_barrier
	s_add_u32 m0, s32, 0x4000
	s_nop 0
	global_load_lds_dwordx4 v[66:67], off
	s_add_u32 m0, s32, 0x5000
	s_nop 0
	global_load_lds_dwordx4 v[70:71], off
	s_add_u32 m0, s32, 0x6000
	s_nop 0
	global_load_lds_dwordx4 v[74:75], off
	s_add_u32 m0, s32, 0x7000
	s_nop 0
	global_load_lds_dwordx4 v[78:79], off
	s_add_u32 m0, s32, 0xc000
	s_nop 0
	global_load_lds_dwordx4 v[68:69], off
	s_add_u32 m0, s32, 0xd000
	s_nop 0
	global_load_lds_dwordx4 v[72:73], off
	s_add_u32 m0, s32, 0xe000
	s_nop 0
	global_load_lds_dwordx4 v[76:77], off
	s_add_u32 m0, s32, 0xf000
	s_nop 0
	global_load_lds_dwordx4 v[80:81], off
	v_mfma_f32_32x32x16_bf16 v[18:33], v[110:113], v[122:125], v[18:33]
	v_mfma_f32_32x32x16_bf16 v[34:49], v[114:117], v[118:121], v[34:49]
	v_mfma_f32_32x32x16_bf16 v[2:17], v[114:117], v[122:125], v[2:17]
	ds_read_b128 v[110:113], v91
	ds_read_b128 v[114:117], v91 offset:4096
	ds_read_b128 v[118:121], v92 offset:32768
	ds_read_b128 v[122:125], v92 offset:36864
	ds_read_b128 v[126:129], v93
	ds_read_b128 v[134:137], v93 offset:4096
	ds_read_b128 v[138:141], v90 offset:32768
	ds_read_b128 v[142:145], v90 offset:36864
	v_mfma_f32_32x32x16_bf16 v[50:65], v[162:165], v[182:185], v[50:65]
	v_mfma_f32_32x32x16_bf16 v[18:33], v[162:165], v[186:189], v[18:33]
	v_mfma_f32_32x32x16_bf16 v[34:49], v[166:169], v[182:185], v[34:49]
	v_mfma_f32_32x32x16_bf16 v[2:17], v[166:169], v[186:189], v[2:17]
	s_waitcnt lgkmcnt(5)
	v_mfma_f32_32x32x16_bf16 v[50:65], v[110:113], v[118:121], v[50:65]
	s_waitcnt lgkmcnt(4)
	v_mfma_f32_32x32x16_bf16 v[18:33], v[110:113], v[122:125], v[18:33]
	v_mfma_f32_32x32x16_bf16 v[34:49], v[114:117], v[118:121], v[34:49]
	v_mfma_f32_32x32x16_bf16 v[2:17], v[114:117], v[122:125], v[2:17]
	ds_read_b128 v[110:113], v89
	ds_read_b128 v[114:117], v89 offset:4096
	ds_read_b128 v[118:121], v88 offset:32768
	ds_read_b128 v[122:125], v88 offset:36864
	s_waitcnt lgkmcnt(5)
	v_mfma_f32_32x32x16_bf16 v[50:65], v[126:129], v[138:141], v[50:65]
	s_waitcnt lgkmcnt(4)
	v_mfma_f32_32x32x16_bf16 v[18:33], v[126:129], v[142:145], v[18:33]
	v_mfma_f32_32x32x16_bf16 v[34:49], v[134:137], v[138:141], v[34:49]
	v_mfma_f32_32x32x16_bf16 v[2:17], v[134:137], v[142:145], v[2:17]
	ds_read_b128 v[126:129], v87
	ds_read_b128 v[134:137], v87 offset:4096
	ds_read_b128 v[138:141], v86 offset:32768
	ds_read_b128 v[142:145], v86 offset:36864
	s_waitcnt vmcnt(0)
	s_waitcnt lgkmcnt(0)
	s_barrier
	ds_read_b128 v[66:69], v91 offset:16384
	ds_read_b128 v[70:73], v91 offset:20480
	ds_read_b128 v[74:77], v92 offset:49152
	ds_read_b128 v[78:81], v92 offset:53248
	ds_read_b128 v[94:97], v93 offset:16384
	ds_read_b128 v[98:101], v93 offset:20480
	ds_read_b128 v[102:105], v90 offset:49152
	ds_read_b128 v[90:93], v90 offset:53248
	v_mfma_f32_32x32x16_bf16 v[50:65], v[110:113], v[118:121], v[50:65]
	v_mfma_f32_32x32x16_bf16 v[18:33], v[110:113], v[122:125], v[18:33]
	v_mfma_f32_32x32x16_bf16 v[34:49], v[114:117], v[118:121], v[34:49]
	v_mfma_f32_32x32x16_bf16 v[2:17], v[114:117], v[122:125], v[2:17]
	v_mfma_f32_32x32x16_bf16 v[50:65], v[126:129], v[138:141], v[50:65]
	v_mfma_f32_32x32x16_bf16 v[18:33], v[126:129], v[142:145], v[18:33]
	v_mfma_f32_32x32x16_bf16 v[34:49], v[134:137], v[138:141], v[34:49]
	v_mfma_f32_32x32x16_bf16 v[2:17], v[134:137], v[142:145], v[2:17]
	s_waitcnt lgkmcnt(5)
	v_mfma_f32_32x32x16_bf16 v[50:65], v[66:69], v[74:77], v[50:65]
	s_waitcnt lgkmcnt(4)
	v_mfma_f32_32x32x16_bf16 v[18:33], v[66:69], v[78:81], v[18:33]
	v_mfma_f32_32x32x16_bf16 v[34:49], v[70:73], v[74:77], v[34:49]
	v_mfma_f32_32x32x16_bf16 v[2:17], v[70:73], v[78:81], v[2:17]
	ds_read_b128 v[66:69], v89 offset:16384
	ds_read_b128 v[70:73], v89 offset:20480
	ds_read_b128 v[74:77], v88 offset:49152
	ds_read_b128 v[78:81], v88 offset:53248
	s_waitcnt lgkmcnt(5)
	v_mfma_f32_32x32x16_bf16 v[50:65], v[94:97], v[102:105], v[50:65]
	s_waitcnt lgkmcnt(4)
	v_mfma_f32_32x32x16_bf16 v[18:33], v[94:97], v[90:93], v[18:33]
	v_mfma_f32_32x32x16_bf16 v[34:49], v[98:101], v[102:105], v[34:49]
	v_mfma_f32_32x32x16_bf16 v[2:17], v[98:101], v[90:93], v[2:17]
	ds_read_b128 v[88:91], v87 offset:16384
	ds_read_b128 v[92:95], v87 offset:20480
	ds_read_b128 v[96:99], v86 offset:49152
	ds_read_b128 v[100:103], v86 offset:53248
	s_lshl_b32 s6, s34, 7
	v_lshl_add_u32 v0, v84, 6, s6
	s_min_i32 s7, s6, 0x4000
	v_lshl_or_b32 v0, v85, 2, v0
	s_movk_i32 s6, 0x4000
	s_waitcnt lgkmcnt(5)
	v_mfma_f32_32x32x16_bf16 v[50:65], v[66:69], v[74:77], v[50:65]
	v_cmp_gt_i32_e32 vcc, s6, v0
	v_readlane_b32 s36, v210, 2
	v_readlane_b32 s40, v210, 6
	s_ashr_i32 s7, s7, 12
	s_add_i32 s7, s7, s70
	s_mul_hi_i32 s8, s7, 0x6000
	s_mulk_i32 s7, 0x6000
	s_waitcnt lgkmcnt(4)
	v_mfma_f32_32x32x16_bf16 v[18:33], v[66:69], v[78:81], v[18:33]
	v_add_u32_e32 v66, 0xffffc000, v0
	v_ashrrev_i32_e32 v67, 31, v0
	v_cndmask_b32_e32 v66, v66, v0, vcc
	v_mov_b32_e32 v0, s95
	v_mov_b32_e32 v68, s89
	v_cndmask_b32_e32 v69, v0, v68, vcc
	v_mov_b32_e32 v0, s94
	v_mov_b32_e32 v68, s88
	v_mfma_f32_32x32x16_bf16 v[34:49], v[70:73], v[74:77], v[34:49]
	v_cndmask_b32_e32 v67, 0, v67, vcc
	v_cndmask_b32_e32 v68, v0, v68, vcc
	v_mov_b32_e32 v0, s40
	v_lshlrev_b64 v[66:67], 12, v[66:67]
	v_lshl_add_u64 v[134:135], v[68:69], 0, v[66:67]
	v_readlane_b32 s37, v210, 3
	v_readlane_b32 s41, v210, 7
	v_mfma_f32_32x32x16_bf16 v[2:17], v[70:73], v[78:81], v[2:17]
	v_mov_b32_e32 v70, s36
	v_cndmask_b32_e32 v0, v0, v70, vcc
	v_cndmask_b32_e64 v68, v68, v0, s[52:53]
	v_lshl_or_b32 v0, v83, 6, v82
	s_add_u32 s7, s90, s7
	v_mov_b32_e32 v70, s41
	v_mov_b32_e32 v71, s37
	v_subrev_u32_e32 v0, s5, v0
	s_addc_u32 s8, s91, s8
	v_cndmask_b32_e32 v70, v70, v71, vcc
	v_add_u32_e32 v168, s3, v0
	s_add_u32 s34, s7, 0x2000
	v_cndmask_b32_e64 v69, v69, v70, s[52:53]
	v_ashrrev_i32_e32 v169, 31, v168
	s_addc_u32 s35, s8, 0
	v_lshl_add_u64 v[66:67], v[68:69], 0, v[66:67]
	v_lshlrev_b64 v[136:137], 2, v[168:169]
	v_lshl_add_u64 v[68:69], s[34:35], 0, v[136:137]
	v_lshl_add_u64 v[66:67], v[66:67], 0, v[136:137]
	s_movk_i32 s8, 0x1000
	s_waitcnt lgkmcnt(0)
	s_barrier
	global_load_dword v0, v[68:69], off
	v_add_co_u32_e32 v68, vcc, s8, v66
	s_movk_i32 s6, 0x2000
	s_nop 0
	v_addc_co_u32_e32 v69, vcc, 0, v67, vcc
	global_load_dword v138, v[66:67], off
	v_add_co_u32_e32 v70, vcc, s6, v66
	v_readlane_b32 s38, v210, 4
	s_nop 0
	v_addc_co_u32_e32 v71, vcc, 0, v67, vcc
	global_load_dword v139, v[70:71], off offset:-4096
	global_load_dword v140, v[70:71], off
	s_movk_i32 s38, 0x3000
	v_add_co_u32_e32 v72, vcc, s38, v66
	s_mov_b32 s7, 0x8000
	s_nop 0
	v_addc_co_u32_e32 v73, vcc, 0, v67, vcc
	global_load_dword v141, v[72:73], off
	v_add_co_u32_e32 v74, vcc, s7, v66
	s_mov_b32 s36, 0x9000
	s_nop 0
	v_addc_co_u32_e32 v75, vcc, 0, v67, vcc
	v_add_co_u32_e32 v76, vcc, s36, v66
	s_mov_b32 s37, 0xa000
	s_nop 0
	v_addc_co_u32_e32 v77, vcc, 0, v67, vcc
	v_add_co_u32_e32 v78, vcc, s37, v66
	s_mov_b32 s5, 0xb000
	s_nop 0
	v_addc_co_u32_e32 v79, vcc, 0, v67, vcc
	global_load_dword v142, v[76:77], off offset:-4096
	global_load_dword v143, v[76:77], off
	v_add_co_u32_e32 v80, vcc, s5, v66
	v_readlane_b32 s39, v210, 5
	s_nop 0
	v_addc_co_u32_e32 v81, vcc, 0, v67, vcc
	v_add_co_u32_e32 v82, vcc, s10, v66
	s_mov_b32 s39, 0x11000
	s_nop 0
	v_addc_co_u32_e32 v83, vcc, 0, v67, vcc
	global_load_dword v144, v[80:81], off offset:-4096
	global_load_dword v145, v[80:81], off
	v_add_co_u32_e32 v84, vcc, s39, v66
	v_mfma_f32_32x32x16_bf16 v[50:65], v[88:91], v[96:99], v[50:65]
	s_nop 0
	v_addc_co_u32_e32 v85, vcc, 0, v67, vcc
	v_add_co_u32_e32 v86, vcc, s62, v66
	global_load_dword v146, v[84:85], off offset:-4096
	global_load_dword v147, v[84:85], off
	v_addc_co_u32_e32 v87, vcc, 0, v67, vcc
	v_mfma_f32_32x32x16_bf16 v[18:33], v[88:91], v[100:103], v[18:33]
	v_add_co_u32_e32 v88, vcc, s57, v66
	v_lshl_add_u64 v[134:135], v[134:135], 0, v[136:137]
	s_nop 0
	v_addc_co_u32_e32 v89, vcc, 0, v67, vcc
	v_add_co_u32_e32 v90, vcc, s54, v66
	v_mfma_f32_32x32x16_bf16 v[34:49], v[92:95], v[96:99], v[34:49]
	s_nop 0
	v_addc_co_u32_e32 v91, vcc, 0, v67, vcc
	global_load_dword v148, v[88:89], off offset:-4096
	global_load_dword v149, v[88:89], off
	s_add_i32 s4, s4, s66
	s_add_i32 s3, s3, s2
	s_cmp_lt_i32 s4, s59
	v_readlane_b32 s42, v210, 8
	v_mfma_f32_32x32x16_bf16 v[2:17], v[92:95], v[100:103], v[2:17]
	v_add_co_u32_e32 v92, vcc, s55, v66
	v_readlane_b32 s43, v210, 9
	s_nop 0
	v_addc_co_u32_e32 v93, vcc, 0, v67, vcc
	v_add_co_u32_e32 v94, vcc, s72, v66
	global_load_dword v150, v[92:93], off offset:-4096
	global_load_dword v151, v[92:93], off
	v_addc_co_u32_e32 v95, vcc, 0, v67, vcc
	v_add_co_u32_e32 v96, vcc, s73, v66
	s_waitcnt vmcnt(13)
	v_fmac_f32_e32 v138, v50, v0
	v_addc_co_u32_e32 v97, vcc, 0, v67, vcc
	v_add_co_u32_e32 v98, vcc, s63, v66
	global_load_dword v152, v[96:97], off offset:-4096
	global_load_dword v153, v[96:97], off
	v_addc_co_u32_e32 v99, vcc, 0, v67, vcc
	v_add_co_u32_e32 v100, vcc, s74, v66
	s_waitcnt vmcnt(14)
	v_fmac_f32_e32 v139, v51, v0
	v_addc_co_u32_e32 v101, vcc, 0, v67, vcc
	v_add_co_u32_e32 v102, vcc, s75, v66
	global_load_dword v154, v[100:101], off offset:-4096
	global_load_dword v155, v[100:101], off
	v_addc_co_u32_e32 v103, vcc, 0, v67, vcc
	v_add_co_u32_e32 v104, vcc, s76, v66
	s_waitcnt vmcnt(15)
	v_fmac_f32_e32 v140, v52, v0
	v_addc_co_u32_e32 v105, vcc, 0, v67, vcc
	v_add_co_u32_e32 v106, vcc, s77, v66
	global_load_dword v156, v[104:105], off offset:-4096
	global_load_dword v157, v[104:105], off
	v_addc_co_u32_e32 v107, vcc, 0, v67, vcc
	v_add_co_u32_e32 v108, vcc, s78, v66
	s_waitcnt vmcnt(16)
	v_fmac_f32_e32 v141, v53, v0
	v_addc_co_u32_e32 v109, vcc, 0, v67, vcc
	v_add_co_u32_e32 v110, vcc, s79, v66
	global_load_dword v158, v[108:109], off offset:-4096
	global_load_dword v159, v[108:109], off
	v_addc_co_u32_e32 v111, vcc, 0, v67, vcc
	v_add_co_u32_e32 v112, vcc, s58, v66
	s_waitcnt vmcnt(17)
	v_fmac_f32_e32 v142, v54, v0
	v_addc_co_u32_e32 v113, vcc, 0, v67, vcc
	v_add_co_u32_e32 v114, vcc, s61, v66
	global_load_dword v160, v[112:113], off offset:-4096
	global_load_dword v161, v[112:113], off
	v_addc_co_u32_e32 v115, vcc, 0, v67, vcc
	v_add_co_u32_e32 v116, vcc, s56, v66
	s_waitcnt vmcnt(18)
	v_fmac_f32_e32 v143, v55, v0
	v_addc_co_u32_e32 v117, vcc, 0, v67, vcc
	v_add_co_u32_e32 v118, vcc, s97, v66
	global_load_dword v162, v[116:117], off offset:-4096
	global_load_dword v163, v[116:117], off
	v_addc_co_u32_e32 v119, vcc, 0, v67, vcc
	v_add_co_u32_e32 v120, vcc, s9, v66
	s_waitcnt vmcnt(19)
	v_fmac_f32_e32 v144, v56, v0
	v_addc_co_u32_e32 v121, vcc, 0, v67, vcc
	v_add_co_u32_e32 v122, vcc, s69, v66
	global_load_dword v164, v[120:121], off offset:-4096
	global_load_dword v165, v[120:121], off
	v_addc_co_u32_e32 v123, vcc, 0, v67, vcc
	v_add_co_u32_e32 v124, vcc, s67, v66
	s_waitcnt vmcnt(20)
	v_fmac_f32_e32 v145, v57, v0
	v_addc_co_u32_e32 v125, vcc, 0, v67, vcc
	v_add_co_u32_e32 v126, vcc, s60, v66
	global_load_dword v166, v[124:125], off offset:-4096
	global_load_dword v167, v[124:125], off
	v_addc_co_u32_e32 v127, vcc, 0, v67, vcc
	v_add_co_u32_e32 v128, vcc, s33, v66
	s_waitcnt vmcnt(21)
	v_fmac_f32_e32 v146, v58, v0
	v_addc_co_u32_e32 v129, vcc, 0, v67, vcc
	global_load_dword v169, v[128:129], off offset:-4096
	global_load_dword v181, v[128:129], off
	v_add_co_u32_e32 v50, vcc, s8, v134
	global_store_dword v[134:135], v138, off
	s_nop 0
	v_addc_co_u32_e32 v51, vcc, 0, v135, vcc
	v_add_co_u32_e32 v136, vcc, s6, v134
	s_waitcnt vmcnt(23)
	v_fmac_f32_e32 v147, v59, v0
	v_addc_co_u32_e32 v137, vcc, 0, v135, vcc
	v_add_co_u32_e32 v52, vcc, s38, v134
	global_store_dword v[136:137], v139, off offset:-4096
	s_nop 0
	v_addc_co_u32_e32 v53, vcc, 0, v135, vcc
	v_add_co_u32_e32 v138, vcc, s7, v134
	global_store_dword v[136:137], v140, off
	s_nop 0
	v_addc_co_u32_e32 v139, vcc, 0, v135, vcc
	v_add_co_u32_e32 v140, vcc, s36, v134
	global_store_dword v[52:53], v141, off
	s_nop 0
	v_addc_co_u32_e32 v141, vcc, 0, v135, vcc
	v_add_co_u32_e32 v54, vcc, s37, v134
	global_store_dword v[140:141], v142, off offset:-4096
	s_nop 0
	v_addc_co_u32_e32 v55, vcc, 0, v135, vcc
	v_add_co_u32_e32 v142, vcc, s5, v134
	global_store_dword v[140:141], v143, off
	s_nop 0
	v_addc_co_u32_e32 v143, vcc, 0, v135, vcc
	v_add_co_u32_e32 v56, vcc, s10, v134
	global_store_dword v[142:143], v144, off offset:-4096
	s_nop 0
	v_addc_co_u32_e32 v57, vcc, 0, v135, vcc
	v_add_co_u32_e32 v144, vcc, s39, v134
	global_store_dword v[142:143], v145, off
	s_nop 0
	v_addc_co_u32_e32 v145, vcc, 0, v135, vcc
	v_add_co_u32_e32 v58, vcc, s62, v134
	global_store_dword v[144:145], v146, off offset:-4096
	s_nop 0
	v_addc_co_u32_e32 v59, vcc, 0, v135, vcc
	v_add_co_u32_e32 v146, vcc, s57, v134
	global_store_dword v[144:145], v147, off
	s_nop 0
	v_addc_co_u32_e32 v147, vcc, 0, v135, vcc
	s_waitcnt vmcnt(31)
	v_fmac_f32_e32 v148, v60, v0
	v_add_co_u32_e32 v60, vcc, s54, v134
	s_waitcnt vmcnt(30)
	v_fmac_f32_e32 v149, v61, v0
	v_addc_co_u32_e32 v61, vcc, 0, v135, vcc
	global_store_dword v[146:147], v148, off offset:-4096
	v_add_co_u32_e32 v148, vcc, s55, v134
	global_store_dword v[146:147], v149, off
	s_nop 0
	v_addc_co_u32_e32 v149, vcc, 0, v135, vcc
	s_waitcnt vmcnt(31)
	v_fmac_f32_e32 v150, v62, v0
	v_add_co_u32_e32 v62, vcc, s72, v134
	s_waitcnt vmcnt(30)
	v_fmac_f32_e32 v151, v63, v0
	v_addc_co_u32_e32 v63, vcc, 0, v135, vcc
	global_store_dword v[148:149], v150, off offset:-4096
	v_add_co_u32_e32 v150, vcc, s73, v134
	global_store_dword v[148:149], v151, off
	s_nop 0
	v_addc_co_u32_e32 v151, vcc, 0, v135, vcc
	s_waitcnt vmcnt(31)
	v_fmac_f32_e32 v152, v64, v0
	v_add_co_u32_e32 v64, vcc, s63, v134
	s_waitcnt vmcnt(30)
	v_fmac_f32_e32 v153, v65, v0
	v_addc_co_u32_e32 v65, vcc, 0, v135, vcc
	global_store_dword v[150:151], v152, off offset:-4096
	v_add_co_u32_e32 v152, vcc, s74, v134
	global_store_dword v[150:151], v153, off
	s_nop 0
	v_addc_co_u32_e32 v153, vcc, 0, v135, vcc
	s_waitcnt vmcnt(31)
	v_fmac_f32_e32 v154, v34, v0
	v_add_co_u32_e32 v34, vcc, s75, v134
	s_waitcnt vmcnt(30)
	v_fmac_f32_e32 v155, v35, v0
	v_addc_co_u32_e32 v35, vcc, 0, v135, vcc
	global_store_dword v[152:153], v154, off offset:-4096
	v_add_co_u32_e32 v154, vcc, s76, v134
	global_store_dword v[152:153], v155, off
	s_nop 0
	v_addc_co_u32_e32 v155, vcc, 0, v135, vcc
	s_waitcnt vmcnt(31)
	v_fmac_f32_e32 v156, v36, v0
	v_add_co_u32_e32 v36, vcc, s77, v134
	s_waitcnt vmcnt(30)
	v_fmac_f32_e32 v157, v37, v0
	v_addc_co_u32_e32 v37, vcc, 0, v135, vcc
	global_store_dword v[154:155], v156, off offset:-4096
	v_add_co_u32_e32 v156, vcc, s78, v134
	global_store_dword v[154:155], v157, off
	s_nop 0
	v_addc_co_u32_e32 v157, vcc, 0, v135, vcc
	s_waitcnt vmcnt(31)
	v_fmac_f32_e32 v158, v38, v0
	v_add_co_u32_e32 v38, vcc, s79, v134
	s_waitcnt vmcnt(30)
	v_fmac_f32_e32 v159, v39, v0
	v_addc_co_u32_e32 v39, vcc, 0, v135, vcc
	global_store_dword v[156:157], v158, off offset:-4096
	v_add_co_u32_e32 v158, vcc, s58, v134
	global_store_dword v[156:157], v159, off
	s_nop 0
	v_addc_co_u32_e32 v159, vcc, 0, v135, vcc
	s_waitcnt vmcnt(31)
	v_fmac_f32_e32 v160, v40, v0
	v_add_co_u32_e32 v40, vcc, s61, v134
	s_waitcnt vmcnt(30)
	v_fmac_f32_e32 v161, v41, v0
	v_addc_co_u32_e32 v41, vcc, 0, v135, vcc
	global_store_dword v[158:159], v160, off offset:-4096
	v_add_co_u32_e32 v160, vcc, s56, v134
	global_store_dword v[158:159], v161, off
	s_nop 0
	v_addc_co_u32_e32 v161, vcc, 0, v135, vcc
	s_waitcnt vmcnt(31)
	v_fmac_f32_e32 v162, v42, v0
	v_add_co_u32_e32 v42, vcc, s97, v134
	s_waitcnt vmcnt(30)
	v_fmac_f32_e32 v163, v43, v0
	v_addc_co_u32_e32 v43, vcc, 0, v135, vcc
	global_store_dword v[160:161], v162, off offset:-4096
	v_add_co_u32_e32 v162, vcc, s9, v134
	global_store_dword v[160:161], v163, off
	s_nop 0
	v_addc_co_u32_e32 v163, vcc, 0, v135, vcc
	s_waitcnt vmcnt(31)
	v_fmac_f32_e32 v164, v44, v0
	v_add_co_u32_e32 v44, vcc, s69, v134
	s_waitcnt vmcnt(30)
	v_fmac_f32_e32 v165, v45, v0
	v_addc_co_u32_e32 v45, vcc, 0, v135, vcc
	global_store_dword v[162:163], v164, off offset:-4096
	v_add_co_u32_e32 v164, vcc, s67, v134
	global_store_dword v[162:163], v165, off
	s_nop 0
	v_addc_co_u32_e32 v165, vcc, 0, v135, vcc
	s_waitcnt vmcnt(31)
	v_fmac_f32_e32 v166, v46, v0
	v_add_co_u32_e32 v46, vcc, s60, v134
	s_waitcnt vmcnt(30)
	v_fmac_f32_e32 v167, v47, v0
	v_addc_co_u32_e32 v47, vcc, 0, v135, vcc
	global_store_dword v[164:165], v166, off offset:-4096
	s_waitcnt vmcnt(30)
	v_fmac_f32_e32 v169, v48, v0
	v_add_co_u32_e32 v166, vcc, s33, v134
	v_add_u32_e32 v48, 32, v168
	global_store_dword v[164:165], v167, off
	v_addc_co_u32_e32 v167, vcc, 0, v135, vcc
	s_waitcnt vmcnt(30)
	v_fmac_f32_e32 v181, v49, v0
	v_ashrrev_i32_e32 v49, 31, v48
	global_store_dword v[166:167], v169, off offset:-4096
	global_store_dword v[166:167], v181, off
	v_lshl_add_u64 v[48:49], v[48:49], 2, s[34:35]
	global_load_dword v0, v[48:49], off
	s_nop 0
	global_load_dword v48, v[66:67], off offset:128
	global_load_dword v49, v[68:69], off offset:128
	s_nop 0
	global_load_dword v66, v[70:71], off offset:128
	global_load_dword v67, v[72:73], off offset:128
	global_load_dword v68, v[74:75], off offset:128
	global_load_dword v69, v[76:77], off offset:128
	s_nop 0
	global_load_dword v70, v[78:79], off offset:128
	global_load_dword v71, v[80:81], off offset:128
	global_load_dword v72, v[82:83], off offset:128
	global_load_dword v73, v[84:85], off offset:128
	global_load_dword v74, v[86:87], off offset:128
	global_load_dword v75, v[88:89], off offset:128
	global_load_dword v76, v[90:91], off offset:128
	global_load_dword v77, v[92:93], off offset:128
	global_load_dword v78, v[94:95], off offset:128
	global_load_dword v79, v[96:97], off offset:128
	global_load_dword v80, v[98:99], off offset:128
	global_load_dword v81, v[100:101], off offset:128
	global_load_dword v82, v[102:103], off offset:128
	global_load_dword v83, v[104:105], off offset:128
	global_load_dword v84, v[106:107], off offset:128
	global_load_dword v85, v[108:109], off offset:128
	global_load_dword v86, v[110:111], off offset:128
	global_load_dword v87, v[112:113], off offset:128
	global_load_dword v88, v[114:115], off offset:128
	global_load_dword v89, v[116:117], off offset:128
	global_load_dword v90, v[118:119], off offset:128
	global_load_dword v91, v[120:121], off offset:128
	global_load_dword v92, v[122:123], off offset:128
	global_load_dword v93, v[124:125], off offset:128
	global_load_dword v94, v[126:127], off offset:128
	global_load_dword v95, v[128:129], off offset:128
	v_readlane_b32 s44, v210, 10
	v_readlane_b32 s45, v210, 11
	v_readlane_b32 s46, v210, 12
	v_readlane_b32 s47, v210, 13
	v_readlane_b32 s48, v210, 14
	v_readlane_b32 s49, v210, 15
	v_readlane_b32 s50, v210, 16
	v_readlane_b32 s51, v210, 17
	s_waitcnt vmcnt(31)
	v_fmac_f32_e32 v48, v18, v0
	s_waitcnt vmcnt(30)
	v_fmac_f32_e32 v49, v19, v0
	s_waitcnt vmcnt(29)
	v_fmac_f32_e32 v66, v20, v0
	s_waitcnt vmcnt(28)
	v_fmac_f32_e32 v67, v21, v0
	s_waitcnt vmcnt(27)
	v_fmac_f32_e32 v68, v22, v0
	s_waitcnt vmcnt(26)
	v_fmac_f32_e32 v69, v23, v0
	s_waitcnt vmcnt(25)
	v_fmac_f32_e32 v70, v24, v0
	s_waitcnt vmcnt(24)
	v_fmac_f32_e32 v71, v25, v0
	s_waitcnt vmcnt(23)
	v_fmac_f32_e32 v72, v26, v0
	s_waitcnt vmcnt(22)
	v_fmac_f32_e32 v73, v27, v0
	s_waitcnt vmcnt(21)
	v_fmac_f32_e32 v74, v28, v0
	s_waitcnt vmcnt(20)
	v_fmac_f32_e32 v75, v29, v0
	s_waitcnt vmcnt(19)
	v_fmac_f32_e32 v76, v30, v0
	s_waitcnt vmcnt(18)
	v_fmac_f32_e32 v77, v31, v0
	s_waitcnt vmcnt(17)
	v_fmac_f32_e32 v78, v32, v0
	s_waitcnt vmcnt(16)
	v_fmac_f32_e32 v79, v33, v0
	s_waitcnt vmcnt(15)
	v_fmac_f32_e32 v80, v2, v0
	s_waitcnt vmcnt(14)
	v_fmac_f32_e32 v81, v3, v0
	s_waitcnt vmcnt(13)
	v_fmac_f32_e32 v82, v4, v0
	s_waitcnt vmcnt(12)
	v_fmac_f32_e32 v83, v5, v0
	s_waitcnt vmcnt(11)
	v_fmac_f32_e32 v84, v6, v0
	s_waitcnt vmcnt(10)
	v_fmac_f32_e32 v85, v7, v0
	s_waitcnt vmcnt(9)
	v_fmac_f32_e32 v86, v8, v0
	s_waitcnt vmcnt(8)
	v_fmac_f32_e32 v87, v9, v0
	s_waitcnt vmcnt(7)
	v_fmac_f32_e32 v88, v10, v0
	s_waitcnt vmcnt(6)
	v_fmac_f32_e32 v89, v11, v0
	s_waitcnt vmcnt(5)
	v_fmac_f32_e32 v90, v12, v0
	s_waitcnt vmcnt(4)
	v_fmac_f32_e32 v91, v13, v0
	s_waitcnt vmcnt(3)
	v_fmac_f32_e32 v92, v14, v0
	s_waitcnt vmcnt(2)
	v_fmac_f32_e32 v93, v15, v0
	s_waitcnt vmcnt(1)
	v_fmac_f32_e32 v94, v16, v0
	s_waitcnt vmcnt(0)
	v_fmac_f32_e32 v95, v17, v0
	global_store_dword v[134:135], v48, off offset:128
	global_store_dword v[50:51], v49, off offset:128
	global_store_dword v[136:137], v66, off offset:128
	global_store_dword v[52:53], v67, off offset:128
	global_store_dword v[138:139], v68, off offset:128
	global_store_dword v[140:141], v69, off offset:128
	global_store_dword v[54:55], v70, off offset:128
	global_store_dword v[142:143], v71, off offset:128
	global_store_dword v[56:57], v72, off offset:128
	global_store_dword v[144:145], v73, off offset:128
	global_store_dword v[58:59], v74, off offset:128
	global_store_dword v[146:147], v75, off offset:128
	global_store_dword v[60:61], v76, off offset:128
	global_store_dword v[148:149], v77, off offset:128
	global_store_dword v[62:63], v78, off offset:128
	global_store_dword v[150:151], v79, off offset:128
	global_store_dword v[64:65], v80, off offset:128
	global_store_dword v[152:153], v81, off offset:128
	global_store_dword v[34:35], v82, off offset:128
	global_store_dword v[154:155], v83, off offset:128
	global_store_dword v[36:37], v84, off offset:128
	global_store_dword v[156:157], v85, off offset:128
	global_store_dword v[38:39], v86, off offset:128
	global_store_dword v[158:159], v87, off offset:128
	global_store_dword v[40:41], v88, off offset:128
	global_store_dword v[160:161], v89, off offset:128
	global_store_dword v[42:43], v90, off offset:128
	global_store_dword v[162:163], v91, off offset:128
	global_store_dword v[44:45], v92, off offset:128
	global_store_dword v[164:165], v93, off offset:128
	global_store_dword v[46:47], v94, off offset:128
	global_store_dword v[166:167], v95, off offset:128
	s_cbranch_scc1 .LBB0_1186
	v_readlane_b32 s72, v208, 43
	v_readlane_b32 s42, v208, 51
	v_readlane_b32 s54, v209, 14
	s_mov_b32 s62, 0x3b000
	v_readlane_b32 s73, v208, 44
	v_readlane_b32 s74, v208, 45
	v_readlane_b32 s75, v208, 46
	v_readlane_b32 s76, v208, 47
	v_readlane_b32 s77, v208, 48
	v_readlane_b32 s78, v208, 49
	v_readlane_b32 s79, v208, 50
	v_readlane_b32 s43, v208, 52
	v_readlane_b32 s55, v209, 15
	s_mov_b32 s67, 0x3a000
	v_readlane_b32 s97, v209, 2
	v_readlane_b32 s60, v208, 63
	s_mov_b32 s56, 0x10000
	s_mov_b32 s57, 0x20000
	s_mov_b32 s58, 0x30000
	s_movk_i32 s59, 0x70
	s_movk_i32 s53, 0x2000
	s_mov_b32 s52, 0xb000

.LBB0_1298:
	s_ashr_i32 s6, s5, 31
	s_lshr_b32 s6, s6, 27
	s_add_i32 s6, s5, s6
	s_ashr_i32 s34, s6, 5
	s_ashr_i32 s35, s34, 31
	v_mov_b32_e32 v36, v133
	s_lshl_b64 s[6:7], s[34:35], 18
	s_add_u32 s6, s38, s6
	v_ashrrev_i32_e32 v34, 3, v36
	v_ashrrev_i32_e32 v35, 31, v34
	s_addc_u32 s7, s39, s7
	v_lshlrev_b64 v[2:3], 11, v[34:35]
	v_lshlrev_b32_e32 v0, 4, v36
	v_lshl_add_u64 v[2:3], s[6:7], 0, v[2:3]
	v_and_b32_e32 v0, 0x70, v0
	s_lshl_b32 s6, s34, 12
	v_lshl_add_u64 v[66:67], v[2:3], 0, v[0:1]
	v_subrev_u32_e32 v2, s6, v34
	v_add_u32_e32 v2, s4, v2
	v_ashrrev_i32_e32 v3, 31, v2
	v_lshlrev_b64 v[2:3], 11, v[2:3]
	v_lshl_add_u64 v[2:3], s[0:1], 0, v[2:3]
	v_add_co_u32_e32 v70, vcc, s56, v66
	v_lshl_add_u64 v[68:69], v[2:3], 0, v[0:1]
	s_nop 0
	v_addc_co_u32_e32 v71, vcc, 0, v67, vcc
	v_add_co_u32_e32 v72, vcc, s56, v68
	v_addc_co_u32_e32 v73, vcc, 0, v69, vcc
	v_add_co_u32_e32 v74, vcc, s57, v66
	s_nop 0
	v_addc_co_u32_e32 v75, vcc, 0, v67, vcc
	v_add_co_u32_e32 v76, vcc, s57, v68
	s_nop 0
	v_addc_co_u32_e32 v77, vcc, 0, v69, vcc
	v_add_co_u32_e32 v78, vcc, s58, v66
	s_nop 0
	v_addc_co_u32_e32 v79, vcc, 0, v67, vcc
	v_add_co_u32_e32 v80, vcc, s58, v68
	v_lshlrev_b32_e32 v0, 7, v34
	s_nop 0
	v_addc_co_u32_e32 v81, vcc, 0, v69, vcc
	v_lshrrev_b32_e32 v216, 4, v133
	v_xor_b32_e32 v216, v216, v133
	v_and_b32_e32 v216, 7, v216
	v_lshlrev_b32_e32 v216, 4, v216
	v_mov_b32_e32 v217, 0x70
	v_lshrrev_b32_e32 v218, 6, v133
	v_lshlrev_b32_e32 v218, 10, v218
	s_nop 0
	v_readfirstlane_b32 s32, v218
	v_bfi_b32 v66, v217, v216, v66
	v_bfi_b32 v70, v217, v216, v70
	v_bfi_b32 v74, v217, v216, v74
	v_bfi_b32 v78, v217, v216, v78
	v_bfi_b32 v68, v217, v216, v68
	v_bfi_b32 v72, v217, v216, v72
	v_bfi_b32 v76, v217, v216, v76
	v_bfi_b32 v80, v217, v216, v80
	s_mov_b64 s[98:99], 0x80
	s_add_u32 m0, s32, 0x0
	s_nop 0
	global_load_lds_dwordx4 v[66:67], off
	s_add_u32 m0, s32, 0x1000
	s_nop 0
	global_load_lds_dwordx4 v[70:71], off
	s_add_u32 m0, s32, 0x2000
	s_nop 0
	global_load_lds_dwordx4 v[74:75], off
	s_add_u32 m0, s32, 0x3000
	s_nop 0
	global_load_lds_dwordx4 v[78:79], off
	s_add_u32 m0, s32, 0x8000
	s_nop 0
	global_load_lds_dwordx4 v[68:69], off
	s_add_u32 m0, s32, 0x9000
	s_nop 0
	global_load_lds_dwordx4 v[72:73], off
	s_add_u32 m0, s32, 0xa000
	s_nop 0
	global_load_lds_dwordx4 v[76:77], off
	s_add_u32 m0, s32, 0xb000
	s_nop 0
	global_load_lds_dwordx4 v[80:81], off
	v_lshl_add_u64 v[66:67], v[66:67], 0, s[98:99]
	v_lshl_add_u64 v[70:71], v[70:71], 0, s[98:99]
	v_lshl_add_u64 v[74:75], v[74:75], 0, s[98:99]
	v_lshl_add_u64 v[78:79], v[78:79], 0, s[98:99]
	v_lshl_add_u64 v[68:69], v[68:69], 0, s[98:99]
	v_lshl_add_u64 v[72:73], v[72:73], 0, s[98:99]
	v_lshl_add_u64 v[76:77], v[76:77], 0, s[98:99]
	v_lshl_add_u64 v[80:81], v[80:81], 0, s[98:99]
	v_lshrrev_b32_e32 v34, 1, v34
	v_xor_b32_e32 v34, v34, v36
	v_lshlrev_b32_e32 v34, 4, v34
	v_and_or_b32 v0, v34, s59, v0
	s_waitcnt vmcnt(26)
	v_and_b32_e32 v82, 31, v36
	v_bfe_u32 v83, v36, 5, 1
	v_ashrrev_i32_e32 v84, 7, v36
	v_bfe_u32 v85, v36, 6, 1
	s_waitcnt vmcnt(0)
	s_waitcnt lgkmcnt(0)
	s_barrier
	s_add_u32 m0, s32, 0x4000
	s_nop 0
	global_load_lds_dwordx4 v[66:67], off
	s_add_u32 m0, s32, 0x5000
	s_nop 0
	global_load_lds_dwordx4 v[70:71], off
	s_add_u32 m0, s32, 0x6000
	s_nop 0
	global_load_lds_dwordx4 v[74:75], off
	s_add_u32 m0, s32, 0x7000
	s_nop 0
	global_load_lds_dwordx4 v[78:79], off
	s_add_u32 m0, s32, 0xc000
	s_nop 0
	global_load_lds_dwordx4 v[68:69], off
	s_add_u32 m0, s32, 0xd000
	s_nop 0
	global_load_lds_dwordx4 v[72:73], off
	s_add_u32 m0, s32, 0xe000
	s_nop 0
	global_load_lds_dwordx4 v[76:77], off
	s_add_u32 m0, s32, 0xf000
	s_nop 0
	global_load_lds_dwordx4 v[80:81], off
	v_lshrrev_b32_e32 v4, 1, v36
	v_lshlrev_b32_e32 v2, 7, v82
	v_bitop3_b32 v4, v4, v83, 7 bitop3:0x6c
	v_lshl_or_b32 v3, v84, 13, v2
	v_bfe_u32 v5, v36, 1, 3
	v_lshlrev_b32_e32 v4, 4, v4
	v_lshl_or_b32 v2, v85, 13, v2
	v_or_b32_e32 v91, v3, v4
	v_or_b32_e32 v92, v2, v4
	v_bitop3_b32 v4, v83, v5, 2 bitop3:0x36
	v_lshlrev_b32_e32 v4, 4, v4
	v_or_b32_e32 v93, v3, v4
	v_or_b32_e32 v90, v2, v4
	v_bitop3_b32 v4, v83, v5, 4 bitop3:0x36
	v_lshlrev_b32_e32 v4, 4, v4
	v_or_b32_e32 v89, v3, v4
	v_or_b32_e32 v88, v2, v4
	v_bitop3_b32 v4, v83, v5, 6 bitop3:0x36
	v_lshlrev_b32_e32 v4, 4, v4
	v_or_b32_e32 v87, v3, v4
	v_or_b32_e32 v86, v2, v4
	ds_read_b128 v[2:5], v91
	ds_read_b128 v[6:9], v92 offset:32768
	ds_read_b128 v[10:13], v91 offset:4096
	ds_read_b128 v[14:17], v92 offset:36864
	ds_read_b128 v[162:165], v93
	ds_read_b128 v[166:169], v90 offset:32768
	ds_read_b128 v[182:185], v93 offset:4096
	ds_read_b128 v[186:189], v90 offset:36864
	s_waitcnt lgkmcnt(6)
	v_mfma_f32_32x32x16_bf16 v[50:65], v[2:5], v[6:9], 0
	s_waitcnt lgkmcnt(4)
	v_mfma_f32_32x32x16_bf16 v[34:49], v[2:5], v[14:17], 0
	v_mfma_f32_32x32x16_bf16 v[18:33], v[10:13], v[6:9], 0
	v_mfma_f32_32x32x16_bf16 v[2:17], v[10:13], v[14:17], 0
	ds_read_b128 v[190:193], v89
	ds_read_b128 v[194:197], v89 offset:4096
	ds_read_b128 v[198:201], v88 offset:32768
	ds_read_b128 v[202:205], v88 offset:36864
	s_waitcnt lgkmcnt(6)
	v_mfma_f32_32x32x16_bf16 v[50:65], v[162:165], v[166:169], v[50:65]
	s_waitcnt lgkmcnt(4)
	v_mfma_f32_32x32x16_bf16 v[34:49], v[162:165], v[186:189], v[34:49]
	v_mfma_f32_32x32x16_bf16 v[18:33], v[182:185], v[166:169], v[18:33]
	v_mfma_f32_32x32x16_bf16 v[2:17], v[182:185], v[186:189], v[2:17]
	ds_read_b128 v[162:165], v87
	ds_read_b128 v[166:169], v87 offset:4096
	ds_read_b128 v[182:185], v86 offset:32768
	ds_read_b128 v[186:189], v86 offset:36864
	v_lshl_add_u64 v[66:67], v[66:67], 0, s[98:99]
	v_lshl_add_u64 v[70:71], v[70:71], 0, s[98:99]
	v_lshl_add_u64 v[74:75], v[74:75], 0, s[98:99]
	v_lshl_add_u64 v[78:79], v[78:79], 0, s[98:99]
	v_lshl_add_u64 v[68:69], v[68:69], 0, s[98:99]
	v_lshl_add_u64 v[72:73], v[72:73], 0, s[98:99]
	v_lshl_add_u64 v[76:77], v[76:77], 0, s[98:99]
	v_lshl_add_u64 v[80:81], v[80:81], 0, s[98:99]
	s_waitcnt vmcnt(0)
	s_waitcnt lgkmcnt(0)
	s_barrier
	s_add_u32 m0, s32, 0x0
	v_mfma_f32_32x32x16_bf16 v[50:65], v[190:193], v[198:201], v[50:65]
	global_load_lds_dwordx4 v[66:67], off
	s_add_u32 m0, s32, 0x1000
	v_mfma_f32_32x32x16_bf16 v[34:49], v[190:193], v[202:205], v[34:49]
	global_load_lds_dwordx4 v[70:71], off
	s_add_u32 m0, s32, 0x2000
	v_mfma_f32_32x32x16_bf16 v[18:33], v[194:197], v[198:201], v[18:33]
	global_load_lds_dwordx4 v[74:75], off
	s_add_u32 m0, s32, 0x3000
	v_mfma_f32_32x32x16_bf16 v[2:17], v[194:197], v[202:205], v[2:17]
	global_load_lds_dwordx4 v[78:79], off
	s_add_u32 m0, s32, 0x8000
	v_mfma_f32_32x32x16_bf16 v[50:65], v[162:165], v[182:185], v[50:65]
	global_load_lds_dwordx4 v[68:69], off
	s_add_u32 m0, s32, 0x9000
	v_mfma_f32_32x32x16_bf16 v[34:49], v[162:165], v[186:189], v[34:49]
	global_load_lds_dwordx4 v[72:73], off
	s_add_u32 m0, s32, 0xa000
	v_mfma_f32_32x32x16_bf16 v[18:33], v[166:169], v[182:185], v[18:33]
	global_load_lds_dwordx4 v[76:77], off
	s_add_u32 m0, s32, 0xb000
	v_mfma_f32_32x32x16_bf16 v[2:17], v[166:169], v[186:189], v[2:17]
	global_load_lds_dwordx4 v[80:81], off
	ds_read_b128 v[162:165], v91 offset:16384
	ds_read_b128 v[166:169], v92 offset:49152
	ds_read_b128 v[182:185], v91 offset:20480
	ds_read_b128 v[186:189], v92 offset:53248
	ds_read_b128 v[190:193], v93 offset:16384
	ds_read_b128 v[194:197], v90 offset:49152
	ds_read_b128 v[198:201], v93 offset:20480
	ds_read_b128 v[202:205], v90 offset:53248
	s_waitcnt lgkmcnt(6)
	v_mfma_f32_32x32x16_bf16 v[50:65], v[162:165], v[166:169], v[50:65]
	s_waitcnt lgkmcnt(4)
	v_mfma_f32_32x32x16_bf16 v[34:49], v[162:165], v[186:189], v[34:49]
	v_mfma_f32_32x32x16_bf16 v[18:33], v[182:185], v[166:169], v[18:33]
	v_mfma_f32_32x32x16_bf16 v[2:17], v[182:185], v[186:189], v[2:17]
	ds_read_b128 v[162:165], v89 offset:16384
	ds_read_b128 v[166:169], v89 offset:20480
	ds_read_b128 v[182:185], v88 offset:49152
	ds_read_b128 v[186:189], v88 offset:53248
	s_waitcnt lgkmcnt(6)
	v_mfma_f32_32x32x16_bf16 v[50:65], v[190:193], v[194:197], v[50:65]
	s_waitcnt lgkmcnt(4)
	v_mfma_f32_32x32x16_bf16 v[34:49], v[190:193], v[202:205], v[34:49]
	v_mfma_f32_32x32x16_bf16 v[18:33], v[198:201], v[194:197], v[18:33]
	v_mfma_f32_32x32x16_bf16 v[2:17], v[198:201], v[202:205], v[2:17]
	ds_read_b128 v[190:193], v87 offset:16384
	ds_read_b128 v[194:197], v87 offset:20480
	ds_read_b128 v[198:201], v86 offset:49152
	ds_read_b128 v[202:205], v86 offset:53248
	v_lshl_add_u64 v[66:67], v[66:67], 0, s[98:99]
	v_lshl_add_u64 v[70:71], v[70:71], 0, s[98:99]
	v_lshl_add_u64 v[74:75], v[74:75], 0, s[98:99]
	v_lshl_add_u64 v[78:79], v[78:79], 0, s[98:99]
	v_lshl_add_u64 v[68:69], v[68:69], 0, s[98:99]
	v_lshl_add_u64 v[72:73], v[72:73], 0, s[98:99]
	v_lshl_add_u64 v[76:77], v[76:77], 0, s[98:99]
	v_lshl_add_u64 v[80:81], v[80:81], 0, s[98:99]
	s_waitcnt vmcnt(0)
	s_waitcnt lgkmcnt(0)
	s_barrier
	s_add_u32 m0, s32, 0x4000
	v_mfma_f32_32x32x16_bf16 v[50:65], v[162:165], v[182:185], v[50:65]
	global_load_lds_dwordx4 v[66:67], off
	s_add_u32 m0, s32, 0x5000
	v_mfma_f32_32x32x16_bf16 v[34:49], v[162:165], v[186:189], v[34:49]
	global_load_lds_dwordx4 v[70:71], off
	s_add_u32 m0, s32, 0x6000
	v_mfma_f32_32x32x16_bf16 v[18:33], v[166:169], v[182:185], v[18:33]
	global_load_lds_dwordx4 v[74:75], off
	s_add_u32 m0, s32, 0x7000
	v_mfma_f32_32x32x16_bf16 v[2:17], v[166:169], v[186:189], v[2:17]
	global_load_lds_dwordx4 v[78:79], off
	s_add_u32 m0, s32, 0xc000
	v_mfma_f32_32x32x16_bf16 v[50:65], v[190:193], v[198:201], v[50:65]
	global_load_lds_dwordx4 v[68:69], off
	s_add_u32 m0, s32, 0xd000
	v_mfma_f32_32x32x16_bf16 v[34:49], v[190:193], v[202:205], v[34:49]
	global_load_lds_dwordx4 v[72:73], off
	s_add_u32 m0, s32, 0xe000
	v_mfma_f32_32x32x16_bf16 v[18:33], v[194:197], v[198:201], v[18:33]
	global_load_lds_dwordx4 v[76:77], off
	s_add_u32 m0, s32, 0xf000
	v_mfma_f32_32x32x16_bf16 v[2:17], v[194:197], v[202:205], v[2:17]
	global_load_lds_dwordx4 v[80:81], off
	ds_read_b128 v[162:165], v91
	ds_read_b128 v[166:169], v92 offset:32768
	ds_read_b128 v[182:185], v91 offset:4096
	ds_read_b128 v[186:189], v92 offset:36864
	ds_read_b128 v[190:193], v93
	ds_read_b128 v[194:197], v90 offset:32768
	ds_read_b128 v[198:201], v93 offset:4096
	ds_read_b128 v[202:205], v90 offset:36864
	s_waitcnt lgkmcnt(6)
	v_mfma_f32_32x32x16_bf16 v[50:65], v[162:165], v[166:169], v[50:65]
	s_waitcnt lgkmcnt(4)
	v_mfma_f32_32x32x16_bf16 v[34:49], v[162:165], v[186:189], v[34:49]
	v_mfma_f32_32x32x16_bf16 v[18:33], v[182:185], v[166:169], v[18:33]
	v_mfma_f32_32x32x16_bf16 v[2:17], v[182:185], v[186:189], v[2:17]
	ds_read_b128 v[162:165], v89
	ds_read_b128 v[166:169], v89 offset:4096
	ds_read_b128 v[182:185], v88 offset:32768
	ds_read_b128 v[186:189], v88 offset:36864
	s_waitcnt lgkmcnt(6)
	v_mfma_f32_32x32x16_bf16 v[50:65], v[190:193], v[194:197], v[50:65]
	s_waitcnt lgkmcnt(4)
	v_mfma_f32_32x32x16_bf16 v[34:49], v[190:193], v[202:205], v[34:49]
	v_mfma_f32_32x32x16_bf16 v[18:33], v[198:201], v[194:197], v[18:33]
	v_mfma_f32_32x32x16_bf16 v[2:17], v[198:201], v[202:205], v[2:17]
	ds_read_b128 v[190:193], v87
	ds_read_b128 v[194:197], v87 offset:4096
	ds_read_b128 v[198:201], v86 offset:32768
	ds_read_b128 v[202:205], v86 offset:36864
	v_lshl_add_u64 v[66:67], v[66:67], 0, s[98:99]
	v_lshl_add_u64 v[70:71], v[70:71], 0, s[98:99]
	v_lshl_add_u64 v[74:75], v[74:75], 0, s[98:99]
	v_lshl_add_u64 v[78:79], v[78:79], 0, s[98:99]
	v_lshl_add_u64 v[68:69], v[68:69], 0, s[98:99]
	v_lshl_add_u64 v[72:73], v[72:73], 0, s[98:99]
	v_lshl_add_u64 v[76:77], v[76:77], 0, s[98:99]
	v_lshl_add_u64 v[80:81], v[80:81], 0, s[98:99]
	s_waitcnt vmcnt(0)
	s_waitcnt lgkmcnt(0)
	s_barrier
	s_add_u32 m0, s32, 0x0
	v_mfma_f32_32x32x16_bf16 v[50:65], v[162:165], v[182:185], v[50:65]
	global_load_lds_dwordx4 v[66:67], off
	s_add_u32 m0, s32, 0x1000
	v_mfma_f32_32x32x16_bf16 v[34:49], v[162:165], v[186:189], v[34:49]
	global_load_lds_dwordx4 v[70:71], off
	s_add_u32 m0, s32, 0x2000
	v_mfma_f32_32x32x16_bf16 v[18:33], v[166:169], v[182:185], v[18:33]
	global_load_lds_dwordx4 v[74:75], off
	s_add_u32 m0, s32, 0x3000
	v_mfma_f32_32x32x16_bf16 v[2:17], v[166:169], v[186:189], v[2:17]
	global_load_lds_dwordx4 v[78:79], off
	s_add_u32 m0, s32, 0x8000
	v_mfma_f32_32x32x16_bf16 v[50:65], v[190:193], v[198:201], v[50:65]
	global_load_lds_dwordx4 v[68:69], off
	s_add_u32 m0, s32, 0x9000
	v_mfma_f32_32x32x16_bf16 v[34:49], v[190:193], v[202:205], v[34:49]
	global_load_lds_dwordx4 v[72:73], off
	s_add_u32 m0, s32, 0xa000
	v_mfma_f32_32x32x16_bf16 v[18:33], v[194:197], v[198:201], v[18:33]
	global_load_lds_dwordx4 v[76:77], off
	s_add_u32 m0, s32, 0xb000
	v_mfma_f32_32x32x16_bf16 v[2:17], v[194:197], v[202:205], v[2:17]
	global_load_lds_dwordx4 v[80:81], off
	ds_read_b128 v[162:165], v91 offset:16384
	ds_read_b128 v[166:169], v92 offset:49152
	ds_read_b128 v[182:185], v91 offset:20480
	ds_read_b128 v[186:189], v92 offset:53248
	ds_read_b128 v[190:193], v93 offset:16384
	ds_read_b128 v[194:197], v90 offset:49152
	ds_read_b128 v[198:201], v93 offset:20480
	ds_read_b128 v[202:205], v90 offset:53248
	s_waitcnt lgkmcnt(6)
	v_mfma_f32_32x32x16_bf16 v[50:65], v[162:165], v[166:169], v[50:65]
	s_waitcnt lgkmcnt(4)
	v_mfma_f32_32x32x16_bf16 v[34:49], v[162:165], v[186:189], v[34:49]
	v_mfma_f32_32x32x16_bf16 v[18:33], v[182:185], v[166:169], v[18:33]
	v_mfma_f32_32x32x16_bf16 v[2:17], v[182:185], v[186:189], v[2:17]
	ds_read_b128 v[162:165], v89 offset:16384
	ds_read_b128 v[166:169], v89 offset:20480
	ds_read_b128 v[182:185], v88 offset:49152
	ds_read_b128 v[186:189], v88 offset:53248
	s_waitcnt lgkmcnt(6)
	v_mfma_f32_32x32x16_bf16 v[50:65], v[190:193], v[194:197], v[50:65]
	s_waitcnt lgkmcnt(4)
	v_mfma_f32_32x32x16_bf16 v[34:49], v[190:193], v[202:205], v[34:49]
	v_mfma_f32_32x32x16_bf16 v[18:33], v[198:201], v[194:197], v[18:33]
	v_mfma_f32_32x32x16_bf16 v[2:17], v[198:201], v[202:205], v[2:17]
	ds_read_b128 v[190:193], v87 offset:16384
	ds_read_b128 v[194:197], v87 offset:20480
	ds_read_b128 v[198:201], v86 offset:49152
	ds_read_b128 v[202:205], v86 offset:53248
	v_lshl_add_u64 v[66:67], v[66:67], 0, s[98:99]
	v_lshl_add_u64 v[70:71], v[70:71], 0, s[98:99]
	v_lshl_add_u64 v[74:75], v[74:75], 0, s[98:99]
	v_lshl_add_u64 v[78:79], v[78:79], 0, s[98:99]
	v_lshl_add_u64 v[68:69], v[68:69], 0, s[98:99]
	v_lshl_add_u64 v[72:73], v[72:73], 0, s[98:99]
	v_lshl_add_u64 v[76:77], v[76:77], 0, s[98:99]
	v_lshl_add_u64 v[80:81], v[80:81], 0, s[98:99]
	s_waitcnt vmcnt(0)
	s_waitcnt lgkmcnt(0)
	s_barrier
	s_add_u32 m0, s32, 0x4000
	v_mfma_f32_32x32x16_bf16 v[50:65], v[162:165], v[182:185], v[50:65]
	global_load_lds_dwordx4 v[66:67], off
	s_add_u32 m0, s32, 0x5000
	v_mfma_f32_32x32x16_bf16 v[34:49], v[162:165], v[186:189], v[34:49]
	global_load_lds_dwordx4 v[70:71], off
	s_add_u32 m0, s32, 0x6000
	v_mfma_f32_32x32x16_bf16 v[18:33], v[166:169], v[182:185], v[18:33]
	global_load_lds_dwordx4 v[74:75], off
	s_add_u32 m0, s32, 0x7000
	v_mfma_f32_32x32x16_bf16 v[2:17], v[166:169], v[186:189], v[2:17]
	global_load_lds_dwordx4 v[78:79], off
	s_add_u32 m0, s32, 0xc000
	v_mfma_f32_32x32x16_bf16 v[50:65], v[190:193], v[198:201], v[50:65]
	global_load_lds_dwordx4 v[68:69], off
	s_add_u32 m0, s32, 0xd000
	v_mfma_f32_32x32x16_bf16 v[34:49], v[190:193], v[202:205], v[34:49]
	global_load_lds_dwordx4 v[72:73], off
	s_add_u32 m0, s32, 0xe000
	v_mfma_f32_32x32x16_bf16 v[18:33], v[194:197], v[198:201], v[18:33]
	global_load_lds_dwordx4 v[76:77], off
	s_add_u32 m0, s32, 0xf000
	v_mfma_f32_32x32x16_bf16 v[2:17], v[194:197], v[202:205], v[2:17]
	global_load_lds_dwordx4 v[80:81], off
	ds_read_b128 v[162:165], v91
	ds_read_b128 v[166:169], v92 offset:32768
	ds_read_b128 v[182:185], v91 offset:4096
	ds_read_b128 v[186:189], v92 offset:36864
	ds_read_b128 v[190:193], v93
	ds_read_b128 v[194:197], v90 offset:32768
	ds_read_b128 v[198:201], v93 offset:4096
	ds_read_b128 v[202:205], v90 offset:36864
	s_waitcnt lgkmcnt(6)
	v_mfma_f32_32x32x16_bf16 v[50:65], v[162:165], v[166:169], v[50:65]
	s_waitcnt lgkmcnt(4)
	v_mfma_f32_32x32x16_bf16 v[34:49], v[162:165], v[186:189], v[34:49]
	v_mfma_f32_32x32x16_bf16 v[18:33], v[182:185], v[166:169], v[18:33]
	v_mfma_f32_32x32x16_bf16 v[2:17], v[182:185], v[186:189], v[2:17]
	ds_read_b128 v[162:165], v89
	ds_read_b128 v[166:169], v89 offset:4096
	ds_read_b128 v[182:185], v88 offset:32768
	ds_read_b128 v[186:189], v88 offset:36864
	s_waitcnt lgkmcnt(6)
	v_mfma_f32_32x32x16_bf16 v[50:65], v[190:193], v[194:197], v[50:65]
	s_waitcnt lgkmcnt(4)
	v_mfma_f32_32x32x16_bf16 v[34:49], v[190:193], v[202:205], v[34:49]
	v_mfma_f32_32x32x16_bf16 v[18:33], v[198:201], v[194:197], v[18:33]
	v_mfma_f32_32x32x16_bf16 v[2:17], v[198:201], v[202:205], v[2:17]
	ds_read_b128 v[190:193], v87
	ds_read_b128 v[194:197], v87 offset:4096
	ds_read_b128 v[198:201], v86 offset:32768
	ds_read_b128 v[202:205], v86 offset:36864
	v_lshl_add_u64 v[66:67], v[66:67], 0, s[98:99]
	v_lshl_add_u64 v[70:71], v[70:71], 0, s[98:99]
	v_lshl_add_u64 v[74:75], v[74:75], 0, s[98:99]
	v_lshl_add_u64 v[78:79], v[78:79], 0, s[98:99]
	v_lshl_add_u64 v[68:69], v[68:69], 0, s[98:99]
	v_lshl_add_u64 v[72:73], v[72:73], 0, s[98:99]
	v_lshl_add_u64 v[76:77], v[76:77], 0, s[98:99]
	v_lshl_add_u64 v[80:81], v[80:81], 0, s[98:99]
	s_waitcnt vmcnt(0)
	s_waitcnt lgkmcnt(0)
	s_barrier
	s_add_u32 m0, s32, 0x0
	v_mfma_f32_32x32x16_bf16 v[50:65], v[162:165], v[182:185], v[50:65]
	global_load_lds_dwordx4 v[66:67], off
	s_add_u32 m0, s32, 0x1000
	v_mfma_f32_32x32x16_bf16 v[34:49], v[162:165], v[186:189], v[34:49]
	global_load_lds_dwordx4 v[70:71], off
	s_add_u32 m0, s32, 0x2000
	v_mfma_f32_32x32x16_bf16 v[18:33], v[166:169], v[182:185], v[18:33]
	global_load_lds_dwordx4 v[74:75], off
	s_add_u32 m0, s32, 0x3000
	v_mfma_f32_32x32x16_bf16 v[2:17], v[166:169], v[186:189], v[2:17]
	global_load_lds_dwordx4 v[78:79], off
	s_add_u32 m0, s32, 0x8000
	v_mfma_f32_32x32x16_bf16 v[50:65], v[190:193], v[198:201], v[50:65]
	global_load_lds_dwordx4 v[68:69], off
	s_add_u32 m0, s32, 0x9000
	v_mfma_f32_32x32x16_bf16 v[34:49], v[190:193], v[202:205], v[34:49]
	global_load_lds_dwordx4 v[72:73], off
	s_add_u32 m0, s32, 0xa000
	v_mfma_f32_32x32x16_bf16 v[18:33], v[194:197], v[198:201], v[18:33]
	global_load_lds_dwordx4 v[76:77], off
	s_add_u32 m0, s32, 0xb000
	v_mfma_f32_32x32x16_bf16 v[2:17], v[194:197], v[202:205], v[2:17]
	global_load_lds_dwordx4 v[80:81], off
	ds_read_b128 v[162:165], v91 offset:16384
	ds_read_b128 v[166:169], v92 offset:49152
	ds_read_b128 v[182:185], v91 offset:20480
	ds_read_b128 v[186:189], v92 offset:53248
	ds_read_b128 v[190:193], v93 offset:16384
	ds_read_b128 v[194:197], v90 offset:49152
	ds_read_b128 v[198:201], v93 offset:20480
	ds_read_b128 v[202:205], v90 offset:53248
	s_waitcnt lgkmcnt(6)
	v_mfma_f32_32x32x16_bf16 v[50:65], v[162:165], v[166:169], v[50:65]
	s_waitcnt lgkmcnt(4)
	v_mfma_f32_32x32x16_bf16 v[34:49], v[162:165], v[186:189], v[34:49]
	v_mfma_f32_32x32x16_bf16 v[18:33], v[182:185], v[166:169], v[18:33]
	v_mfma_f32_32x32x16_bf16 v[2:17], v[182:185], v[186:189], v[2:17]
	ds_read_b128 v[162:165], v89 offset:16384
	ds_read_b128 v[166:169], v89 offset:20480
	ds_read_b128 v[182:185], v88 offset:49152
	ds_read_b128 v[186:189], v88 offset:53248
	s_waitcnt lgkmcnt(6)
	v_mfma_f32_32x32x16_bf16 v[50:65], v[190:193], v[194:197], v[50:65]
	s_waitcnt lgkmcnt(4)
	v_mfma_f32_32x32x16_bf16 v[34:49], v[190:193], v[202:205], v[34:49]
	v_mfma_f32_32x32x16_bf16 v[18:33], v[198:201], v[194:197], v[18:33]
	v_mfma_f32_32x32x16_bf16 v[2:17], v[198:201], v[202:205], v[2:17]
	ds_read_b128 v[190:193], v87 offset:16384
	ds_read_b128 v[194:197], v87 offset:20480
	ds_read_b128 v[198:201], v86 offset:49152
	ds_read_b128 v[202:205], v86 offset:53248
	v_lshl_add_u64 v[66:67], v[66:67], 0, s[98:99]
	v_lshl_add_u64 v[70:71], v[70:71], 0, s[98:99]
	v_lshl_add_u64 v[74:75], v[74:75], 0, s[98:99]
	v_lshl_add_u64 v[78:79], v[78:79], 0, s[98:99]
	v_lshl_add_u64 v[68:69], v[68:69], 0, s[98:99]
	v_lshl_add_u64 v[72:73], v[72:73], 0, s[98:99]
	v_lshl_add_u64 v[76:77], v[76:77], 0, s[98:99]
	v_lshl_add_u64 v[80:81], v[80:81], 0, s[98:99]
	s_waitcnt vmcnt(0)
	s_waitcnt lgkmcnt(0)
	s_barrier
	s_add_u32 m0, s32, 0x4000
	v_mfma_f32_32x32x16_bf16 v[50:65], v[162:165], v[182:185], v[50:65]
	global_load_lds_dwordx4 v[66:67], off
	s_add_u32 m0, s32, 0x5000
	v_mfma_f32_32x32x16_bf16 v[34:49], v[162:165], v[186:189], v[34:49]
	global_load_lds_dwordx4 v[70:71], off
	s_add_u32 m0, s32, 0x6000
	v_mfma_f32_32x32x16_bf16 v[18:33], v[166:169], v[182:185], v[18:33]
	global_load_lds_dwordx4 v[74:75], off
	s_add_u32 m0, s32, 0x7000
	v_mfma_f32_32x32x16_bf16 v[2:17], v[166:169], v[186:189], v[2:17]
	global_load_lds_dwordx4 v[78:79], off
	s_add_u32 m0, s32, 0xc000
	v_mfma_f32_32x32x16_bf16 v[50:65], v[190:193], v[198:201], v[50:65]
	global_load_lds_dwordx4 v[68:69], off
	s_add_u32 m0, s32, 0xd000
	v_mfma_f32_32x32x16_bf16 v[34:49], v[190:193], v[202:205], v[34:49]
	global_load_lds_dwordx4 v[72:73], off
	s_add_u32 m0, s32, 0xe000
	v_mfma_f32_32x32x16_bf16 v[18:33], v[194:197], v[198:201], v[18:33]
	global_load_lds_dwordx4 v[76:77], off
	s_add_u32 m0, s32, 0xf000
	v_mfma_f32_32x32x16_bf16 v[2:17], v[194:197], v[202:205], v[2:17]
	global_load_lds_dwordx4 v[80:81], off
	ds_read_b128 v[162:165], v91
	ds_read_b128 v[166:169], v92 offset:32768
	ds_read_b128 v[182:185], v91 offset:4096
	ds_read_b128 v[186:189], v92 offset:36864
	ds_read_b128 v[190:193], v93
	ds_read_b128 v[194:197], v90 offset:32768
	ds_read_b128 v[198:201], v93 offset:4096
	ds_read_b128 v[202:205], v90 offset:36864
	s_waitcnt lgkmcnt(6)
	v_mfma_f32_32x32x16_bf16 v[50:65], v[162:165], v[166:169], v[50:65]
	s_waitcnt lgkmcnt(4)
	v_mfma_f32_32x32x16_bf16 v[34:49], v[162:165], v[186:189], v[34:49]
	v_mfma_f32_32x32x16_bf16 v[18:33], v[182:185], v[166:169], v[18:33]
	v_mfma_f32_32x32x16_bf16 v[2:17], v[182:185], v[186:189], v[2:17]
	ds_read_b128 v[162:165], v89
	ds_read_b128 v[166:169], v89 offset:4096
	ds_read_b128 v[182:185], v88 offset:32768
	ds_read_b128 v[186:189], v88 offset:36864
	s_waitcnt lgkmcnt(6)
	v_mfma_f32_32x32x16_bf16 v[50:65], v[190:193], v[194:197], v[50:65]
	s_waitcnt lgkmcnt(4)
	v_mfma_f32_32x32x16_bf16 v[34:49], v[190:193], v[202:205], v[34:49]
	v_mfma_f32_32x32x16_bf16 v[18:33], v[198:201], v[194:197], v[18:33]
	v_mfma_f32_32x32x16_bf16 v[2:17], v[198:201], v[202:205], v[2:17]
	ds_read_b128 v[190:193], v87
	ds_read_b128 v[194:197], v87 offset:4096
	ds_read_b128 v[198:201], v86 offset:32768
	ds_read_b128 v[202:205], v86 offset:36864
	v_lshl_add_u64 v[66:67], v[66:67], 0, s[98:99]
	v_lshl_add_u64 v[70:71], v[70:71], 0, s[98:99]
	v_lshl_add_u64 v[74:75], v[74:75], 0, s[98:99]
	v_lshl_add_u64 v[78:79], v[78:79], 0, s[98:99]
	v_lshl_add_u64 v[68:69], v[68:69], 0, s[98:99]
	v_lshl_add_u64 v[72:73], v[72:73], 0, s[98:99]
	v_lshl_add_u64 v[76:77], v[76:77], 0, s[98:99]
	v_lshl_add_u64 v[80:81], v[80:81], 0, s[98:99]
	s_waitcnt vmcnt(0)
	s_waitcnt lgkmcnt(0)
	s_barrier
	s_add_u32 m0, s32, 0x0
	v_mfma_f32_32x32x16_bf16 v[50:65], v[162:165], v[182:185], v[50:65]
	global_load_lds_dwordx4 v[66:67], off
	s_add_u32 m0, s32, 0x1000
	v_mfma_f32_32x32x16_bf16 v[34:49], v[162:165], v[186:189], v[34:49]
	global_load_lds_dwordx4 v[70:71], off
	s_add_u32 m0, s32, 0x2000
	v_mfma_f32_32x32x16_bf16 v[18:33], v[166:169], v[182:185], v[18:33]
	global_load_lds_dwordx4 v[74:75], off
	s_add_u32 m0, s32, 0x3000
	v_mfma_f32_32x32x16_bf16 v[2:17], v[166:169], v[186:189], v[2:17]
	global_load_lds_dwordx4 v[78:79], off
	s_add_u32 m0, s32, 0x8000
	v_mfma_f32_32x32x16_bf16 v[50:65], v[190:193], v[198:201], v[50:65]
	global_load_lds_dwordx4 v[68:69], off
	s_add_u32 m0, s32, 0x9000
	v_mfma_f32_32x32x16_bf16 v[34:49], v[190:193], v[202:205], v[34:49]
	global_load_lds_dwordx4 v[72:73], off
	s_add_u32 m0, s32, 0xa000
	v_mfma_f32_32x32x16_bf16 v[18:33], v[194:197], v[198:201], v[18:33]
	global_load_lds_dwordx4 v[76:77], off
	s_add_u32 m0, s32, 0xb000
	v_mfma_f32_32x32x16_bf16 v[2:17], v[194:197], v[202:205], v[2:17]
	global_load_lds_dwordx4 v[80:81], off
	ds_read_b128 v[162:165], v91 offset:16384
	ds_read_b128 v[166:169], v92 offset:49152
	ds_read_b128 v[182:185], v91 offset:20480
	ds_read_b128 v[186:189], v92 offset:53248
	ds_read_b128 v[190:193], v93 offset:16384
	ds_read_b128 v[194:197], v90 offset:49152
	ds_read_b128 v[198:201], v93 offset:20480
	ds_read_b128 v[202:205], v90 offset:53248
	s_waitcnt lgkmcnt(6)
	v_mfma_f32_32x32x16_bf16 v[50:65], v[162:165], v[166:169], v[50:65]
	s_waitcnt lgkmcnt(4)
	v_mfma_f32_32x32x16_bf16 v[34:49], v[162:165], v[186:189], v[34:49]
	v_mfma_f32_32x32x16_bf16 v[18:33], v[182:185], v[166:169], v[18:33]
	v_mfma_f32_32x32x16_bf16 v[2:17], v[182:185], v[186:189], v[2:17]
	ds_read_b128 v[162:165], v89 offset:16384
	ds_read_b128 v[166:169], v89 offset:20480
	ds_read_b128 v[182:185], v88 offset:49152
	ds_read_b128 v[186:189], v88 offset:53248
	s_waitcnt lgkmcnt(6)
	v_mfma_f32_32x32x16_bf16 v[50:65], v[190:193], v[194:197], v[50:65]
	s_waitcnt lgkmcnt(4)
	v_mfma_f32_32x32x16_bf16 v[34:49], v[190:193], v[202:205], v[34:49]
	v_mfma_f32_32x32x16_bf16 v[18:33], v[198:201], v[194:197], v[18:33]
	v_mfma_f32_32x32x16_bf16 v[2:17], v[198:201], v[202:205], v[2:17]
	ds_read_b128 v[190:193], v87 offset:16384
	ds_read_b128 v[194:197], v87 offset:20480
	ds_read_b128 v[198:201], v86 offset:49152
	ds_read_b128 v[202:205], v86 offset:53248
	v_lshl_add_u64 v[66:67], v[66:67], 0, s[98:99]
	v_lshl_add_u64 v[70:71], v[70:71], 0, s[98:99]
	v_lshl_add_u64 v[74:75], v[74:75], 0, s[98:99]
	v_lshl_add_u64 v[78:79], v[78:79], 0, s[98:99]
	v_lshl_add_u64 v[68:69], v[68:69], 0, s[98:99]
	v_lshl_add_u64 v[72:73], v[72:73], 0, s[98:99]
	v_lshl_add_u64 v[76:77], v[76:77], 0, s[98:99]
	v_lshl_add_u64 v[80:81], v[80:81], 0, s[98:99]
	s_waitcnt vmcnt(0)
	s_waitcnt lgkmcnt(0)
	s_barrier
	s_add_u32 m0, s32, 0x4000
	v_mfma_f32_32x32x16_bf16 v[50:65], v[162:165], v[182:185], v[50:65]
	global_load_lds_dwordx4 v[66:67], off
	s_add_u32 m0, s32, 0x5000
	v_mfma_f32_32x32x16_bf16 v[34:49], v[162:165], v[186:189], v[34:49]
	global_load_lds_dwordx4 v[70:71], off
	s_add_u32 m0, s32, 0x6000
	v_mfma_f32_32x32x16_bf16 v[18:33], v[166:169], v[182:185], v[18:33]
	global_load_lds_dwordx4 v[74:75], off
	s_add_u32 m0, s32, 0x7000
	v_mfma_f32_32x32x16_bf16 v[2:17], v[166:169], v[186:189], v[2:17]
	global_load_lds_dwordx4 v[78:79], off
	s_add_u32 m0, s32, 0xc000
	v_mfma_f32_32x32x16_bf16 v[50:65], v[190:193], v[198:201], v[50:65]
	global_load_lds_dwordx4 v[68:69], off
	s_add_u32 m0, s32, 0xd000
	v_mfma_f32_32x32x16_bf16 v[34:49], v[190:193], v[202:205], v[34:49]
	global_load_lds_dwordx4 v[72:73], off
	s_add_u32 m0, s32, 0xe000
	v_mfma_f32_32x32x16_bf16 v[18:33], v[194:197], v[198:201], v[18:33]
	global_load_lds_dwordx4 v[76:77], off
	s_add_u32 m0, s32, 0xf000
	v_mfma_f32_32x32x16_bf16 v[2:17], v[194:197], v[202:205], v[2:17]
	global_load_lds_dwordx4 v[80:81], off
	ds_read_b128 v[162:165], v91
	ds_read_b128 v[166:169], v92 offset:32768
	ds_read_b128 v[182:185], v91 offset:4096
	ds_read_b128 v[186:189], v92 offset:36864
	ds_read_b128 v[190:193], v93
	ds_read_b128 v[194:197], v90 offset:32768
	ds_read_b128 v[198:201], v93 offset:4096
	ds_read_b128 v[202:205], v90 offset:36864
	s_waitcnt lgkmcnt(6)
	v_mfma_f32_32x32x16_bf16 v[50:65], v[162:165], v[166:169], v[50:65]
	s_waitcnt lgkmcnt(4)
	v_mfma_f32_32x32x16_bf16 v[34:49], v[162:165], v[186:189], v[34:49]
	v_mfma_f32_32x32x16_bf16 v[18:33], v[182:185], v[166:169], v[18:33]
	v_mfma_f32_32x32x16_bf16 v[2:17], v[182:185], v[186:189], v[2:17]
	ds_read_b128 v[162:165], v89
	ds_read_b128 v[166:169], v89 offset:4096
	ds_read_b128 v[182:185], v88 offset:32768
	ds_read_b128 v[186:189], v88 offset:36864
	s_waitcnt lgkmcnt(6)
	v_mfma_f32_32x32x16_bf16 v[50:65], v[190:193], v[194:197], v[50:65]
	s_waitcnt lgkmcnt(4)
	v_mfma_f32_32x32x16_bf16 v[34:49], v[190:193], v[202:205], v[34:49]
	v_mfma_f32_32x32x16_bf16 v[18:33], v[198:201], v[194:197], v[18:33]
	v_mfma_f32_32x32x16_bf16 v[2:17], v[198:201], v[202:205], v[2:17]
	ds_read_b128 v[190:193], v87
	ds_read_b128 v[194:197], v87 offset:4096
	ds_read_b128 v[198:201], v86 offset:32768
	ds_read_b128 v[202:205], v86 offset:36864
	v_lshl_add_u64 v[66:67], v[66:67], 0, s[98:99]
	v_lshl_add_u64 v[70:71], v[70:71], 0, s[98:99]
	v_lshl_add_u64 v[74:75], v[74:75], 0, s[98:99]
	v_lshl_add_u64 v[78:79], v[78:79], 0, s[98:99]
	v_lshl_add_u64 v[68:69], v[68:69], 0, s[98:99]
	v_lshl_add_u64 v[72:73], v[72:73], 0, s[98:99]
	v_lshl_add_u64 v[76:77], v[76:77], 0, s[98:99]
	v_lshl_add_u64 v[80:81], v[80:81], 0, s[98:99]
	s_waitcnt vmcnt(0)
	s_waitcnt lgkmcnt(0)
	s_barrier
	s_add_u32 m0, s32, 0x0
	v_mfma_f32_32x32x16_bf16 v[50:65], v[162:165], v[182:185], v[50:65]
	global_load_lds_dwordx4 v[66:67], off
	s_add_u32 m0, s32, 0x1000
	v_mfma_f32_32x32x16_bf16 v[34:49], v[162:165], v[186:189], v[34:49]
	global_load_lds_dwordx4 v[70:71], off
	s_add_u32 m0, s32, 0x2000
	v_mfma_f32_32x32x16_bf16 v[18:33], v[166:169], v[182:185], v[18:33]
	global_load_lds_dwordx4 v[74:75], off
	s_add_u32 m0, s32, 0x3000
	v_mfma_f32_32x32x16_bf16 v[2:17], v[166:169], v[186:189], v[2:17]
	global_load_lds_dwordx4 v[78:79], off
	s_add_u32 m0, s32, 0x8000
	v_mfma_f32_32x32x16_bf16 v[50:65], v[190:193], v[198:201], v[50:65]
	global_load_lds_dwordx4 v[68:69], off
	s_add_u32 m0, s32, 0x9000
	v_mfma_f32_32x32x16_bf16 v[34:49], v[190:193], v[202:205], v[34:49]
	global_load_lds_dwordx4 v[72:73], off
	s_add_u32 m0, s32, 0xa000
	v_mfma_f32_32x32x16_bf16 v[18:33], v[194:197], v[198:201], v[18:33]
	global_load_lds_dwordx4 v[76:77], off
	s_add_u32 m0, s32, 0xb000
	v_mfma_f32_32x32x16_bf16 v[2:17], v[194:197], v[202:205], v[2:17]
	global_load_lds_dwordx4 v[80:81], off
	ds_read_b128 v[162:165], v91 offset:16384
	ds_read_b128 v[166:169], v92 offset:49152
	ds_read_b128 v[182:185], v91 offset:20480
	ds_read_b128 v[186:189], v92 offset:53248
	ds_read_b128 v[190:193], v93 offset:16384
	ds_read_b128 v[194:197], v90 offset:49152
	ds_read_b128 v[198:201], v93 offset:20480
	ds_read_b128 v[202:205], v90 offset:53248
	s_waitcnt lgkmcnt(6)
	v_mfma_f32_32x32x16_bf16 v[50:65], v[162:165], v[166:169], v[50:65]
	s_waitcnt lgkmcnt(4)
	v_mfma_f32_32x32x16_bf16 v[34:49], v[162:165], v[186:189], v[34:49]
	v_mfma_f32_32x32x16_bf16 v[18:33], v[182:185], v[166:169], v[18:33]
	v_mfma_f32_32x32x16_bf16 v[2:17], v[182:185], v[186:189], v[2:17]
	ds_read_b128 v[162:165], v89 offset:16384
	ds_read_b128 v[166:169], v89 offset:20480
	ds_read_b128 v[182:185], v88 offset:49152
	ds_read_b128 v[186:189], v88 offset:53248
	s_waitcnt lgkmcnt(6)
	v_mfma_f32_32x32x16_bf16 v[50:65], v[190:193], v[194:197], v[50:65]
	s_waitcnt lgkmcnt(4)
	v_mfma_f32_32x32x16_bf16 v[34:49], v[190:193], v[202:205], v[34:49]
	v_mfma_f32_32x32x16_bf16 v[18:33], v[198:201], v[194:197], v[18:33]
	v_mfma_f32_32x32x16_bf16 v[2:17], v[198:201], v[202:205], v[2:17]
	ds_read_b128 v[190:193], v87 offset:16384
	ds_read_b128 v[194:197], v87 offset:20480
	ds_read_b128 v[198:201], v86 offset:49152
	ds_read_b128 v[202:205], v86 offset:53248
	v_lshl_add_u64 v[66:67], v[66:67], 0, s[98:99]
	v_lshl_add_u64 v[70:71], v[70:71], 0, s[98:99]
	v_lshl_add_u64 v[74:75], v[74:75], 0, s[98:99]
	v_lshl_add_u64 v[78:79], v[78:79], 0, s[98:99]
	v_lshl_add_u64 v[68:69], v[68:69], 0, s[98:99]
	v_lshl_add_u64 v[72:73], v[72:73], 0, s[98:99]
	v_lshl_add_u64 v[76:77], v[76:77], 0, s[98:99]
	v_lshl_add_u64 v[80:81], v[80:81], 0, s[98:99]
	s_waitcnt vmcnt(0)
	s_waitcnt lgkmcnt(0)
	s_barrier
	s_add_u32 m0, s32, 0x4000
	v_mfma_f32_32x32x16_bf16 v[50:65], v[162:165], v[182:185], v[50:65]
	global_load_lds_dwordx4 v[66:67], off
	s_add_u32 m0, s32, 0x5000
	v_mfma_f32_32x32x16_bf16 v[34:49], v[162:165], v[186:189], v[34:49]
	global_load_lds_dwordx4 v[70:71], off
	s_add_u32 m0, s32, 0x6000
	v_mfma_f32_32x32x16_bf16 v[18:33], v[166:169], v[182:185], v[18:33]
	global_load_lds_dwordx4 v[74:75], off
	s_add_u32 m0, s32, 0x7000
	v_mfma_f32_32x32x16_bf16 v[2:17], v[166:169], v[186:189], v[2:17]
	global_load_lds_dwordx4 v[78:79], off
	s_add_u32 m0, s32, 0xc000
	v_mfma_f32_32x32x16_bf16 v[50:65], v[190:193], v[198:201], v[50:65]
	global_load_lds_dwordx4 v[68:69], off
	s_add_u32 m0, s32, 0xd000
	v_mfma_f32_32x32x16_bf16 v[34:49], v[190:193], v[202:205], v[34:49]
	global_load_lds_dwordx4 v[72:73], off
	s_add_u32 m0, s32, 0xe000
	v_mfma_f32_32x32x16_bf16 v[18:33], v[194:197], v[198:201], v[18:33]
	global_load_lds_dwordx4 v[76:77], off
	s_add_u32 m0, s32, 0xf000
	v_mfma_f32_32x32x16_bf16 v[2:17], v[194:197], v[202:205], v[2:17]
	global_load_lds_dwordx4 v[80:81], off
	ds_read_b128 v[162:165], v91
	ds_read_b128 v[166:169], v92 offset:32768
	ds_read_b128 v[182:185], v91 offset:4096
	ds_read_b128 v[186:189], v92 offset:36864
	ds_read_b128 v[190:193], v93
	ds_read_b128 v[194:197], v90 offset:32768
	ds_read_b128 v[198:201], v93 offset:4096
	ds_read_b128 v[202:205], v90 offset:36864
	s_waitcnt lgkmcnt(6)
	v_mfma_f32_32x32x16_bf16 v[50:65], v[162:165], v[166:169], v[50:65]
	s_waitcnt lgkmcnt(4)
	v_mfma_f32_32x32x16_bf16 v[34:49], v[162:165], v[186:189], v[34:49]
	v_mfma_f32_32x32x16_bf16 v[18:33], v[182:185], v[166:169], v[18:33]
	v_mfma_f32_32x32x16_bf16 v[2:17], v[182:185], v[186:189], v[2:17]
	ds_read_b128 v[162:165], v89
	ds_read_b128 v[166:169], v89 offset:4096
	ds_read_b128 v[182:185], v88 offset:32768
	ds_read_b128 v[186:189], v88 offset:36864
	s_waitcnt lgkmcnt(6)
	v_mfma_f32_32x32x16_bf16 v[50:65], v[190:193], v[194:197], v[50:65]
	s_waitcnt lgkmcnt(4)
	v_mfma_f32_32x32x16_bf16 v[34:49], v[190:193], v[202:205], v[34:49]
	v_mfma_f32_32x32x16_bf16 v[18:33], v[198:201], v[194:197], v[18:33]
	v_mfma_f32_32x32x16_bf16 v[2:17], v[198:201], v[202:205], v[2:17]
	ds_read_b128 v[190:193], v87
	ds_read_b128 v[194:197], v87 offset:4096
	ds_read_b128 v[198:201], v86 offset:32768
	ds_read_b128 v[202:205], v86 offset:36864
	v_lshl_add_u64 v[66:67], v[66:67], 0, s[98:99]
	v_lshl_add_u64 v[70:71], v[70:71], 0, s[98:99]
	v_lshl_add_u64 v[74:75], v[74:75], 0, s[98:99]
	v_lshl_add_u64 v[78:79], v[78:79], 0, s[98:99]
	v_lshl_add_u64 v[68:69], v[68:69], 0, s[98:99]
	v_lshl_add_u64 v[72:73], v[72:73], 0, s[98:99]
	v_lshl_add_u64 v[76:77], v[76:77], 0, s[98:99]
	v_lshl_add_u64 v[80:81], v[80:81], 0, s[98:99]
	s_waitcnt vmcnt(0)
	s_waitcnt lgkmcnt(0)
	s_barrier
	s_add_u32 m0, s32, 0x0
	v_mfma_f32_32x32x16_bf16 v[50:65], v[162:165], v[182:185], v[50:65]
	global_load_lds_dwordx4 v[66:67], off
	s_add_u32 m0, s32, 0x1000
	v_mfma_f32_32x32x16_bf16 v[34:49], v[162:165], v[186:189], v[34:49]
	global_load_lds_dwordx4 v[70:71], off
	s_add_u32 m0, s32, 0x2000
	v_mfma_f32_32x32x16_bf16 v[18:33], v[166:169], v[182:185], v[18:33]
	global_load_lds_dwordx4 v[74:75], off
	s_add_u32 m0, s32, 0x3000
	v_mfma_f32_32x32x16_bf16 v[2:17], v[166:169], v[186:189], v[2:17]
	global_load_lds_dwordx4 v[78:79], off
	s_add_u32 m0, s32, 0x8000
	v_mfma_f32_32x32x16_bf16 v[50:65], v[190:193], v[198:201], v[50:65]
	global_load_lds_dwordx4 v[68:69], off
	s_add_u32 m0, s32, 0x9000
	v_mfma_f32_32x32x16_bf16 v[34:49], v[190:193], v[202:205], v[34:49]
	global_load_lds_dwordx4 v[72:73], off
	s_add_u32 m0, s32, 0xa000
	v_mfma_f32_32x32x16_bf16 v[18:33], v[194:197], v[198:201], v[18:33]
	global_load_lds_dwordx4 v[76:77], off
	s_add_u32 m0, s32, 0xb000
	v_mfma_f32_32x32x16_bf16 v[2:17], v[194:197], v[202:205], v[2:17]
	global_load_lds_dwordx4 v[80:81], off
	ds_read_b128 v[162:165], v91 offset:16384
	ds_read_b128 v[166:169], v92 offset:49152
	ds_read_b128 v[182:185], v91 offset:20480
	ds_read_b128 v[186:189], v92 offset:53248
	ds_read_b128 v[190:193], v93 offset:16384
	ds_read_b128 v[194:197], v90 offset:49152
	ds_read_b128 v[198:201], v93 offset:20480
	ds_read_b128 v[202:205], v90 offset:53248
	s_waitcnt lgkmcnt(6)
	v_mfma_f32_32x32x16_bf16 v[50:65], v[162:165], v[166:169], v[50:65]
	s_waitcnt lgkmcnt(4)
	v_mfma_f32_32x32x16_bf16 v[34:49], v[162:165], v[186:189], v[34:49]
	v_mfma_f32_32x32x16_bf16 v[18:33], v[182:185], v[166:169], v[18:33]
	v_mfma_f32_32x32x16_bf16 v[2:17], v[182:185], v[186:189], v[2:17]
	ds_read_b128 v[162:165], v89 offset:16384
	ds_read_b128 v[166:169], v89 offset:20480
	ds_read_b128 v[182:185], v88 offset:49152
	ds_read_b128 v[186:189], v88 offset:53248
	s_waitcnt lgkmcnt(6)
	v_mfma_f32_32x32x16_bf16 v[50:65], v[190:193], v[194:197], v[50:65]
	s_waitcnt lgkmcnt(4)
	v_mfma_f32_32x32x16_bf16 v[34:49], v[190:193], v[202:205], v[34:49]
	v_mfma_f32_32x32x16_bf16 v[18:33], v[198:201], v[194:197], v[18:33]
	v_mfma_f32_32x32x16_bf16 v[2:17], v[198:201], v[202:205], v[2:17]
	ds_read_b128 v[190:193], v87 offset:16384
	ds_read_b128 v[194:197], v87 offset:20480
	ds_read_b128 v[198:201], v86 offset:49152
	ds_read_b128 v[202:205], v86 offset:53248
	v_lshl_add_u64 v[66:67], v[66:67], 0, s[98:99]
	v_lshl_add_u64 v[70:71], v[70:71], 0, s[98:99]
	v_lshl_add_u64 v[74:75], v[74:75], 0, s[98:99]
	v_lshl_add_u64 v[78:79], v[78:79], 0, s[98:99]
	v_lshl_add_u64 v[68:69], v[68:69], 0, s[98:99]
	v_lshl_add_u64 v[72:73], v[72:73], 0, s[98:99]
	v_lshl_add_u64 v[76:77], v[76:77], 0, s[98:99]
	v_lshl_add_u64 v[80:81], v[80:81], 0, s[98:99]
	s_waitcnt vmcnt(0)
	s_waitcnt lgkmcnt(0)
	s_barrier
	s_add_u32 m0, s32, 0x4000
	v_mfma_f32_32x32x16_bf16 v[50:65], v[162:165], v[182:185], v[50:65]
	global_load_lds_dwordx4 v[66:67], off
	s_add_u32 m0, s32, 0x5000
	v_mfma_f32_32x32x16_bf16 v[34:49], v[162:165], v[186:189], v[34:49]
	global_load_lds_dwordx4 v[70:71], off
	s_add_u32 m0, s32, 0x6000
	v_mfma_f32_32x32x16_bf16 v[18:33], v[166:169], v[182:185], v[18:33]
	global_load_lds_dwordx4 v[74:75], off
	s_add_u32 m0, s32, 0x7000
	v_mfma_f32_32x32x16_bf16 v[2:17], v[166:169], v[186:189], v[2:17]
	global_load_lds_dwordx4 v[78:79], off
	s_add_u32 m0, s32, 0xc000
	v_mfma_f32_32x32x16_bf16 v[50:65], v[190:193], v[198:201], v[50:65]
	global_load_lds_dwordx4 v[68:69], off
	s_add_u32 m0, s32, 0xd000
	v_mfma_f32_32x32x16_bf16 v[34:49], v[190:193], v[202:205], v[34:49]
	global_load_lds_dwordx4 v[72:73], off
	s_add_u32 m0, s32, 0xe000
	v_mfma_f32_32x32x16_bf16 v[18:33], v[194:197], v[198:201], v[18:33]
	global_load_lds_dwordx4 v[76:77], off
	s_add_u32 m0, s32, 0xf000
	v_mfma_f32_32x32x16_bf16 v[2:17], v[194:197], v[202:205], v[2:17]
	global_load_lds_dwordx4 v[80:81], off
	ds_read_b128 v[162:165], v91
	ds_read_b128 v[166:169], v92 offset:32768
	ds_read_b128 v[182:185], v91 offset:4096
	ds_read_b128 v[186:189], v92 offset:36864
	ds_read_b128 v[190:193], v93
	ds_read_b128 v[194:197], v90 offset:32768
	ds_read_b128 v[198:201], v93 offset:4096
	ds_read_b128 v[202:205], v90 offset:36864
	s_waitcnt lgkmcnt(6)
	v_mfma_f32_32x32x16_bf16 v[50:65], v[162:165], v[166:169], v[50:65]
	s_waitcnt lgkmcnt(4)
	v_mfma_f32_32x32x16_bf16 v[34:49], v[162:165], v[186:189], v[34:49]
	v_mfma_f32_32x32x16_bf16 v[18:33], v[182:185], v[166:169], v[18:33]
	v_mfma_f32_32x32x16_bf16 v[2:17], v[182:185], v[186:189], v[2:17]
	ds_read_b128 v[162:165], v89
	ds_read_b128 v[166:169], v89 offset:4096
	ds_read_b128 v[182:185], v88 offset:32768
	ds_read_b128 v[186:189], v88 offset:36864
	s_waitcnt lgkmcnt(6)
	v_mfma_f32_32x32x16_bf16 v[50:65], v[190:193], v[194:197], v[50:65]
	s_waitcnt lgkmcnt(4)
	v_mfma_f32_32x32x16_bf16 v[34:49], v[190:193], v[202:205], v[34:49]
	v_mfma_f32_32x32x16_bf16 v[18:33], v[198:201], v[194:197], v[18:33]
	v_mfma_f32_32x32x16_bf16 v[2:17], v[198:201], v[202:205], v[2:17]
	ds_read_b128 v[190:193], v87
	ds_read_b128 v[194:197], v87 offset:4096
	ds_read_b128 v[198:201], v86 offset:32768
	ds_read_b128 v[202:205], v86 offset:36864
	v_lshl_add_u64 v[66:67], v[66:67], 0, s[98:99]
	v_lshl_add_u64 v[70:71], v[70:71], 0, s[98:99]
	v_lshl_add_u64 v[74:75], v[74:75], 0, s[98:99]
	v_lshl_add_u64 v[78:79], v[78:79], 0, s[98:99]
	v_lshl_add_u64 v[68:69], v[68:69], 0, s[98:99]
	v_lshl_add_u64 v[72:73], v[72:73], 0, s[98:99]
	v_lshl_add_u64 v[76:77], v[76:77], 0, s[98:99]
	v_lshl_add_u64 v[80:81], v[80:81], 0, s[98:99]
	s_waitcnt vmcnt(0)
	s_waitcnt lgkmcnt(0)
	s_barrier
	s_add_u32 m0, s32, 0x0
	s_nop 0
	global_load_lds_dwordx4 v[66:67], off
	s_add_u32 m0, s32, 0x1000
	s_nop 0
	global_load_lds_dwordx4 v[70:71], off
	s_add_u32 m0, s32, 0x2000
	s_nop 0
	global_load_lds_dwordx4 v[74:75], off
	s_add_u32 m0, s32, 0x3000
	s_nop 0
	global_load_lds_dwordx4 v[78:79], off
	s_add_u32 m0, s32, 0x8000
	s_nop 0
	global_load_lds_dwordx4 v[68:69], off
	s_add_u32 m0, s32, 0x9000
	s_nop 0
	global_load_lds_dwordx4 v[72:73], off
	s_add_u32 m0, s32, 0xa000
	s_nop 0
	global_load_lds_dwordx4 v[76:77], off
	s_add_u32 m0, s32, 0xb000
	s_nop 0
	global_load_lds_dwordx4 v[80:81], off
	s_nop 0
	s_nop 0
	s_nop 0
	s_nop 0
	s_nop 0
	s_nop 0
	s_nop 0
	v_mfma_f32_32x32x16_bf16 v[50:65], v[162:165], v[182:185], v[50:65]
	v_mfma_f32_32x32x16_bf16 v[34:49], v[162:165], v[186:189], v[34:49]
	v_mfma_f32_32x32x16_bf16 v[18:33], v[166:169], v[182:185], v[18:33]
	v_mfma_f32_32x32x16_bf16 v[2:17], v[166:169], v[186:189], v[2:17]
	ds_read_b128 v[110:113], v91 offset:16384
	ds_read_b128 v[114:117], v91 offset:20480
	ds_read_b128 v[118:121], v92 offset:49152
	ds_read_b128 v[122:125], v92 offset:53248
	ds_read_b128 v[162:165], v93 offset:16384
	ds_read_b128 v[166:169], v93 offset:20480
	ds_read_b128 v[182:185], v90 offset:49152
	ds_read_b128 v[186:189], v90 offset:53248
	v_mfma_f32_32x32x16_bf16 v[50:65], v[190:193], v[198:201], v[50:65]
	v_mfma_f32_32x32x16_bf16 v[34:49], v[190:193], v[202:205], v[34:49]
	v_mfma_f32_32x32x16_bf16 v[18:33], v[194:197], v[198:201], v[18:33]
	v_mfma_f32_32x32x16_bf16 v[2:17], v[194:197], v[202:205], v[2:17]
	s_waitcnt lgkmcnt(5)
	v_mfma_f32_32x32x16_bf16 v[50:65], v[110:113], v[118:121], v[50:65]
	s_waitcnt lgkmcnt(4)
	v_mfma_f32_32x32x16_bf16 v[34:49], v[110:113], v[122:125], v[34:49]
	v_mfma_f32_32x32x16_bf16 v[18:33], v[114:117], v[118:121], v[18:33]
	v_mfma_f32_32x32x16_bf16 v[2:17], v[114:117], v[122:125], v[2:17]
	ds_read_b128 v[110:113], v89 offset:16384
	ds_read_b128 v[114:117], v89 offset:20480
	ds_read_b128 v[118:121], v88 offset:49152
	ds_read_b128 v[122:125], v88 offset:53248
	s_waitcnt lgkmcnt(5)
	v_mfma_f32_32x32x16_bf16 v[50:65], v[162:165], v[182:185], v[50:65]
	s_waitcnt lgkmcnt(4)
	v_mfma_f32_32x32x16_bf16 v[34:49], v[162:165], v[186:189], v[34:49]
	v_mfma_f32_32x32x16_bf16 v[18:33], v[166:169], v[182:185], v[18:33]
	v_mfma_f32_32x32x16_bf16 v[2:17], v[166:169], v[186:189], v[2:17]
	ds_read_b128 v[162:165], v87 offset:16384
	ds_read_b128 v[166:169], v87 offset:20480
	ds_read_b128 v[182:185], v86 offset:49152
	ds_read_b128 v[186:189], v86 offset:53248
	s_waitcnt lgkmcnt(5)
	v_mfma_f32_32x32x16_bf16 v[50:65], v[110:113], v[118:121], v[50:65]
	v_lshl_add_u64 v[66:67], v[66:67], 0, s[98:99]
	v_lshl_add_u64 v[70:71], v[70:71], 0, s[98:99]
	v_lshl_add_u64 v[74:75], v[74:75], 0, s[98:99]
	v_lshl_add_u64 v[78:79], v[78:79], 0, s[98:99]
	v_lshl_add_u64 v[68:69], v[68:69], 0, s[98:99]
	v_lshl_add_u64 v[72:73], v[72:73], 0, s[98:99]
	v_lshl_add_u64 v[76:77], v[76:77], 0, s[98:99]
	v_lshl_add_u64 v[80:81], v[80:81], 0, s[98:99]
	s_waitcnt vmcnt(0)
	s_waitcnt lgkmcnt(0)
	s_barrier
	s_add_u32 m0, s32, 0x4000
	s_nop 0
	global_load_lds_dwordx4 v[66:67], off
	s_add_u32 m0, s32, 0x5000
	s_nop 0
	global_load_lds_dwordx4 v[70:71], off
	s_add_u32 m0, s32, 0x6000
	s_nop 0
	global_load_lds_dwordx4 v[74:75], off
	s_add_u32 m0, s32, 0x7000
	s_nop 0
	global_load_lds_dwordx4 v[78:79], off
	s_add_u32 m0, s32, 0xc000
	s_nop 0
	global_load_lds_dwordx4 v[68:69], off
	s_add_u32 m0, s32, 0xd000
	s_nop 0
	global_load_lds_dwordx4 v[72:73], off
	s_add_u32 m0, s32, 0xe000
	s_nop 0
	global_load_lds_dwordx4 v[76:77], off
	s_add_u32 m0, s32, 0xf000
	s_nop 0
	global_load_lds_dwordx4 v[80:81], off
	v_mfma_f32_32x32x16_bf16 v[34:49], v[110:113], v[122:125], v[34:49]
	v_mfma_f32_32x32x16_bf16 v[18:33], v[114:117], v[118:121], v[18:33]
	v_mfma_f32_32x32x16_bf16 v[2:17], v[114:117], v[122:125], v[2:17]
	ds_read_b128 v[110:113], v91
	ds_read_b128 v[114:117], v91 offset:4096
	ds_read_b128 v[118:121], v92 offset:32768
	ds_read_b128 v[122:125], v92 offset:36864
	ds_read_b128 v[126:129], v93
	ds_read_b128 v[134:137], v93 offset:4096
	ds_read_b128 v[138:141], v90 offset:32768
	ds_read_b128 v[142:145], v90 offset:36864
	v_mfma_f32_32x32x16_bf16 v[50:65], v[162:165], v[182:185], v[50:65]
	v_mfma_f32_32x32x16_bf16 v[34:49], v[162:165], v[186:189], v[34:49]
	v_mfma_f32_32x32x16_bf16 v[18:33], v[166:169], v[182:185], v[18:33]
	v_mfma_f32_32x32x16_bf16 v[2:17], v[166:169], v[186:189], v[2:17]
	s_waitcnt lgkmcnt(5)
	v_mfma_f32_32x32x16_bf16 v[50:65], v[110:113], v[118:121], v[50:65]
	s_waitcnt lgkmcnt(4)
	v_mfma_f32_32x32x16_bf16 v[34:49], v[110:113], v[122:125], v[34:49]
	v_mfma_f32_32x32x16_bf16 v[18:33], v[114:117], v[118:121], v[18:33]
	v_mfma_f32_32x32x16_bf16 v[2:17], v[114:117], v[122:125], v[2:17]
	ds_read_b128 v[110:113], v89
	ds_read_b128 v[114:117], v89 offset:4096
	ds_read_b128 v[118:121], v88 offset:32768
	ds_read_b128 v[122:125], v88 offset:36864
	s_waitcnt lgkmcnt(5)
	v_mfma_f32_32x32x16_bf16 v[50:65], v[126:129], v[138:141], v[50:65]
	s_waitcnt lgkmcnt(4)
	v_mfma_f32_32x32x16_bf16 v[34:49], v[126:129], v[142:145], v[34:49]
	v_mfma_f32_32x32x16_bf16 v[18:33], v[134:137], v[138:141], v[18:33]
	v_mfma_f32_32x32x16_bf16 v[2:17], v[134:137], v[142:145], v[2:17]
	ds_read_b128 v[126:129], v87
	ds_read_b128 v[134:137], v87 offset:4096
	ds_read_b128 v[138:141], v86 offset:32768
	ds_read_b128 v[142:145], v86 offset:36864
	s_waitcnt vmcnt(0)
	s_waitcnt lgkmcnt(0)
	s_barrier
	ds_read_b128 v[66:69], v91 offset:16384
	ds_read_b128 v[70:73], v91 offset:20480
	ds_read_b128 v[74:77], v92 offset:49152
	ds_read_b128 v[78:81], v92 offset:53248
	ds_read_b128 v[94:97], v93 offset:16384
	ds_read_b128 v[98:101], v93 offset:20480
	ds_read_b128 v[102:105], v90 offset:49152
	ds_read_b128 v[90:93], v90 offset:53248
	v_mfma_f32_32x32x16_bf16 v[50:65], v[110:113], v[118:121], v[50:65]
	v_mfma_f32_32x32x16_bf16 v[34:49], v[110:113], v[122:125], v[34:49]
	v_mfma_f32_32x32x16_bf16 v[18:33], v[114:117], v[118:121], v[18:33]
	v_mfma_f32_32x32x16_bf16 v[2:17], v[114:117], v[122:125], v[2:17]
	v_mfma_f32_32x32x16_bf16 v[50:65], v[126:129], v[138:141], v[50:65]
	v_mfma_f32_32x32x16_bf16 v[34:49], v[126:129], v[142:145], v[34:49]
	v_mfma_f32_32x32x16_bf16 v[18:33], v[134:137], v[138:141], v[18:33]
	v_mfma_f32_32x32x16_bf16 v[2:17], v[134:137], v[142:145], v[2:17]
	s_waitcnt lgkmcnt(5)
	v_mfma_f32_32x32x16_bf16 v[50:65], v[66:69], v[74:77], v[50:65]
	s_waitcnt lgkmcnt(4)
	v_mfma_f32_32x32x16_bf16 v[34:49], v[66:69], v[78:81], v[34:49]
	v_mfma_f32_32x32x16_bf16 v[18:33], v[70:73], v[74:77], v[18:33]
	v_mfma_f32_32x32x16_bf16 v[2:17], v[70:73], v[78:81], v[2:17]
	ds_read_b128 v[66:69], v89 offset:16384
	ds_read_b128 v[70:73], v89 offset:20480
	ds_read_b128 v[74:77], v88 offset:49152
	ds_read_b128 v[78:81], v88 offset:53248
	s_waitcnt lgkmcnt(5)
	v_mfma_f32_32x32x16_bf16 v[50:65], v[94:97], v[102:105], v[50:65]
	s_waitcnt lgkmcnt(4)
	v_mfma_f32_32x32x16_bf16 v[34:49], v[94:97], v[90:93], v[34:49]
	v_mfma_f32_32x32x16_bf16 v[18:33], v[98:101], v[102:105], v[18:33]
	v_mfma_f32_32x32x16_bf16 v[2:17], v[98:101], v[90:93], v[2:17]
	ds_read_b128 v[88:91], v87 offset:16384
	ds_read_b128 v[92:95], v87 offset:20480
	ds_read_b128 v[96:99], v86 offset:49152
	ds_read_b128 v[100:103], v86 offset:53248
	s_waitcnt lgkmcnt(5)
	v_mfma_f32_32x32x16_bf16 v[50:65], v[66:69], v[74:77], v[50:65]
	v_lshlrev_b32_e32 v0, 6, v85
	v_lshlrev_b32_e32 v84, 6, v84
	v_subrev_u32_e32 v0, s6, v0
	v_add_u32_e32 v0, s4, v0
	v_ashrrev_i32_e32 v0, 6, v0
	v_lshlrev_b32_e32 v85, 2, v83
	s_waitcnt lgkmcnt(0)
	v_mfma_f32_32x32x16_bf16 v[50:65], v[88:91], v[96:99], v[50:65]
	s_barrier
	v_or_b32_e32 v83, 2, v84
	v_or_b32_e32 v86, 3, v84
	v_or_b32_e32 v87, 8, v85
	s_add_i32 s5, s5, s66
	s_add_i32 s4, s4, s3
	v_mfma_f32_32x32x16_bf16 v[34:49], v[66:69], v[78:81], v[34:49]
	v_lshl_add_u32 v66, s34, 7, v84
	v_ashrrev_i32_e32 v66, 1, v66
	v_and_b32_e32 v66, 0xffffffc0, v66
	v_add_u32_e32 v66, v66, v0
	v_ashrrev_i32_e32 v67, 31, v66
	v_lshlrev_b64 v[66:67], 14, v[66:67]
	v_lshl_add_u64 v[66:67], s[50:51], 0, v[66:67]
	v_lshlrev_b32_e32 v0, 1, v82
	v_lshl_add_u64 v[66:67], v[66:67], 0, v[0:1]
	v_max_f32_e32 v0, v50, v50
	v_max_f32_e32 v0, 0, v0
	v_or_b32_e32 v68, v85, v84
	v_mul_f32_e32 v0, v0, v0
	v_cvt_pk_bf16_f32 v50, v0, s0
	v_lshlrev_b32_e32 v0, 7, v68
	v_and_b32_e32 v0, 0x2200, v0
	v_lshl_add_u64 v[68:69], v[66:67], 0, v[0:1]
	v_or_b32_e32 v82, 1, v84
	global_store_short v[68:69], v50, off
	v_or_b32_e32 v0, v85, v82
	v_max_f32_e32 v50, v51, v51
	v_max_f32_e32 v50, 0, v50
	v_lshlrev_b32_e32 v0, 7, v0
	v_mul_f32_e32 v50, v50, v50
	v_and_b32_e32 v0, 0x2280, v0
	v_mfma_f32_32x32x16_bf16 v[18:33], v[70:73], v[74:77], v[18:33]
	v_max_f32_e32 v52, v52, v52
	v_max_f32_e32 v52, 0, v52
	v_mul_f32_e32 v52, v52, v52
	v_cvt_pk_bf16_f32 v52, v52, s0
	v_max_f32_e32 v54, v54, v54
	v_max_f32_e32 v54, 0, v54
	v_mul_f32_e32 v54, v54, v54
	v_mfma_f32_32x32x16_bf16 v[2:17], v[70:73], v[78:81], v[2:17]
	v_cvt_pk_bf16_f32 v70, v50, s0
	v_lshl_add_u64 v[50:51], v[66:67], 0, v[0:1]
	v_or_b32_e32 v0, v85, v83
	v_lshlrev_b32_e32 v0, 7, v0
	v_and_b32_e32 v0, 0x2300, v0
	global_store_short v[50:51], v70, off
	v_lshl_add_u64 v[70:71], v[66:67], 0, v[0:1]
	global_store_short v[70:71], v52, off
	v_or_b32_e32 v0, v85, v86
	v_max_f32_e32 v52, v53, v53
	v_max_f32_e32 v52, 0, v52
	v_lshlrev_b32_e32 v0, 7, v0
	v_mul_f32_e32 v52, v52, v52
	v_and_b32_e32 v0, 0x2380, v0
	v_cvt_pk_bf16_f32 v72, v52, s0
	v_lshl_add_u64 v[52:53], v[66:67], 0, v[0:1]
	v_or_b32_e32 v0, v87, v84
	v_lshlrev_b32_e32 v0, 7, v0
	v_and_b32_e32 v0, 0x2600, v0
	global_store_short v[52:53], v72, off
	v_cvt_pk_bf16_f32 v54, v54, s0
	v_lshl_add_u64 v[72:73], v[66:67], 0, v[0:1]
	global_store_short v[72:73], v54, off
	v_or_b32_e32 v0, v87, v82
	v_max_f32_e32 v54, v55, v55
	v_max_f32_e32 v54, 0, v54
	v_lshlrev_b32_e32 v0, 7, v0
	v_mul_f32_e32 v54, v54, v54
	v_and_b32_e32 v0, 0x2680, v0
	v_cvt_pk_bf16_f32 v74, v54, s0
	v_lshl_add_u64 v[54:55], v[66:67], 0, v[0:1]
	v_or_b32_e32 v0, v87, v83
	v_max_f32_e32 v56, v56, v56
	v_max_f32_e32 v56, 0, v56
	v_lshlrev_b32_e32 v0, 7, v0
	v_mul_f32_e32 v56, v56, v56
	v_and_b32_e32 v0, 0x2700, v0
	global_store_short v[54:55], v74, off
	v_cvt_pk_bf16_f32 v56, v56, s0
	v_lshl_add_u64 v[74:75], v[66:67], 0, v[0:1]
	global_store_short v[74:75], v56, off
	v_or_b32_e32 v0, v87, v86
	v_max_f32_e32 v56, v57, v57
	v_max_f32_e32 v56, 0, v56
	v_lshlrev_b32_e32 v0, 7, v0
	v_mfma_f32_32x32x16_bf16 v[34:49], v[88:91], v[100:103], v[34:49]
	v_mul_f32_e32 v56, v56, v56
	v_and_b32_e32 v0, 0x2780, v0
	v_or_b32_e32 v88, 16, v85
	v_cvt_pk_bf16_f32 v76, v56, s0
	v_lshl_add_u64 v[56:57], v[66:67], 0, v[0:1]
	v_or_b32_e32 v0, v88, v84
	v_max_f32_e32 v58, v58, v58
	v_max_f32_e32 v58, 0, v58
	v_lshlrev_b32_e32 v0, 7, v0
	v_mul_f32_e32 v58, v58, v58
	v_and_b32_e32 v0, 0x2a00, v0
	global_store_short v[56:57], v76, off
	v_cvt_pk_bf16_f32 v58, v58, s0
	v_lshl_add_u64 v[76:77], v[66:67], 0, v[0:1]
	global_store_short v[76:77], v58, off
	v_or_b32_e32 v0, v88, v82
	v_max_f32_e32 v58, v59, v59
	v_max_f32_e32 v58, 0, v58
	v_lshlrev_b32_e32 v0, 7, v0
	v_mul_f32_e32 v58, v58, v58
	v_and_b32_e32 v0, 0x2a80, v0
	v_cvt_pk_bf16_f32 v78, v58, s0
	v_lshl_add_u64 v[58:59], v[66:67], 0, v[0:1]
	v_or_b32_e32 v0, v88, v83
	v_max_f32_e32 v60, v60, v60
	v_max_f32_e32 v60, 0, v60
	v_lshlrev_b32_e32 v0, 7, v0
	v_mul_f32_e32 v60, v60, v60
	v_and_b32_e32 v0, 0x2b00, v0
	global_store_short v[58:59], v78, off
	v_cvt_pk_bf16_f32 v60, v60, s0
	v_lshl_add_u64 v[78:79], v[66:67], 0, v[0:1]
	global_store_short v[78:79], v60, off
	v_or_b32_e32 v0, v88, v86
	v_max_f32_e32 v60, v61, v61
	v_max_f32_e32 v60, 0, v60
	v_lshlrev_b32_e32 v0, 7, v0
	v_mul_f32_e32 v60, v60, v60
	v_and_b32_e32 v0, 0x2b80, v0
	v_or_b32_e32 v89, 24, v85
	v_cvt_pk_bf16_f32 v80, v60, s0
	v_lshl_add_u64 v[60:61], v[66:67], 0, v[0:1]
	v_or_b32_e32 v0, v89, v84
	v_max_f32_e32 v62, v62, v62
	v_max_f32_e32 v62, 0, v62
	v_lshlrev_b32_e32 v0, 7, v0
	v_mul_f32_e32 v62, v62, v62
	v_and_b32_e32 v0, 0x2e00, v0
	global_store_short v[60:61], v80, off
	v_cvt_pk_bf16_f32 v62, v62, s0
	v_lshl_add_u64 v[80:81], v[66:67], 0, v[0:1]
	global_store_short v[80:81], v62, off
	v_or_b32_e32 v0, v89, v82
	v_max_f32_e32 v62, v63, v63
	v_max_f32_e32 v62, 0, v62
	v_lshlrev_b32_e32 v0, 7, v0
	v_mul_f32_e32 v62, v62, v62
	v_and_b32_e32 v0, 0x2e80, v0
	v_cvt_pk_bf16_f32 v82, v62, s0
	v_lshl_add_u64 v[62:63], v[66:67], 0, v[0:1]
	v_or_b32_e32 v0, v89, v83
	v_max_f32_e32 v64, v64, v64
	v_max_f32_e32 v64, 0, v64
	v_lshlrev_b32_e32 v0, 7, v0
	v_mul_f32_e32 v64, v64, v64
	v_and_b32_e32 v0, 0x2f00, v0
	global_store_short v[62:63], v82, off
	v_cvt_pk_bf16_f32 v64, v64, s0
	v_lshl_add_u64 v[82:83], v[66:67], 0, v[0:1]
	global_store_short v[82:83], v64, off
	v_or_b32_e32 v0, v89, v86
	v_max_f32_e32 v64, v65, v65
	v_max_f32_e32 v64, 0, v64
	v_lshlrev_b32_e32 v0, 7, v0
	v_mul_f32_e32 v64, v64, v64
	v_and_b32_e32 v0, 0x2f80, v0
	v_cvt_pk_bf16_f32 v86, v64, s0
	v_lshl_add_u64 v[64:65], v[66:67], 0, v[0:1]
	v_max_f32_e32 v0, v34, v34
	v_max_f32_e32 v0, 0, v0
	v_mul_f32_e32 v0, v0, v0
	v_cvt_pk_bf16_f32 v0, v0, s0
	global_store_short v[64:65], v86, off
	global_store_short v[68:69], v0, off offset:64
	v_max_f32_e32 v0, v35, v35
	v_max_f32_e32 v0, 0, v0
	v_mul_f32_e32 v0, v0, v0
	v_cvt_pk_bf16_f32 v0, v0, s0
	global_store_short v[50:51], v0, off offset:64
	v_max_f32_e32 v0, v36, v36
	v_max_f32_e32 v0, 0, v0
	v_mul_f32_e32 v0, v0, v0
	v_cvt_pk_bf16_f32 v0, v0, s0
	global_store_short v[70:71], v0, off offset:64
	v_max_f32_e32 v0, v37, v37
	v_max_f32_e32 v0, 0, v0
	v_mul_f32_e32 v0, v0, v0
	v_cvt_pk_bf16_f32 v0, v0, s0
	global_store_short v[52:53], v0, off offset:64
	v_max_f32_e32 v0, v38, v38
	v_max_f32_e32 v0, 0, v0
	v_mul_f32_e32 v0, v0, v0
	v_cvt_pk_bf16_f32 v0, v0, s0
	global_store_short v[72:73], v0, off offset:64
	v_max_f32_e32 v0, v39, v39
	v_max_f32_e32 v0, 0, v0
	v_mul_f32_e32 v0, v0, v0
	v_cvt_pk_bf16_f32 v0, v0, s0
	global_store_short v[54:55], v0, off offset:64
	v_max_f32_e32 v0, v40, v40
	v_max_f32_e32 v0, 0, v0
	v_mul_f32_e32 v0, v0, v0
	v_cvt_pk_bf16_f32 v0, v0, s0
	global_store_short v[74:75], v0, off offset:64
	v_max_f32_e32 v0, v41, v41
	v_max_f32_e32 v0, 0, v0
	v_mul_f32_e32 v0, v0, v0
	v_cvt_pk_bf16_f32 v0, v0, s0
	global_store_short v[56:57], v0, off offset:64
	v_max_f32_e32 v0, v42, v42
	v_max_f32_e32 v0, 0, v0
	v_mul_f32_e32 v0, v0, v0
	v_cvt_pk_bf16_f32 v0, v0, s0
	global_store_short v[76:77], v0, off offset:64
	v_max_f32_e32 v0, v43, v43
	v_max_f32_e32 v0, 0, v0
	v_mul_f32_e32 v0, v0, v0
	v_cvt_pk_bf16_f32 v0, v0, s0
	global_store_short v[58:59], v0, off offset:64
	v_max_f32_e32 v0, v44, v44
	v_max_f32_e32 v0, 0, v0
	v_mul_f32_e32 v0, v0, v0
	v_cvt_pk_bf16_f32 v0, v0, s0
	global_store_short v[78:79], v0, off offset:64
	v_max_f32_e32 v0, v45, v45
	v_max_f32_e32 v0, 0, v0
	v_mul_f32_e32 v0, v0, v0
	v_cvt_pk_bf16_f32 v0, v0, s0
	global_store_short v[60:61], v0, off offset:64
	v_max_f32_e32 v0, v46, v46
	v_max_f32_e32 v0, 0, v0
	v_mul_f32_e32 v0, v0, v0
	v_cvt_pk_bf16_f32 v0, v0, s0
	global_store_short v[80:81], v0, off offset:64
	v_max_f32_e32 v0, v47, v47
	v_max_f32_e32 v0, 0, v0
	v_mul_f32_e32 v0, v0, v0
	v_cvt_pk_bf16_f32 v0, v0, s0
	v_mfma_f32_32x32x16_bf16 v[18:33], v[92:95], v[96:99], v[18:33]
	global_store_short v[62:63], v0, off offset:64
	v_max_f32_e32 v0, v48, v48
	v_max_f32_e32 v0, 0, v0
	v_mul_f32_e32 v0, v0, v0
	v_cvt_pk_bf16_f32 v0, v0, s0
	global_store_short v[82:83], v0, off offset:64
	v_max_f32_e32 v0, v49, v49
	v_max_f32_e32 v0, 0, v0
	v_mul_f32_e32 v0, v0, v0
	v_cvt_pk_bf16_f32 v0, v0, s0
	v_or_b32_e32 v46, 32, v84
	global_store_short v[64:65], v0, off offset:64
	v_or_b32_e32 v0, v85, v46
	v_max_f32_e32 v18, v18, v18
	v_max_f32_e32 v18, 0, v18
	v_lshlrev_b32_e32 v0, 7, v0
	v_mul_f32_e32 v18, v18, v18
	v_and_b32_e32 v0, 0x3200, v0
	v_cvt_pk_bf16_f32 v18, v18, s0
	v_lshl_add_u64 v[34:35], v[66:67], 0, v[0:1]
	v_or_b32_e32 v48, 33, v84
	global_store_short v[34:35], v18, off
	v_or_b32_e32 v0, v85, v48
	v_max_f32_e32 v18, v19, v19
	v_max_f32_e32 v18, 0, v18
	v_lshlrev_b32_e32 v0, 7, v0
	v_mul_f32_e32 v18, v18, v18
	v_and_b32_e32 v0, 0x3280, v0
	v_or_b32_e32 v49, 34, v84
	v_cvt_pk_bf16_f32 v36, v18, s0
	v_lshl_add_u64 v[18:19], v[66:67], 0, v[0:1]
	v_or_b32_e32 v0, v85, v49
	v_max_f32_e32 v20, v20, v20
	v_max_f32_e32 v20, 0, v20
	v_lshlrev_b32_e32 v0, 7, v0
	v_mul_f32_e32 v20, v20, v20
	v_and_b32_e32 v0, 0x3300, v0
	global_store_short v[18:19], v36, off
	v_cvt_pk_bf16_f32 v20, v20, s0
	v_lshl_add_u64 v[36:37], v[66:67], 0, v[0:1]
	v_or_b32_e32 v50, 35, v84
	global_store_short v[36:37], v20, off
	v_or_b32_e32 v0, v85, v50
	v_max_f32_e32 v20, v21, v21
	v_max_f32_e32 v20, 0, v20
	v_lshlrev_b32_e32 v0, 7, v0
	v_mul_f32_e32 v20, v20, v20
	v_and_b32_e32 v0, 0x3380, v0
	v_cvt_pk_bf16_f32 v38, v20, s0
	v_lshl_add_u64 v[20:21], v[66:67], 0, v[0:1]
	v_or_b32_e32 v0, v87, v46
	v_max_f32_e32 v22, v22, v22
	v_max_f32_e32 v22, 0, v22
	v_lshlrev_b32_e32 v0, 7, v0
	v_mul_f32_e32 v22, v22, v22
	v_and_b32_e32 v0, 0x3600, v0
	global_store_short v[20:21], v38, off
	v_cvt_pk_bf16_f32 v22, v22, s0
	v_lshl_add_u64 v[38:39], v[66:67], 0, v[0:1]
	global_store_short v[38:39], v22, off
	v_or_b32_e32 v0, v87, v48
	v_max_f32_e32 v22, v23, v23
	v_max_f32_e32 v22, 0, v22
	v_lshlrev_b32_e32 v0, 7, v0
	v_mul_f32_e32 v22, v22, v22
	v_and_b32_e32 v0, 0x3680, v0
	v_cvt_pk_bf16_f32 v40, v22, s0
	v_lshl_add_u64 v[22:23], v[66:67], 0, v[0:1]
	v_or_b32_e32 v0, v87, v49
	v_max_f32_e32 v24, v24, v24
	v_max_f32_e32 v24, 0, v24
	v_lshlrev_b32_e32 v0, 7, v0
	v_mul_f32_e32 v24, v24, v24
	v_and_b32_e32 v0, 0x3700, v0
	global_store_short v[22:23], v40, off
	v_cvt_pk_bf16_f32 v24, v24, s0
	v_lshl_add_u64 v[40:41], v[66:67], 0, v[0:1]
	global_store_short v[40:41], v24, off
	v_or_b32_e32 v0, v87, v50
	v_max_f32_e32 v24, v25, v25
	v_max_f32_e32 v24, 0, v24
	v_lshlrev_b32_e32 v0, 7, v0
	v_mul_f32_e32 v24, v24, v24
	v_and_b32_e32 v0, 0x3780, v0
	v_cvt_pk_bf16_f32 v42, v24, s0
	v_lshl_add_u64 v[24:25], v[66:67], 0, v[0:1]
	v_or_b32_e32 v0, v88, v46
	v_max_f32_e32 v26, v26, v26
	v_max_f32_e32 v26, 0, v26
	v_lshlrev_b32_e32 v0, 7, v0
	v_mul_f32_e32 v26, v26, v26
	v_and_b32_e32 v0, 0x3a00, v0
	global_store_short v[24:25], v42, off
	v_cvt_pk_bf16_f32 v26, v26, s0
	v_lshl_add_u64 v[42:43], v[66:67], 0, v[0:1]
	global_store_short v[42:43], v26, off
	v_or_b32_e32 v0, v88, v48
	v_max_f32_e32 v26, v27, v27
	v_max_f32_e32 v26, 0, v26
	v_lshlrev_b32_e32 v0, 7, v0
	v_mul_f32_e32 v26, v26, v26
	v_and_b32_e32 v0, 0x3a80, v0
	v_cvt_pk_bf16_f32 v44, v26, s0
	v_lshl_add_u64 v[26:27], v[66:67], 0, v[0:1]
	v_or_b32_e32 v0, v88, v49
	v_max_f32_e32 v28, v28, v28
	v_max_f32_e32 v28, 0, v28
	v_lshlrev_b32_e32 v0, 7, v0
	v_mul_f32_e32 v28, v28, v28
	v_and_b32_e32 v0, 0x3b00, v0
	global_store_short v[26:27], v44, off
	v_cvt_pk_bf16_f32 v28, v28, s0
	v_lshl_add_u64 v[44:45], v[66:67], 0, v[0:1]
	global_store_short v[44:45], v28, off
	v_or_b32_e32 v0, v88, v50
	v_max_f32_e32 v28, v29, v29
	v_max_f32_e32 v28, 0, v28
	v_lshlrev_b32_e32 v0, 7, v0
	v_mul_f32_e32 v28, v28, v28
	v_and_b32_e32 v0, 0x3b80, v0
	v_cvt_pk_bf16_f32 v47, v28, s0
	v_lshl_add_u64 v[28:29], v[66:67], 0, v[0:1]
	v_or_b32_e32 v0, v89, v46
	v_max_f32_e32 v30, v30, v30
	v_max_f32_e32 v30, 0, v30
	v_lshlrev_b32_e32 v0, 7, v0
	v_mul_f32_e32 v30, v30, v30
	v_and_b32_e32 v0, 0x3e00, v0
	global_store_short v[28:29], v47, off
	v_cvt_pk_bf16_f32 v30, v30, s0
	v_lshl_add_u64 v[46:47], v[66:67], 0, v[0:1]
	global_store_short v[46:47], v30, off
	v_or_b32_e32 v0, v89, v48
	v_max_f32_e32 v30, v31, v31
	v_max_f32_e32 v30, 0, v30
	v_lshlrev_b32_e32 v0, 7, v0
	v_mfma_f32_32x32x16_bf16 v[2:17], v[92:95], v[100:103], v[2:17]
	v_mul_f32_e32 v30, v30, v30
	v_and_b32_e32 v0, 0x3e80, v0
	v_cvt_pk_bf16_f32 v48, v30, s0
	v_lshl_add_u64 v[30:31], v[66:67], 0, v[0:1]
	v_or_b32_e32 v0, v89, v49
	v_max_f32_e32 v32, v32, v32
	v_max_f32_e32 v32, 0, v32
	v_lshlrev_b32_e32 v0, 7, v0
	v_mul_f32_e32 v32, v32, v32
	v_and_b32_e32 v0, 0x3f00, v0
	global_store_short v[30:31], v48, off
	v_cvt_pk_bf16_f32 v32, v32, s0
	v_lshl_add_u64 v[48:49], v[66:67], 0, v[0:1]
	global_store_short v[48:49], v32, off
	v_or_b32_e32 v0, v89, v50
	v_max_f32_e32 v32, v33, v33
	v_max_f32_e32 v32, 0, v32
	v_lshlrev_b32_e32 v0, 7, v0
	v_mul_f32_e32 v32, v32, v32
	v_and_b32_e32 v0, 0x3f80, v0
	v_cvt_pk_bf16_f32 v50, v32, s0
	v_lshl_add_u64 v[32:33], v[66:67], 0, v[0:1]
	v_max_f32_e32 v0, v2, v2
	v_max_f32_e32 v0, 0, v0
	v_mul_f32_e32 v0, v0, v0
	v_cvt_pk_bf16_f32 v0, v0, s0
	global_store_short v[32:33], v50, off
	global_store_short v[34:35], v0, off offset:64
	v_max_f32_e32 v0, v3, v3
	v_max_f32_e32 v0, 0, v0
	v_mul_f32_e32 v0, v0, v0
	v_cvt_pk_bf16_f32 v0, v0, s0
	global_store_short v[18:19], v0, off offset:64
	v_max_f32_e32 v0, v4, v4
	v_max_f32_e32 v0, 0, v0
	v_mul_f32_e32 v0, v0, v0
	v_cvt_pk_bf16_f32 v0, v0, s0
	global_store_short v[36:37], v0, off offset:64
	v_max_f32_e32 v0, v5, v5
	v_max_f32_e32 v0, 0, v0
	v_mul_f32_e32 v0, v0, v0
	v_cvt_pk_bf16_f32 v0, v0, s0
	global_store_short v[20:21], v0, off offset:64
	v_max_f32_e32 v0, v6, v6
	v_max_f32_e32 v0, 0, v0
	v_mul_f32_e32 v0, v0, v0
	v_cvt_pk_bf16_f32 v0, v0, s0
	global_store_short v[38:39], v0, off offset:64
	v_max_f32_e32 v0, v7, v7
	v_max_f32_e32 v0, 0, v0
	v_mul_f32_e32 v0, v0, v0
	v_cvt_pk_bf16_f32 v0, v0, s0
	global_store_short v[22:23], v0, off offset:64
	v_max_f32_e32 v0, v8, v8
	v_max_f32_e32 v0, 0, v0
	v_mul_f32_e32 v0, v0, v0
	v_cvt_pk_bf16_f32 v0, v0, s0
	global_store_short v[40:41], v0, off offset:64
	v_max_f32_e32 v0, v9, v9
	v_max_f32_e32 v0, 0, v0
	v_mul_f32_e32 v0, v0, v0
	v_cvt_pk_bf16_f32 v0, v0, s0
	global_store_short v[24:25], v0, off offset:64
	v_max_f32_e32 v0, v10, v10
	v_max_f32_e32 v0, 0, v0
	v_mul_f32_e32 v0, v0, v0
	v_cvt_pk_bf16_f32 v0, v0, s0
	global_store_short v[42:43], v0, off offset:64
	v_max_f32_e32 v0, v11, v11
	v_max_f32_e32 v0, 0, v0
	v_mul_f32_e32 v0, v0, v0
	v_cvt_pk_bf16_f32 v0, v0, s0
	global_store_short v[26:27], v0, off offset:64
	v_max_f32_e32 v0, v12, v12
	v_max_f32_e32 v0, 0, v0
	v_mul_f32_e32 v0, v0, v0
	v_cvt_pk_bf16_f32 v0, v0, s0
	global_store_short v[44:45], v0, off offset:64
	v_max_f32_e32 v0, v13, v13
	v_max_f32_e32 v0, 0, v0
	v_mul_f32_e32 v0, v0, v0
	v_cvt_pk_bf16_f32 v0, v0, s0
	global_store_short v[28:29], v0, off offset:64
	v_max_f32_e32 v0, v14, v14
	v_max_f32_e32 v0, 0, v0
	v_mul_f32_e32 v0, v0, v0
	v_cvt_pk_bf16_f32 v0, v0, s0
	global_store_short v[46:47], v0, off offset:64
	v_max_f32_e32 v0, v15, v15
	v_max_f32_e32 v0, 0, v0
	v_mul_f32_e32 v0, v0, v0
	v_cvt_pk_bf16_f32 v0, v0, s0
	global_store_short v[30:31], v0, off offset:64
	v_max_f32_e32 v0, v16, v16
	v_max_f32_e32 v0, 0, v0
	v_mul_f32_e32 v0, v0, v0
	v_cvt_pk_bf16_f32 v0, v0, s0
	global_store_short v[48:49], v0, off offset:64
	v_max_f32_e32 v0, v17, v17
	v_max_f32_e32 v0, 0, v0
	v_mul_f32_e32 v0, v0, v0
	v_cvt_pk_bf16_f32 v0, v0, s0
	s_cmp_lt_i32 s5, s2
	global_store_short v[32:33], v0, off offset:64
	s_cbranch_scc1 .LBB0_1298
	s_mov_b32 s10, 0x8000
	s_mov_b32 s34, 0xa000
	s_mov_b32 s35, 0x2b000
	s_mov_b64 s[42:43], s[8:9]

.LBB0_1355:
	s_ashr_i32 s2, s7, 31
	s_lshr_b32 s2, s2, 29
	s_add_i32 s8, s7, s2
	s_ashr_i32 s2, s8, 3
	s_ashr_i32 s3, s2, 31
	v_readlane_b32 s36, v210, 50
	s_lshl_b64 s[4:5], s[2:3], 20
	v_readlane_b32 s50, v209, 0
	v_readlane_b32 s51, v209, 1
	s_add_u32 s4, s50, s4
	v_mov_b32_e32 v52, v133
	s_addc_u32 s5, s51, s5
	s_and_b32 s3, s8, 0x1fffff8
	s_sub_i32 s3, s7, s3
	v_ashrrev_i32_e32 v34, 3, v52
	v_ashrrev_i32_e32 v35, 31, v34
	s_lshl_b32 s8, s3, 7
	v_lshlrev_b64 v[2:3], 7, v[34:35]
	v_lshl_add_u64 v[134:135], s[4:5], 0, v[2:3]
	v_lshlrev_b32_e32 v0, 4, v52
	v_add_u32_e32 v2, s8, v34
	v_and_b32_e32 v0, 0x70, v0
	v_ashrrev_i32_e32 v3, 31, v2
	v_lshl_add_u64 v[36:37], v[134:135], 0, v[0:1]
	v_lshlrev_b64 v[2:3], 13, v[2:3]
	v_lshl_add_u64 v[136:137], s[0:1], 0, v[2:3]
	v_add_co_u32_e32 v18, vcc, s53, v36
	v_lshl_add_u64 v[38:39], v[136:137], 0, v[0:1]
	v_lshrrev_b32_e32 v232, 4, v133
	v_xor_b32_e32 v232, v232, v133
	v_and_b32_e32 v232, 7, v232
	v_lshlrev_b32_e32 v232, 4, v232
	v_mov_b32_e32 v233, 0x70
	v_lshrrev_b32_e32 v238, 6, v133
	v_lshlrev_b32_e32 v238, 10, v238
	s_nop 0
	v_readfirstlane_b32 s32, v238
	v_bfi_b32 v216, v233, v232, v36
	v_mov_b32_e32 v217, v37
	v_bfi_b32 v224, v233, v232, v38
	v_mov_b32_e32 v225, v39
	v_mov_b32_e32 v234, 0x1000
	v_mov_b32_e32 v235, 0
	v_mov_b32_e32 v236, 0x40000
	v_mov_b32_e32 v237, 0
	v_lshl_add_u64 v[218:219], v[234:235], 0, v[216:217]
	v_lshl_add_u64 v[220:221], v[234:235], 1, v[216:217]
	v_lshl_add_u64 v[222:223], v[234:235], 1, v[218:219]
	v_lshl_add_u64 v[226:227], v[236:237], 0, v[224:225]
	v_lshl_add_u64 v[228:229], v[236:237], 1, v[224:225]
	v_lshl_add_u64 v[230:231], v[236:237], 1, v[226:227]
	s_add_u32 m0, s32, 0x0
	s_nop 0
	global_load_lds_dwordx4 v[216:217], off
	s_add_u32 m0, s32, 0x1000
	v_lshl_add_u64 v[216:217], v[234:235], 2, v[216:217]
	global_load_lds_dwordx4 v[218:219], off
	s_add_u32 m0, s32, 0x2000
	v_lshl_add_u64 v[218:219], v[234:235], 2, v[218:219]
	global_load_lds_dwordx4 v[220:221], off
	s_add_u32 m0, s32, 0x3000
	v_lshl_add_u64 v[220:221], v[234:235], 2, v[220:221]
	global_load_lds_dwordx4 v[222:223], off
	s_add_u32 m0, s32, 0x8000
	v_lshl_add_u64 v[222:223], v[234:235], 2, v[222:223]
	global_load_lds_dwordx4 v[224:225], off
	s_add_u32 m0, s32, 0x9000
	v_lshl_add_u64 v[224:225], 32, 2, v[224:225]
	global_load_lds_dwordx4 v[226:227], off
	s_add_u32 m0, s32, 0xa000
	v_lshl_add_u64 v[226:227], 32, 2, v[226:227]
	global_load_lds_dwordx4 v[228:229], off
	s_add_u32 m0, s32, 0xb000
	v_lshl_add_u64 v[228:229], 32, 2, v[228:229]
	global_load_lds_dwordx4 v[230:231], off
	v_lshl_add_u64 v[230:231], 32, 2, v[230:231]
	s_nop 0
	v_addc_co_u32_e32 v19, vcc, 0, v37, vcc
	s_mov_b32 s3, 0x40000
	v_add_co_u32_e32 v40, vcc, s3, v38
	s_mov_b32 s3, 0x80000
	s_nop 0
	v_addc_co_u32_e32 v41, vcc, 0, v39, vcc
	v_add_co_u32_e32 v42, vcc, s3, v38
	s_nop 0
	v_addc_co_u32_e32 v43, vcc, 0, v39, vcc
	v_add_co_u32_e32 v44, vcc, s9, v36
	s_mov_b32 s3, 0xc0000
	s_nop 0
	v_addc_co_u32_e32 v45, vcc, 0, v37, vcc
	v_add_co_u32_e32 v46, vcc, s3, v38
	s_nop 0
	v_addc_co_u32_e32 v47, vcc, 0, v39, vcc
	v_lshlrev_b32_e32 v0, 7, v34
	v_lshrrev_b32_e32 v34, 1, v34
	v_xor_b32_e32 v34, v34, v52
	v_lshlrev_b32_e32 v34, 4, v34
	s_movk_i32 s4, 0x6000
	v_and_or_b32 v146, v34, s59, v0
	v_add_co_u32_e32 v34, vcc, s4, v36
	v_and_b32_e32 v142, 31, v52
	s_nop 0
	v_addc_co_u32_e32 v35, vcc, 0, v37, vcc
	v_add_co_u32_e32 v48, vcc, s10, v36
	v_ashrrev_i32_e32 v144, 7, v52
	s_nop 0
	v_addc_co_u32_e32 v49, vcc, 0, v37, vcc
	v_add_co_u32_e32 v50, vcc, s34, v36
	v_bfe_u32 v145, v52, 5, 1
	s_nop 0
	v_addc_co_u32_e32 v51, vcc, 0, v37, vcc
	v_bfe_u32 v143, v52, 6, 1
	v_lshlrev_b32_e32 v0, 7, v142
	v_lshl_or_b32 v147, v144, 13, v0
	v_lshl_or_b32 v149, v143, 13, v0
	s_mov_b32 s3, 0
	v_readlane_b32 s37, v210, 51
	v_readlane_b32 s38, v210, 52
	v_readlane_b32 s39, v210, 53
	v_readlane_b32 s40, v210, 54
	v_readlane_b32 s41, v210, 55
	v_readlane_b32 s42, v210, 56
	v_readlane_b32 s43, v210, 57
	v_readlane_b32 s44, v210, 58
	v_readlane_b32 s45, v210, 59
	v_readlane_b32 s46, v210, 60
	v_readlane_b32 s47, v210, 61
	v_readlane_b32 s48, v210, 62
	v_readlane_b32 s49, v210, 63
	v_add_co_u32_e32 v2, vcc, s52, v36
	s_waitcnt vmcnt(0)
	s_waitcnt lgkmcnt(0)
	s_barrier
	s_add_u32 m0, s32, 0x4000
	s_nop 0
	global_load_lds_dwordx4 v[216:217], off
	s_add_u32 m0, s32, 0x5000
	v_lshl_add_u64 v[216:217], v[234:235], 2, v[216:217]
	global_load_lds_dwordx4 v[218:219], off
	s_add_u32 m0, s32, 0x6000
	v_lshl_add_u64 v[218:219], v[234:235], 2, v[218:219]
	global_load_lds_dwordx4 v[220:221], off
	s_add_u32 m0, s32, 0x7000
	v_lshl_add_u64 v[220:221], v[234:235], 2, v[220:221]
	global_load_lds_dwordx4 v[222:223], off
	s_add_u32 m0, s32, 0xc000
	v_lshl_add_u64 v[222:223], v[234:235], 2, v[222:223]
	global_load_lds_dwordx4 v[224:225], off
	s_add_u32 m0, s32, 0xd000
	v_lshl_add_u64 v[224:225], 32, 2, v[224:225]
	global_load_lds_dwordx4 v[226:227], off
	s_add_u32 m0, s32, 0xe000
	v_lshl_add_u64 v[226:227], 32, 2, v[226:227]
	global_load_lds_dwordx4 v[228:229], off
	s_add_u32 m0, s32, 0xf000
	v_lshl_add_u64 v[228:229], 32, 2, v[228:229]
	global_load_lds_dwordx4 v[230:231], off
	v_lshl_add_u64 v[230:231], 32, 2, v[230:231]
	v_addc_co_u32_e32 v3, vcc, 0, v37, vcc
	v_bfe_u32 v3, v52, 1, 3
	v_bitop3_b32 v0, v145, v3, 2 bitop3:0x36
	v_lshrrev_b32_e32 v2, 1, v52
	v_lshlrev_b32_e32 v150, 4, v0
	v_bitop3_b32 v0, v145, v3, 4 bitop3:0x36
	v_bitop3_b32 v2, v2, v145, 7 bitop3:0x6c
	v_lshlrev_b32_e32 v151, 4, v0
	v_bitop3_b32 v0, v145, v3, 6 bitop3:0x36
	v_lshlrev_b32_e32 v148, 4, v2
	v_lshlrev_b32_e32 v152, 4, v0
	v_and_b32_e32 v0, 7, v52
	v_mov_b32_e32 v2, 0
	v_lshlrev_b32_e32 v0, 4, v0
	v_mov_b32_e32 v3, v2
	v_mov_b32_e32 v4, v2
	v_mov_b32_e32 v5, v2
	v_mov_b32_e32 v6, v2
	v_mov_b32_e32 v7, v2
	v_mov_b32_e32 v8, v2
	v_mov_b32_e32 v9, v2
	v_mov_b32_e32 v10, v2
	v_mov_b32_e32 v11, v2
	v_mov_b32_e32 v12, v2
	v_mov_b32_e32 v13, v2
	v_mov_b32_e32 v14, v2
	v_mov_b32_e32 v15, v2
	v_mov_b32_e32 v16, v2
	v_mov_b32_e32 v17, v2
	v_mov_b32_e32 v34, v2
	v_mov_b32_e32 v35, v2
	v_mov_b32_e32 v36, v2
	v_mov_b32_e32 v37, v2
	v_mov_b32_e32 v38, v2
	v_mov_b32_e32 v39, v2
	v_mov_b32_e32 v40, v2
	v_mov_b32_e32 v41, v2
	v_mov_b32_e32 v42, v2
	v_mov_b32_e32 v43, v2
	v_mov_b32_e32 v44, v2
	v_mov_b32_e32 v45, v2
	v_mov_b32_e32 v46, v2
	v_mov_b32_e32 v47, v2
	v_mov_b32_e32 v48, v2
	v_mov_b32_e32 v49, v2
	v_mov_b32_e32 v18, v2
	v_mov_b32_e32 v19, v2
	v_mov_b32_e32 v20, v2
	v_mov_b32_e32 v21, v2
	v_mov_b32_e32 v22, v2
	v_mov_b32_e32 v23, v2
	v_mov_b32_e32 v24, v2
	v_mov_b32_e32 v25, v2
	v_mov_b32_e32 v26, v2
	v_mov_b32_e32 v27, v2
	v_mov_b32_e32 v28, v2
	v_mov_b32_e32 v29, v2
	v_mov_b32_e32 v30, v2
	v_mov_b32_e32 v31, v2
	v_mov_b32_e32 v32, v2
	v_mov_b32_e32 v33, v2
	v_mov_b32_e32 v50, v2
	v_mov_b32_e32 v51, v2
	v_mov_b32_e32 v52, v2
	v_mov_b32_e32 v53, v2
	v_mov_b32_e32 v54, v2
	v_mov_b32_e32 v55, v2
	v_mov_b32_e32 v56, v2
	v_mov_b32_e32 v57, v2
	v_mov_b32_e32 v58, v2
	v_mov_b32_e32 v59, v2
	v_mov_b32_e32 v60, v2
	v_mov_b32_e32 v61, v2
	v_mov_b32_e32 v62, v2
	v_mov_b32_e32 v63, v2
	v_mov_b32_e32 v64, v2
	v_mov_b32_e32 v65, v2
	s_branch .LBB0_1357
.LBB0_1356:
	s_cmp_gt_u32 s3, 60
	s_cbranch_scc1 .Ldma9_skip_b
	s_add_u32 m0, s32, 0x4000
	s_nop 0
	global_load_lds_dwordx4 v[216:217], off
	s_add_u32 m0, s32, 0x5000
	v_lshl_add_u64 v[216:217], v[234:235], 2, v[216:217]
	global_load_lds_dwordx4 v[218:219], off
	s_add_u32 m0, s32, 0x6000
	v_lshl_add_u64 v[218:219], v[234:235], 2, v[218:219]
	global_load_lds_dwordx4 v[220:221], off
	s_add_u32 m0, s32, 0x7000
	v_lshl_add_u64 v[220:221], v[234:235], 2, v[220:221]
	global_load_lds_dwordx4 v[222:223], off
	s_add_u32 m0, s32, 0xc000
	v_lshl_add_u64 v[222:223], v[234:235], 2, v[222:223]
	global_load_lds_dwordx4 v[224:225], off
	s_add_u32 m0, s32, 0xd000
	v_lshl_add_u64 v[224:225], 32, 2, v[224:225]
	global_load_lds_dwordx4 v[226:227], off
	s_add_u32 m0, s32, 0xe000
	v_lshl_add_u64 v[226:227], 32, 2, v[226:227]
	global_load_lds_dwordx4 v[228:229], off
	s_add_u32 m0, s32, 0xf000
	v_lshl_add_u64 v[228:229], 32, 2, v[228:229]
	global_load_lds_dwordx4 v[230:231], off
	v_lshl_add_u64 v[230:231], 32, 2, v[230:231]

.LBB0_1357:
	v_add_u32_e32 v153, v147, v148
	v_add_u32_e32 v155, v147, v150
	v_add_u32_e32 v154, v149, v148
	ds_read_b128 v[138:141], v153
	ds_read_b128 v[158:161], v153 offset:4096
	ds_read_b128 v[162:165], v154 offset:32768
	ds_read_b128 v[166:169], v154 offset:36864
	v_add_u32_e32 v156, v149, v150
	ds_read_b128 v[182:185], v155
	ds_read_b128 v[186:189], v155 offset:4096
	ds_read_b128 v[190:193], v156 offset:32768
	ds_read_b128 v[194:197], v156 offset:36864
	s_waitcnt lgkmcnt(5)
	v_mfma_f32_32x32x16_bf16 v[50:65], v[138:141], v[162:165], v[50:65]
	s_waitcnt lgkmcnt(4)
	v_mfma_f32_32x32x16_bf16 v[18:33], v[138:141], v[166:169], v[18:33]
	v_mfma_f32_32x32x16_bf16 v[34:49], v[158:161], v[162:165], v[34:49]
	v_mfma_f32_32x32x16_bf16 v[2:17], v[158:161], v[166:169], v[2:17]
	v_add_u32_e32 v157, v147, v151
	v_add_u32_e32 v158, v149, v151
	ds_read_b128 v[138:141], v157
	ds_read_b128 v[162:165], v157 offset:4096
	ds_read_b128 v[166:169], v158 offset:32768
	ds_read_b128 v[198:201], v158 offset:36864
	s_waitcnt lgkmcnt(5)
	v_mfma_f32_32x32x16_bf16 v[50:65], v[182:185], v[190:193], v[50:65]
	s_waitcnt lgkmcnt(4)
	v_mfma_f32_32x32x16_bf16 v[18:33], v[182:185], v[194:197], v[18:33]
	v_mfma_f32_32x32x16_bf16 v[34:49], v[186:189], v[190:193], v[34:49]
	v_mfma_f32_32x32x16_bf16 v[2:17], v[186:189], v[194:197], v[2:17]
	v_add_u32_e32 v159, v147, v152
	v_add_u32_e32 v160, v149, v152
	ds_read_b128 v[182:185], v159
	ds_read_b128 v[186:189], v159 offset:4096
	ds_read_b128 v[190:193], v160 offset:32768
	ds_read_b128 v[194:197], v160 offset:36864
	s_waitcnt lgkmcnt(5)
	v_mfma_f32_32x32x16_bf16 v[50:65], v[138:141], v[166:169], v[50:65]
	s_cmp_gt_u32 s3, 60
	s_waitcnt vmcnt(0)
	s_waitcnt lgkmcnt(0)
	s_barrier
	v_mfma_f32_32x32x16_bf16 v[18:33], v[138:141], v[198:201], v[18:33]
	v_lshl_add_u64 v[140:141], v[134:135], 0, v[0:1]
	v_lshl_add_u64 v[138:139], v[136:137], 0, v[0:1]
	v_mfma_f32_32x32x16_bf16 v[34:49], v[162:165], v[166:169], v[34:49]
	v_mfma_f32_32x32x16_bf16 v[2:17], v[162:165], v[198:201], v[2:17]
	v_mfma_f32_32x32x16_bf16 v[50:65], v[182:185], v[190:193], v[50:65]
	v_mfma_f32_32x32x16_bf16 v[18:33], v[182:185], v[194:197], v[18:33]
	v_mfma_f32_32x32x16_bf16 v[34:49], v[186:189], v[190:193], v[34:49]
	v_mfma_f32_32x32x16_bf16 v[2:17], v[186:189], v[194:197], v[2:17]
	s_cbranch_scc1 .LBB0_1359
	v_add_co_u32_e32 v66, vcc, 0xc000, v140
	s_nop 1
	v_addc_co_u32_e32 v67, vcc, 0, v141, vcc
	v_add_co_u32_e32 v70, vcc, 0xd000, v140
	s_nop 1
	v_addc_co_u32_e32 v71, vcc, 0, v141, vcc
	v_add_co_u32_e32 v74, vcc, 0x40000, v138
	s_nop 0
	v_addc_co_u32_e32 v75, vcc, 0, v139, vcc
	v_add_co_u32_e32 v78, vcc, 0xe000, v140
	s_nop 0
	v_addc_co_u32_e32 v79, vcc, 0, v141, vcc
	v_add_co_u32_e32 v94, vcc, 0x80000, v138
	s_nop 0
	v_addc_co_u32_e32 v95, vcc, 0, v139, vcc
	v_add_co_u32_e32 v98, vcc, 0xf000, v140
	s_nop 0
	v_addc_co_u32_e32 v99, vcc, 0, v141, vcc
	v_add_co_u32_e32 v110, vcc, 0xc0000, v138
	s_nop 0
	v_addc_co_u32_e32 v111, vcc, 0, v139, vcc
	s_nop 0
.LBB0_1359:
	s_cmp_gt_u32 s3, 60
	s_cbranch_scc1 .Ldma9_skip_a
	s_add_u32 m0, s32, 0x0
	s_nop 0
	global_load_lds_dwordx4 v[216:217], off
	s_add_u32 m0, s32, 0x1000
	v_lshl_add_u64 v[216:217], v[234:235], 2, v[216:217]
	global_load_lds_dwordx4 v[218:219], off
	s_add_u32 m0, s32, 0x2000
	v_lshl_add_u64 v[218:219], v[234:235], 2, v[218:219]
	global_load_lds_dwordx4 v[220:221], off
	s_add_u32 m0, s32, 0x3000
	v_lshl_add_u64 v[220:221], v[234:235], 2, v[220:221]
	global_load_lds_dwordx4 v[222:223], off
	s_add_u32 m0, s32, 0x8000
	v_lshl_add_u64 v[222:223], v[234:235], 2, v[222:223]
	global_load_lds_dwordx4 v[224:225], off
	s_add_u32 m0, s32, 0x9000
	v_lshl_add_u64 v[224:225], 32, 2, v[224:225]
	global_load_lds_dwordx4 v[226:227], off
	s_add_u32 m0, s32, 0xa000
	v_lshl_add_u64 v[226:227], 32, 2, v[226:227]
	global_load_lds_dwordx4 v[228:229], off
	s_add_u32 m0, s32, 0xb000
	v_lshl_add_u64 v[228:229], 32, 2, v[228:229]
	global_load_lds_dwordx4 v[230:231], off
	v_lshl_add_u64 v[230:231], 32, 2, v[230:231]

.LBB0_1361:
	s_cmp_gt_u32 s3, 59
	s_waitcnt vmcnt(0)
	s_waitcnt lgkmcnt(0)
	s_barrier
	s_cbranch_scc1 .LBB0_1356
	v_add_co_u32_e32 v82, vcc, 0x10000, v140
	s_nop 1
	v_addc_co_u32_e32 v83, vcc, 0, v141, vcc
	v_add_co_u32_e32 v84, vcc, 0x11000, v140
	s_nop 1
	v_addc_co_u32_e32 v85, vcc, 0, v141, vcc
	v_add_co_u32_e32 v90, vcc, 0x40000, v138
	s_nop 0
	v_addc_co_u32_e32 v91, vcc, 0, v139, vcc
	v_add_co_u32_e32 v102, vcc, 0x12000, v140
	s_nop 0
	v_addc_co_u32_e32 v103, vcc, 0, v141, vcc
	v_add_co_u32_e32 v114, vcc, 0x80000, v138
	s_nop 0
	v_addc_co_u32_e32 v115, vcc, 0, v139, vcc
	v_add_co_u32_e32 v118, vcc, 0x13000, v140
	s_nop 0
	v_addc_co_u32_e32 v119, vcc, 0, v141, vcc
	v_add_co_u32_e32 v126, vcc, 0xc0000, v138
	s_nop 0
	v_addc_co_u32_e32 v127, vcc, 0, v139, vcc
	s_nop 0
	s_branch .LBB0_1356

	.amdhsa_kernel _Z11mega_kernel6Params
		.amdhsa_group_segment_fixed_size 65560
		.amdhsa_private_segment_fixed_size 0
		.amdhsa_kernarg_size 696
		.amdhsa_user_sgpr_count 2
		.amdhsa_user_sgpr_dispatch_ptr 0
		.amdhsa_user_sgpr_queue_ptr 0
		.amdhsa_user_sgpr_kernarg_segment_ptr 1
		.amdhsa_user_sgpr_dispatch_id 0
		.amdhsa_user_sgpr_kernarg_preload_length 0
		.amdhsa_user_sgpr_kernarg_preload_offset 0
		.amdhsa_user_sgpr_private_segment_size 0
		.amdhsa_uses_dynamic_stack 0
		.amdhsa_enable_private_segment 0
		.amdhsa_system_sgpr_workgroup_id_x 1
		.amdhsa_system_sgpr_workgroup_id_y 0
		.amdhsa_system_sgpr_workgroup_id_z 0
		.amdhsa_system_sgpr_workgroup_info 0
		.amdhsa_system_vgpr_workitem_id 2
		.amdhsa_next_free_vgpr 240
		.amdhsa_next_free_sgpr 100
		.amdhsa_accum_offset 240
		.amdhsa_reserve_vcc 1
		.amdhsa_float_round_mode_32 0
		.amdhsa_float_round_mode_16_64 0
		.amdhsa_float_denorm_mode_32 3
		.amdhsa_float_denorm_mode_16_64 3
		.amdhsa_dx10_clamp 1
		.amdhsa_ieee_mode 1
		.amdhsa_fp16_overflow 0
		.amdhsa_tg_split 0
		.amdhsa_exception_fp_ieee_invalid_op 0
		.amdhsa_exception_fp_denorm_src 0
		.amdhsa_exception_fp_ieee_div_zero 0
		.amdhsa_exception_fp_ieee_overflow 0
		.amdhsa_exception_fp_ieee_underflow 0
		.amdhsa_exception_fp_ieee_inexact 0
		.amdhsa_exception_int_div_zero 0
	.end_amdhsa_kernel

amdhsa.kernels:
  - .agpr_count:     0
    .args:
      - .offset:         0
        .size:           440
        .value_kind:     by_value
      - .offset:         440
        .size:           4
        .value_kind:     hidden_block_count_x
      - .offset:         444
        .size:           4
        .value_kind:     hidden_block_count_y
      - .offset:         448
        .size:           4
        .value_kind:     hidden_block_count_z
      - .offset:         452
        .size:           2
        .value_kind:     hidden_group_size_x
      - .offset:         454
        .size:           2
        .value_kind:     hidden_group_size_y
      - .offset:         456
        .size:           2
        .value_kind:     hidden_group_size_z
      - .offset:         458
        .size:           2
        .value_kind:     hidden_remainder_x
      - .offset:         460
        .size:           2
        .value_kind:     hidden_remainder_y
      - .offset:         462
        .size:           2
        .value_kind:     hidden_remainder_z
      - .offset:         480
        .size:           8
        .value_kind:     hidden_global_offset_x
      - .offset:         488
        .size:           8
        .value_kind:     hidden_global_offset_y
      - .offset:         496
        .size:           8
        .value_kind:     hidden_global_offset_z
      - .offset:         504
        .size:           2
        .value_kind:     hidden_grid_dims
      - .offset:         528
        .size:           8
        .value_kind:     hidden_multigrid_sync_arg
    .group_segment_fixed_size: 65560
    .kernarg_segment_align: 8
    .kernarg_segment_size: 696
    .language:       OpenCL C
    .language_version:
      - 2
      - 0
    .max_flat_workgroup_size: 256
    .name:           _Z11mega_kernel6Params
    .private_segment_fixed_size: 0
    .sgpr_count:     106
    .sgpr_spill_count: 289
    .symbol:         _Z11mega_kernel6Params.kd
    .uniform_work_group_size: 1
    .uses_dynamic_stack: false
    .vgpr_count:     240
    .vgpr_spill_count: 0
    .wavefront_size: 64
